# stack7: + phase-1 row prefetch pipeline, in-proj/ff1 epilogue sum-of-squares loads hoisted, ff1 epilogue stores write-through sc1
# speedup vs baseline: 1.0535x; 1.0083x over previous
; DI void phase1(const Params& p) {
;     int tid = threadIdx.x;
;     asm volatile("" : "+v"(tid));
;     const int lane = tid & 63, wid = tid >> 6;
;     const int gw = blockIdx.x * 8 + wid, nw = gridDim.x * 8;
;     for (int row = gw; row < NTOK; row += nw) {
;         const float* src = row < NLAT ? p.x + (size_t)row * DM : p.ctx + (size_t)(row - NLAT) * DM;
;         const int cond = row < NLAT ? (row >> 12) : 4;
;         const float* mp = p.mod + ((size_t)cond) * 6144;
;         f32x4 v[4];
;         float ss = 0.f;
; #pragma unroll
;         for (int i = 0; i < 4; ++i) { v[i] = *(const f32x4*)(src + i * 256 + lane * 4); ss += v[i][0] * v[i][0] + v[i][1] * v[i][1] + v[i][2] * v[i][2] + v[i][3] * v[i][3]; }
; #pragma unroll
;         for (int o = 1; o < 64; o <<= 1) ss += __shfl_xor(ss, o);
;         if (lane < 16) p.ss[(size_t)row * 16 + lane] = lane == 0 ? ss : 0.f;
.LBB0_10:
	s_cmp_eq_u32 s93, 1
	s_mov_b64 s[4:5], -1
	s_cbranch_scc0 .LBB0_96
	v_mov_b32_e32 v32, v252
	s_load_dword s4, s[88:89], 0x0
	v_ashrrev_i32_e32 v0, 6, v32
	v_readlane_b32 s5, v253, 19
	v_and_b32_e32 v33, 63, v32
	s_waitcnt lgkmcnt(0)
	s_lshl_b32 s36, s4, 3
	v_add_u32_e32 v18, s5, v0
	s_movk_i32 s4, 0x4400
	v_cmp_gt_i32_e32 vcc, s4, v18
	s_and_saveexec_b64 s[8:9], vcc
	s_cbranch_execz .LBB0_16
	v_cmp_lt_i32_e64 s[6:7], v134, v203
	v_lshlrev_b32_e32 v6, 4, v33
	v_mov_b32_e32 v7, v193
	v_cndmask_b32_e64 v0, v202, v134, s[6:7]
	v_cmp_lt_i32_e64 s[6:7], v135, v203
	v_lshlrev_b32_e32 v34, 2, v0
	v_ashrrev_i32_e32 v19, 31, v18
	v_cndmask_b32_e64 v0, v202, v135, s[6:7]
	v_lshlrev_b32_e32 v35, 2, v0
	v_xor_b32_e32 v0, 4, v202
	v_cmp_lt_i32_e64 s[6:7], v0, v203
	v_lshlrev_b32_e32 v192, 2, v33
	v_lshl_add_u64 v[16:17], s[24:25], 0, v[6:7]
	v_cndmask_b32_e64 v0, v202, v0, s[6:7]
	v_lshlrev_b32_e32 v36, 2, v0
	v_xor_b32_e32 v0, 8, v202
	v_cmp_lt_i32_e64 s[6:7], v0, v203
	v_lshlrev_b64 v[6:7], 6, v[18:19]
	v_lshl_add_u64 v[6:7], v[6:7], 0, v[192:193]
	v_cndmask_b32_e64 v0, v202, v0, s[6:7]
	v_cmp_lt_i32_e64 s[6:7], v230, v203
	v_lshlrev_b32_e32 v37, 2, v0
	v_lshl_add_u64 v[20:21], s[74:75], 0, v[6:7]
	v_cndmask_b32_e64 v0, v202, v230, s[6:7]
	v_cmp_lt_i32_e64 s[6:7], v209, v203
	v_lshlrev_b32_e32 v38, 2, v0
	v_lshlrev_b64 v[6:7], 11, v[18:19]
	v_cndmask_b32_e64 v0, v202, v209, s[6:7]
	v_lshlrev_b32_e32 v39, 2, v0
	v_or_b32_e32 v0, 0x100, v192
	v_or_b32_e32 v2, 0x200, v192
	v_or_b32_e32 v4, 0x300, v192
	s_ashr_i32 s37, s36, 31
	v_lshl_or_b32 v6, v33, 3, v6
	v_cmp_gt_u32_e32 vcc, 16, v33
	v_cmp_eq_u32_e64 s[4:5], 0, v33
	s_lshl_b64 s[38:39], s[36:37], 6
	v_lshl_add_u64 v[22:23], s[82:83], 0, v[6:7]
	s_lshl_b64 s[40:41], s[36:37], 11
	s_mov_b64 s[42:43], 0
	v_lshlrev_b32_e32 v192, 2, v192
	v_lshlrev_b32_e32 v24, 2, v0
	v_mov_b32_e32 v25, v193
	v_lshlrev_b32_e32 v26, 2, v2
	v_mov_b32_e32 v27, v193
	v_lshlrev_b32_e32 v28, 2, v4
	v_mov_b32_e32 v29, v193
	v_mov_b64_e32 v[30:31], v[18:19]
	v_cmp_gt_i32_e64 s[6:7], s33, v30
	v_add_u32_e32 v152, 0xffffc000, v30
	v_mov_b32_e32 v155, s17
	v_mov_b32_e32 v156, s13
	v_cndmask_b32_e64 v152, v152, v30, s[6:7]
	v_mov_b32_e32 v153, 0
	v_cndmask_b32_e64 v157, v155, v156, s[6:7]
	v_mov_b32_e32 v155, s16
	v_mov_b32_e32 v156, s12
	v_cndmask_b32_e64 v156, v155, v156, s[6:7]
	v_lshlrev_b64 v[152:153], 12, v[152:153]
	v_lshl_add_u64 v[152:153], v[156:157], 0, v[152:153]
	v_lshl_add_u64 v[152:153], v[152:153], 0, v[192:193]
	global_load_dwordx4 v[136:139], v[152:153], off
	global_load_dwordx4 v[140:143], v[152:153], off offset:1024
	global_load_dwordx4 v[144:147], v[152:153], off offset:2048
	global_load_dwordx4 v[148:151], v[152:153], off offset:3072
	s_waitcnt vmcnt(0)
	s_branch .Lph1a_entry
.LBB0_13:
	s_or_b64 exec, exec, s[6:7]
	s_waitcnt vmcnt(5) lgkmcnt(0)
	v_lshl_add_u64 v[30:31], v[30:31], 0, s[36:37]
	s_movk_i32 s6, 0x43ff
	v_cmp_lt_i32_e64 s[6:7], s6, v30
	v_lshl_add_u64 v[20:21], v[20:21], 0, s[38:39]
	s_or_b64 s[42:43], s[6:7], s[42:43]
	v_pk_mul_f32 v[10:11], v[10:11], v[66:67]
	v_pk_mul_f32 v[8:9], v[8:9], v[64:65]
	v_pk_add_f32 v[40:41], v[80:81], 1.0 op_sel_hi:[1,0]
	v_pk_add_f32 v[42:43], v[82:83], 1.0 op_sel_hi:[1,0]
	v_pk_mul_f32 v[8:9], v[8:9], v[40:41]
	v_pk_mul_f32 v[10:11], v[10:11], v[42:43]
	v_cvt_pk_bf16_f32 v8, v8, v9
	v_cvt_pk_bf16_f32 v9, v10, v11
	global_store_dwordx2 v[22:23], v[8:9], off
	v_pk_mul_f32 v[6:7], v[6:7], v[70:71]
	v_pk_mul_f32 v[4:5], v[4:5], v[68:69]
	v_pk_add_f32 v[40:41], v[84:85], 1.0 op_sel_hi:[1,0]
	v_pk_add_f32 v[42:43], v[86:87], 1.0 op_sel_hi:[1,0]
	v_pk_mul_f32 v[4:5], v[4:5], v[40:41]
	v_pk_mul_f32 v[6:7], v[6:7], v[42:43]
	v_cvt_pk_bf16_f32 v4, v4, v5
	v_cvt_pk_bf16_f32 v5, v6, v7
	global_store_dwordx2 v[22:23], v[4:5], off offset:512
	v_pk_mul_f32 v[14:15], v[14:15], v[74:75]
	v_pk_mul_f32 v[12:13], v[12:13], v[72:73]
	v_pk_add_f32 v[40:41], v[88:89], 1.0 op_sel_hi:[1,0]
	v_pk_add_f32 v[42:43], v[90:91], 1.0 op_sel_hi:[1,0]
	v_pk_mul_f32 v[12:13], v[12:13], v[40:41]
	v_pk_mul_f32 v[14:15], v[14:15], v[42:43]
	v_cvt_pk_bf16_f32 v12, v12, v13
	v_cvt_pk_bf16_f32 v13, v14, v15
	global_store_dwordx2 v[22:23], v[12:13], off offset:1024
	v_pk_mul_f32 v[62:63], v[62:63], v[78:79]
	v_pk_mul_f32 v[60:61], v[60:61], v[76:77]
	v_pk_add_f32 v[40:41], v[92:93], 1.0 op_sel_hi:[1,0]
	v_pk_add_f32 v[42:43], v[94:95], 1.0 op_sel_hi:[1,0]
	v_pk_mul_f32 v[60:61], v[60:61], v[40:41]
	v_pk_mul_f32 v[62:63], v[62:63], v[42:43]
	v_cvt_pk_bf16_f32 v60, v60, v61
	v_cvt_pk_bf16_f32 v61, v62, v63
	global_store_dwordx2 v[22:23], v[60:61], off offset:1536
	v_lshl_add_u64 v[22:23], v[22:23], 0, s[40:41]
	s_andn2_b64 exec, exec, s[42:43]
	s_cbranch_execz .LBB0_16
; DI void phase1(const Params& p) {
;     ...
;     for (int row = gw; row < NTOK; row += nw) {
;         const float* src = row < NLAT ? p.x + (size_t)row * DM : p.ctx + (size_t)(row - NLAT) * DM;
;         const int cond = row < NLAT ? (row >> 12) : 4;
;         const float* mp = p.mod + ((size_t)cond) * 6144;
;         f32x4 v[4];
;         float ss = 0.f;
; #pragma unroll
;         for (int i = 0; i < 4; ++i) { v[i] = *(const f32x4*)(src + i * 256 + lane * 4); ss += v[i][0] * v[i][0] + v[i][1] * v[i][1] + v[i][2] * v[i][2] + v[i][3] * v[i][3]; }
; #pragma unroll
;         for (int o = 1; o < 64; o <<= 1) ss += __shfl_xor(ss, o);
;         if (lane < 16) p.ss[(size_t)row * 16 + lane] = lane == 0 ? ss : 0.f;
;     ...
;         const int fr = lane & 15, fq = lane >> 4;
;         constexpr int G_IN = IN_DIM / 16, G_FF = FF / 16, G_L = G_IN + G_FF;
;         for (int gi = gw; gi < DEPTH * G_L; gi += nw) {
;             const int l = gi / G_L, r = gi % G_L;
;             const bool which = r >= G_IN;
;             const int n0 = (which ? r - G_IN : r) * 16;
;             const int N = which ? FF : IN_DIM;
;             const bf16_t* W = (which ? p.wt_ff1 + (size_t)l * FF * DM : p.wt_in + (size_t)l * IN_DIM * DM) + (size_t)(n0 + fr) * DM + fq * 8;
;             float* dst = which ? p.shw_ff1 + (size_t)l * 5 * FF : p.shw_in + (size_t)l * 5 * IN_DIM;
;             const int c = fr < 5 ? fr : fr - 5;
;             const float* sh = p.mod + ((size_t)l * 5 + (c < 5 ? c : 0)) * 6144 + (which ? 3 : 0) * DM + fq * 8;
.LBB0_14:
	s_waitcnt vmcnt(5)
.Lph1a_entry:
	v_mov_b64_e32 v[8:9], v[136:137]
	v_mov_b64_e32 v[10:11], v[138:139]
	v_mov_b64_e32 v[4:5], v[140:141]
	v_mov_b64_e32 v[6:7], v[142:143]
	v_mov_b64_e32 v[12:13], v[144:145]
	v_mov_b64_e32 v[14:15], v[146:147]
	v_mov_b64_e32 v[60:61], v[148:149]
	v_mov_b64_e32 v[62:63], v[150:151]
	global_load_dwordx4 v[64:67], v[16:17], off
	global_load_dwordx4 v[68:71], v[16:17], off offset:1024
	global_load_dwordx4 v[72:75], v[16:17], off offset:2048
	global_load_dwordx4 v[76:79], v[16:17], off offset:3072
	v_min_i32_e32 v96, 0x4000, v30
	v_ashrrev_i32_e32 v96, 12, v96
	v_mul_hi_i32_i24_e32 v99, 0x6000, v96
	v_mul_i32_i24_e32 v98, 0x6000, v96
	v_lshl_add_u64 v[98:99], s[66:67], 0, v[98:99]
	s_mov_b64 s[6:7], 0x1000
	v_lshl_add_u64 v[98:99], v[98:99], 0, s[6:7]
	v_lshl_add_u64 v[100:101], v[98:99], 0, v[192:193]
	global_load_dwordx4 v[80:83], v[100:101], off
	v_lshl_add_u64 v[100:101], v[98:99], 0, v[24:25]
	global_load_dwordx4 v[84:87], v[100:101], off
	v_lshl_add_u64 v[100:101], v[98:99], 0, v[26:27]
	global_load_dwordx4 v[88:91], v[100:101], off
	v_lshl_add_u64 v[100:101], v[98:99], 0, v[28:29]
	global_load_dwordx4 v[92:95], v[100:101], off
	v_add_u32_e32 v154, s36, v30
	v_min_i32_e32 v154, 0x43ff, v154
	v_cmp_gt_i32_e64 s[6:7], s33, v154
	v_add_u32_e32 v152, 0xffffc000, v154
	v_mov_b32_e32 v155, s17
	v_mov_b32_e32 v156, s13
	v_cndmask_b32_e64 v152, v152, v154, s[6:7]
	v_mov_b32_e32 v153, 0
	v_cndmask_b32_e64 v157, v155, v156, s[6:7]
	v_mov_b32_e32 v155, s16
	v_mov_b32_e32 v156, s12
	v_cndmask_b32_e64 v156, v155, v156, s[6:7]
	v_lshlrev_b64 v[152:153], 12, v[152:153]
	v_lshl_add_u64 v[152:153], v[156:157], 0, v[152:153]
	v_lshl_add_u64 v[152:153], v[152:153], 0, v[192:193]
	global_load_dwordx4 v[136:139], v[152:153], off
	global_load_dwordx4 v[140:143], v[152:153], off offset:1024
	global_load_dwordx4 v[144:147], v[152:153], off offset:2048
	global_load_dwordx4 v[148:151], v[152:153], off offset:3072
	v_mul_f32_e32 v2, v9, v9
	v_mul_f32_e32 v3, v5, v5
	v_fmac_f32_e32 v2, v8, v8
	v_fmac_f32_e32 v3, v4, v4
	v_fmac_f32_e32 v2, v10, v10
	v_fmac_f32_e32 v3, v6, v6
	v_fmac_f32_e32 v2, v11, v11
	v_fmac_f32_e32 v3, v7, v7
	v_add_f32_e32 v2, v2, v3
	v_mul_f32_e32 v3, v13, v13
	v_fmac_f32_e32 v3, v12, v12
	v_fmac_f32_e32 v3, v14, v14
	v_fmac_f32_e32 v3, v15, v15
	v_add_f32_e32 v19, v2, v3
	v_mul_f32_e32 v40, v61, v61
	v_fmac_f32_e32 v40, v60, v60
	v_fmac_f32_e32 v40, v62, v62
	v_fmac_f32_e32 v40, v63, v63
	v_add_f32_e32 v19, v19, v40
	ds_bpermute_b32 v40, v34, v19
	s_waitcnt lgkmcnt(0)
	v_add_f32_e32 v19, v19, v40
	ds_bpermute_b32 v40, v35, v19
	s_waitcnt lgkmcnt(0)
	v_add_f32_e32 v19, v19, v40
	ds_bpermute_b32 v40, v36, v19
	s_waitcnt lgkmcnt(0)
	v_add_f32_e32 v19, v19, v40
	ds_bpermute_b32 v40, v37, v19
	s_waitcnt lgkmcnt(0)
	v_add_f32_e32 v19, v19, v40
	ds_bpermute_b32 v40, v38, v19
	s_waitcnt lgkmcnt(0)
	v_add_f32_e32 v19, v19, v40
	ds_bpermute_b32 v40, v39, v19
	s_and_saveexec_b64 s[6:7], vcc
	s_cbranch_execz .LBB0_13
	s_waitcnt lgkmcnt(0)
	v_add_f32_e32 v19, v19, v40
	v_cndmask_b32_e64 v19, 0, v19, s[4:5]
	global_store_dword v[20:21], v19, off
	s_branch .LBB0_13
.LBB0_16:
	s_or_b64 exec, exec, s[8:9]
	s_waitcnt vmcnt(0)
	s_movk_i32 s4, 0x5c0
	v_cmp_gt_i32_e32 vcc, s4, v18
	s_and_saveexec_b64 s[38:39], vcc
	s_cbranch_execz .LBB0_95
	v_and_b32_e32 v20, 15, v32
	v_subrev_co_u32_e32 v1, vcc, 5, v20
	s_xor_b64 s[40:41], vcc, -1
	s_nop 0
	v_cndmask_b32_e32 v1, v1, v20, vcc
	v_cmp_gt_i32_e32 vcc, 5, v1
	v_lshrrev_b32_e32 v0, 1, v32
	v_and_b32_e32 v0, 24, v0
	v_cndmask_b32_e32 v19, 0, v1, vcc
	v_and_or_b32 v1, v202, 64, v20
	v_lshlrev_b32_e32 v1, 2, v1
	v_cmp_gt_u32_e32 vcc, 10, v20
	v_or_b32_e32 v21, 64, v1
	v_or_b32_e32 v38, 0x80, v1
	v_cmp_gt_u32_e64 s[4:5], 16, v33
	v_and_b32_e32 v22, 48, v32
	v_mov_b32_e32 v23, v193
	s_mov_b64 s[42:43], 0
	v_lshlrev_b32_e32 v24, 2, v0
	v_lshlrev_b32_e32 v26, 2, v20
	s_branch .LBB0_19

; #define WAIT_V0() asm volatile("s_waitcnt vmcnt(0)" ::: "memory")
; #define G_STAGE_A(Ap, buf, kt) do { const char* ab_ = (const char*)(Ap) + (size_t)(kt) * 128; \
;       _Pragma("unroll") for (int i = 0; i < 4; ++i) \
;         __builtin_amdgcn_global_load_lds((const unsigned*)(ab_ + soff[i]), (LDSP unsigned*)(G_SA(buf) + wid * 1024 + i * 8192), 16, 0, 0); } while (0)
; #define G_STAGE_B(Bp, buf, kt) do { const char* bb_ = (const char*)(Bp) + (size_t)(kt) * 128; \
;       _Pragma("unroll") for (int i = 0; i < 4; ++i) \
;         __builtin_amdgcn_global_load_lds((const unsigned*)(bb_ + soff[i]), (LDSP unsigned*)(G_SB(buf) + wid * 1024 + i * 8192), 16, 0, 0); } while (0)
; #define G_RDA(AF, buf, ks, mh) do { _Pragma("unroll") for (int m = 0; m < 4; ++m) AF[m] = *(const LDSP bf16x8*)(G_SA(buf) + aoff + ((mh) * 4 + m) * 2048 + (ks) * 1024); } while (0)
; #define G_RDB(BF, buf, ks) do { _Pragma("unroll") for (int n = 0; n < 4; ++n) BF[n] = *(const LDSP bf16x8*)(G_SB(buf) + boff + n * 2048 + (ks) * 1024); } while (0)
; #define G_SB0() __builtin_amdgcn_sched_barrier(0)
; template <int EK>
; DI void gemm_stream(const Params& p, int l, const bf16_t* __restrict__ A, const bf16_t* __restrict__ Bt, int M, int N, int K, ldsp_t shm) {
;     ...
;         for (int t = 0; t < nt; ++t) {
;             const int cur = t & 1;
;             G_RDA(Aa, cur, 0, 0); G_RDB(Bk0, cur, 0);
;             if (t + 1 < nt) G_STAGE_B(Bb, cur ^ 1, t + 1);
;             else if (has_next) G_STAGE_B(Bb2, cur ^ 1, 0);
;             G_SB0();
;             if (t > 0) G_MMA(Ab_, Bk1, 1);
;             G_SB0();
;             if (t + 1 < nt) G_STAGE_A(Ab, cur ^ 1, t + 1);
;             else if (has_next) G_STAGE_A(Ab2, cur ^ 1, 0);
;             G_RDA(Ab_, cur, 0, 1);
;             G_MMA(Aa, Bk0, 0); G_SB0();
;             G_RDA(Aa, cur, 1, 0); G_RDB(Bk1, cur, 1);
;             G_MMA(Ab_, Bk0, 1); G_SB0();
;             G_RDA(Ab_, cur, 1, 1);
;             G_MMA(Aa, Bk1, 0); G_SB0();
;             asm volatile("s_waitcnt lgkmcnt(0)" ::: "memory");
;             WAIT_V0(); __syncthreads();
;         }
;         G_MMA(Ab_, Bk1, 1);
.LBB0_103:
	v_add_u32_e32 v80, 0x12000, v218
	v_add_u32_e32 v132, 0x12800, v218
	v_add_u32_e32 v136, 0x13000, v218
	v_add_u32_e32 v140, 0x13800, v218
	ds_read_b128 v[80:83], v80
	ds_read_b128 v[132:135], v132
	ds_read_b128 v[136:139], v136
	ds_read_b128 v[140:143], v140
	s_setprio 1
	s_waitcnt lgkmcnt(0)
	v_mfma_f32_16x16x32_bf16 v[60:63], v[160:163], v[188:191], v[60:63]
	v_mfma_f32_16x16x32_bf16 v[56:59], v[164:167], v[188:191], v[56:59]
	v_mfma_f32_16x16x32_bf16 v[52:55], v[168:171], v[188:191], v[52:55]
	v_mfma_f32_16x16x32_bf16 v[48:51], v[172:175], v[188:191], v[48:51]
	v_mfma_f32_16x16x32_bf16 v[44:47], v[160:163], v[180:183], v[44:47]
	v_mfma_f32_16x16x32_bf16 v[40:43], v[164:167], v[180:183], v[40:43]
	v_mfma_f32_16x16x32_bf16 v[36:39], v[168:171], v[180:183], v[36:39]
	v_mfma_f32_16x16x32_bf16 v[32:35], v[172:175], v[180:183], v[32:35]
	v_mfma_f32_16x16x32_bf16 v[28:31], v[160:163], v[184:187], v[28:31]
	v_mfma_f32_16x16x32_bf16 v[24:27], v[164:167], v[184:187], v[24:27]
	v_mfma_f32_16x16x32_bf16 v[20:23], v[168:171], v[184:187], v[20:23]
	v_mfma_f32_16x16x32_bf16 v[16:19], v[172:175], v[184:187], v[16:19]
	v_mfma_f32_16x16x32_bf16 v[12:15], v[160:163], v[176:179], v[12:15]
	v_mfma_f32_16x16x32_bf16 v[8:11], v[164:167], v[176:179], v[8:11]
	v_mfma_f32_16x16x32_bf16 v[4:7], v[168:171], v[176:179], v[4:7]
	v_mfma_f32_16x16x32_bf16 v[0:3], v[172:175], v[176:179], v[0:3]
	s_setprio 0
	v_add_u32_e32 v144, 0x10400, v218
	v_add_u32_e32 v148, 0x10c00, v218
	v_add_u32_e32 v152, 0x11400, v218
	v_add_u32_e32 v156, 0x11c00, v218
	v_add_u32_e32 v176, 0x18400, v219
	v_add_u32_e32 v180, 0x18c00, v219
	v_add_u32_e32 v184, 0x19400, v219
	v_add_u32_e32 v188, 0x19c00, v219
	ds_read_b128 v[144:147], v144
	ds_read_b128 v[148:151], v148
	ds_read_b128 v[152:155], v152
	ds_read_b128 v[156:159], v156
	ds_read_b128 v[176:179], v176
	ds_read_b128 v[180:183], v180
	ds_read_b128 v[184:187], v184
	ds_read_b128 v[188:191], v188
	s_setprio 1
	v_mfma_f32_16x16x32_bf16 v[128:131], v[160:163], v[80:83], v[128:131]
	v_mfma_f32_16x16x32_bf16 v[124:127], v[164:167], v[80:83], v[124:127]
	v_mfma_f32_16x16x32_bf16 v[120:123], v[168:171], v[80:83], v[120:123]
	v_mfma_f32_16x16x32_bf16 v[116:119], v[172:175], v[80:83], v[116:119]
	v_mfma_f32_16x16x32_bf16 v[112:115], v[160:163], v[132:135], v[112:115]
	v_mfma_f32_16x16x32_bf16 v[194:197], v[164:167], v[132:135], v[108:111]
	v_mfma_f32_16x16x32_bf16 v[198:201], v[168:171], v[132:135], v[104:107]
	v_mfma_f32_16x16x32_bf16 v[132:135], v[172:175], v[132:135], v[100:103]
	v_mfma_f32_16x16x32_bf16 v[204:207], v[160:163], v[136:139], v[96:99]
	v_mfma_f32_16x16x32_bf16 v[210:213], v[164:167], v[136:139], v[92:95]
	v_mfma_f32_16x16x32_bf16 v[214:217], v[168:171], v[136:139], v[88:91]
	v_mfma_f32_16x16x32_bf16 v[136:139], v[172:175], v[136:139], v[84:87]
	v_mfma_f32_16x16x32_bf16 v[160:163], v[160:163], v[140:143], v[64:67]
	v_mfma_f32_16x16x32_bf16 v[164:167], v[164:167], v[140:143], v[68:71]
	v_mfma_f32_16x16x32_bf16 v[168:171], v[168:171], v[140:143], v[76:79]
	v_mfma_f32_16x16x32_bf16 v[140:143], v[172:175], v[140:143], v[72:75]
	s_setprio 0
	v_add_u32_e32 v64, 0x12400, v218
	v_add_u32_e32 v68, 0x12c00, v218
	ds_read_b128 v[64:67], v64
	ds_read_b128 v[172:175], v68
	v_add_u32_e32 v68, 0x13400, v218
	v_add_u32_e32 v69, 0x13c00, v218
	ds_read_b128 v[218:221], v68
	ds_read_b128 v[222:225], v69
	s_setprio 1
	s_waitcnt lgkmcnt(0)
	v_mfma_f32_16x16x32_bf16 v[226:229], v[176:179], v[144:147], v[60:63]
	v_mfma_f32_16x16x32_bf16 v[230:233], v[180:183], v[144:147], v[56:59]
	v_mfma_f32_16x16x32_bf16 v[234:237], v[184:187], v[144:147], v[52:55]
	v_mfma_f32_16x16x32_bf16 v[238:241], v[188:191], v[144:147], v[48:51]
	v_mfma_f32_16x16x32_bf16 v[242:245], v[176:179], v[148:151], v[44:47]
	v_mfma_f32_16x16x32_bf16 v[246:249], v[180:183], v[148:151], v[40:43]
	v_mfma_f32_16x16x32_bf16 v[144:147], v[184:187], v[148:151], v[36:39]
	v_mfma_f32_16x16x32_bf16 v[48:51], v[188:191], v[148:151], v[32:35]
	v_mfma_f32_16x16x32_bf16 v[108:111], v[176:179], v[152:155], v[28:31]
	v_mfma_f32_16x16x32_bf16 v[104:107], v[180:183], v[152:155], v[24:27]
	v_mfma_f32_16x16x32_bf16 v[100:103], v[184:187], v[152:155], v[20:23]
	v_mfma_f32_16x16x32_bf16 v[96:99], v[188:191], v[152:155], v[16:19]
	v_mfma_f32_16x16x32_bf16 v[92:95], v[176:179], v[156:159], v[12:15]
	v_mfma_f32_16x16x32_bf16 v[88:91], v[180:183], v[156:159], v[8:11]
	v_mfma_f32_16x16x32_bf16 v[84:87], v[184:187], v[156:159], v[4:7]
	v_mfma_f32_16x16x32_bf16 v[80:83], v[188:191], v[156:159], v[0:3]
	s_setprio 0
	s_waitcnt lgkmcnt(0)
	s_waitcnt vmcnt(0)
	s_waitcnt vmcnt(0)
	s_barrier
; #define G_STAGE_B(Bp, buf, kt) do { const char* bb_ = (const char*)(Bp) + (size_t)(kt) * 128; \
;       _Pragma("unroll") for (int i = 0; i < 4; ++i) \
;         __builtin_amdgcn_global_load_lds((const unsigned*)(bb_ + soff[i]), (LDSP unsigned*)(G_SB(buf) + wid * 1024 + i * 8192), 16, 0, 0); } while (0)
; #define G_MMA(AF, BF, mh) do { __builtin_amdgcn_s_setprio(1); \
;             _Pragma("unroll") for (int m = 0; m < 4; ++m) _Pragma("unroll") for (int n = 0; n < 4; ++n) \
;                 acc[(mh) * 4 + m][n] = __builtin_amdgcn_mfma_f32_16x16x32_bf16(BF[n], AF[m], acc[(mh) * 4 + m][n], 0, 0, 0); \
;             __builtin_amdgcn_s_setprio(0); } while (0)
; template <int EK>
; DI void gemm_stream(const Params& p, int l, const bf16_t* __restrict__ A, const bf16_t* __restrict__ Bt, int M, int N, int K, ldsp_t shm) {
;     ...
;         G_MMA(Ab_, Bk1, 1);
;         G_SB0();
;         {
;             int tid2 = threadIdx.x, pme = pm, pne = pn;
;             asm volatile("" : "+v"(tid2), "+s"(pme), "+s"(pne));
;             TileCtx tc;
;             tc.wid = tid2 >> 6; tc.lane = tid2 & 63; tc.wr = tc.wid >> 2; tc.wc = tc.wid & 3; tc.fr = tc.lane & 15; tc.fq = tc.lane >> 4; tc.l = l;
;             tc.brow = pme * 256; tc.bcol = pne * 256; tc.pn = pne;
;             ldsp_t ex = shm + G_STAGE_B + tc.wid * 8192;
;             if (EK == 0 || EK == 2) {
;                 const int cond = tc.brow < NLAT ? (tc.brow >> 12) : 4;
;                 const float* ssp = p.ss + ((size_t)(l * 2 + (EK == 0 ? 0 : 1)) * NTOK + tc.brow + tc.wr * 128 + tc.fr) * 16 + tc.fq * 4;
;                 const float* shw = (EK == 0 ? p.shw_in + ((size_t)l * 5 + cond) * IN_DIM : p.shw_ff1 + ((size_t)l * 5 + cond) * FF) + tc.bcol + tc.wc * 64 + tc.fq * 4;
;                 f32x4 shv[4];
; #pragma unroll
;                 for (int n = 0; n < 4; ++n) shv[n] = *(const f32x4*)(shw + n * 16);
; #pragma unroll
;                 for (int m = 0; m < 8; ++m) {
;                     const f32x4 pp = *(const f32x4*)(ssp + m * 256);
;                     float sq = pp[0] + pp[1] + pp[2] + pp[3];
;                     sq += __shfl_xor(sq, 16);
;                     sq += __shfl_xor(sq, 32);
;                     const float rstd = rsqrtf(sq * (1.f / DM) + EPS);
; #pragma unroll
;                     for (int n = 0; n < 4; ++n) acc[m][n] = acc[m][n] * rstd + shv[n];
	s_setprio 1
	v_mfma_f32_16x16x32_bf16 v[76:79], v[176:179], v[64:67], v[128:131]
	v_mfma_f32_16x16x32_bf16 v[72:75], v[180:183], v[64:67], v[124:127]
	v_mfma_f32_16x16x32_bf16 v[68:71], v[184:187], v[64:67], v[120:123]
	v_mfma_f32_16x16x32_bf16 v[64:67], v[188:191], v[64:67], v[116:119]
	v_mfma_f32_16x16x32_bf16 v[60:63], v[176:179], v[172:175], v[112:115]
	v_mfma_f32_16x16x32_bf16 v[56:59], v[180:183], v[172:175], v[194:197]
	v_mfma_f32_16x16x32_bf16 v[52:55], v[184:187], v[172:175], v[198:201]
	v_mfma_f32_16x16x32_bf16 v[172:175], v[188:191], v[172:175], v[132:135]
	v_mfma_f32_16x16x32_bf16 v[28:31], v[176:179], v[218:221], v[204:207]
	v_mfma_f32_16x16x32_bf16 v[24:27], v[180:183], v[218:221], v[210:213]
	v_mfma_f32_16x16x32_bf16 v[20:23], v[184:187], v[218:221], v[214:217]
	v_mfma_f32_16x16x32_bf16 v[16:19], v[188:191], v[218:221], v[136:139]
	v_mfma_f32_16x16x32_bf16 v[12:15], v[176:179], v[222:225], v[160:163]
	v_mfma_f32_16x16x32_bf16 v[8:11], v[180:183], v[222:225], v[164:167]
	v_mfma_f32_16x16x32_bf16 v[4:7], v[184:187], v[222:225], v[168:171]
	v_mfma_f32_16x16x32_bf16 v[0:3], v[188:191], v[222:225], v[140:143]
	s_setprio 0
	v_mov_b32_e32 v158, v252
	s_lshl_b32 s35, s51, 8
	s_min_i32 s4, s35, 0x4000
	s_lshl_b32 s42, s50, 8
	s_ashr_i32 s4, s4, 12
	s_ashr_i32 s5, s35, 31
	v_lshlrev_b32_e32 v32, 7, v158
	s_add_u32 s37, s11, s35
	v_and_b32_e32 v159, 15, v158
	v_and_b32_e32 v160, 0xffffe000, v32
	s_addc_u32 s5, s10, s5
	v_ashrrev_i32_e32 v32, 1, v158
	v_and_b32_e32 v112, 0xffffff80, v32
	v_or_b32_e32 v32, s37, v159
	v_mov_b32_e32 v33, s5
	s_ashr_i32 s5, s4, 31
	s_mul_i32 s37, s48, 5
	s_add_u32 s4, s37, s4
	s_mul_hi_i32 s37, s48, 5
	s_addc_u32 s5, s37, s5
	s_lshl_b64 s[4:5], s[4:5], 14
	s_add_u32 s37, s78, s4
	s_addc_u32 s50, s79, s5
	s_ashr_i32 s43, s42, 31
	v_ashrrev_i32_e32 v113, 31, v112
	s_lshl_b64 s[4:5], s[42:43], 2
	v_lshl_add_u64 v[32:33], v[32:33], 0, v[112:113]
	s_add_u32 s4, s37, s4
	v_and_b32_e32 v113, 0xc0, v158
	v_lshlrev_b64 v[114:115], 6, v[32:33]
	s_addc_u32 s5, s50, s5
	v_lshlrev_b32_e32 v192, 2, v113
	v_lshl_add_u64 v[32:33], s[4:5], 0, v[192:193]
	v_and_b32_e32 v192, 48, v158
	v_lshl_add_u64 v[114:115], s[74:75], 0, v[114:115]
	v_lshl_add_u64 v[150:151], v[114:115], 0, v[192:193]
	v_xor_b32_e32 v114, 16, v202
	v_cmp_lt_i32_e32 vcc, v114, v203
	v_lshl_add_u64 v[32:33], v[32:33], 0, v[192:193]
	global_load_dwordx4 v[44:47], v[32:33], off
	global_load_dwordx4 v[40:43], v[32:33], off offset:64
	global_load_dwordx4 v[36:39], v[32:33], off offset:128
	s_nop 0
	global_load_dwordx4 v[32:35], v[32:33], off offset:192
	v_cndmask_b32_e32 v114, v202, v114, vcc
	v_cmp_lt_i32_e32 vcc, v209, v203
	v_lshlrev_b32_e32 v162, 2, v114
	s_mov_b32 s4, 0x358637bd
	v_cndmask_b32_e32 v114, v202, v209, vcc
	v_lshlrev_b32_e32 v161, 2, v114
	global_load_dwordx4 v[114:117], v[150:151], off
	global_load_dwordx4 v[118:121], v[150:151], off offset:1024
	global_load_dwordx4 v[176:179], v[150:151], off offset:2048
	global_load_dwordx4 v[180:183], v[150:151], off offset:3072
	v_mov_b32_e32 v194, s29
	v_mov_b32_e32 v195, 0
	v_lshl_add_u64 v[194:195], v[150:151], 0, v[194:195]
	global_load_dwordx4 v[184:187], v[194:195], off
	global_load_dwordx4 v[188:191], v[194:195], off offset:1024
	global_load_dwordx4 v[218:221], v[194:195], off offset:2048
	global_load_dwordx4 v[222:225], v[194:195], off offset:3072
	v_mov_b64_e32 v[166:167], s[4:5]
	s_mov_b32 s16, 0x3a800000
	v_lshlrev_b32_e32 v192, 1, v113
	s_mov_b32 s50, s36
	s_mov_b32 s51, s34
	s_waitcnt vmcnt(7)
	v_mov_b32_e32 v123, v114
	s_waitcnt vmcnt(6)
	v_mov_b32_e32 v122, v118
	v_mov_b32_e32 v114, v119
	v_pk_add_f32 v[114:115], v[122:123], v[114:115]
	v_mov_b32_e32 v118, v120
	v_mov_b32_e32 v119, v116
	v_pk_add_f32 v[114:115], v[118:119], v[114:115]
	v_mov_b32_e32 v116, v121
	v_pk_add_f32 v[114:115], v[116:117], v[114:115]
	ds_bpermute_b32 v117, v162, v115
	ds_bpermute_b32 v116, v162, v114
	s_waitcnt lgkmcnt(0)
	v_pk_add_f32 v[114:115], v[114:115], v[116:117]
	ds_bpermute_b32 v117, v161, v115
	ds_bpermute_b32 v116, v161, v114
	s_waitcnt lgkmcnt(0)
	v_pk_add_f32 v[114:115], v[114:115], v[116:117]
	s_nop 0
	v_pk_fma_f32 v[114:115], v[114:115], s[16:17], v[166:167] op_sel_hi:[1,0,0]
	s_nop 0
	v_mul_f32_e32 v116, 0x4b800000, v115
	v_cmp_gt_f32_e64 s[4:5], s92, v115
	v_cmp_gt_f32_e32 vcc, s92, v114
	s_nop 0
	v_cndmask_b32_e64 v115, v115, v116, s[4:5]
	v_rsq_f32_e32 v115, v115
	s_nop 0
	v_mul_f32_e32 v116, 0x45800000, v115
	v_cndmask_b32_e64 v116, v115, v116, s[4:5]
	v_mul_f32_e32 v115, 0x4b800000, v114
	v_cndmask_b32_e32 v114, v114, v115, vcc
	v_rsq_f32_e32 v114, v114
	v_pk_fma_f32 v[142:143], v[228:229], v[116:117], v[46:47] op_sel_hi:[1,0,1]
	v_pk_fma_f32 v[164:165], v[226:227], v[116:117], v[44:45] op_sel_hi:[1,0,1]
	v_pk_fma_f32 v[138:139], v[232:233], v[116:117], v[42:43] op_sel_hi:[1,0,1]
	v_mul_f32_e32 v115, 0x45800000, v114
	v_pk_fma_f32 v[140:141], v[230:231], v[116:117], v[40:41] op_sel_hi:[1,0,1]
	v_pk_fma_f32 v[134:135], v[236:237], v[116:117], v[38:39] op_sel_hi:[1,0,1]
	v_pk_fma_f32 v[136:137], v[234:235], v[116:117], v[36:37] op_sel_hi:[1,0,1]
	v_pk_fma_f32 v[130:131], v[240:241], v[116:117], v[34:35] op_sel_hi:[1,0,1]
	v_pk_fma_f32 v[132:133], v[238:239], v[116:117], v[32:33] op_sel_hi:[1,0,1]
	v_cndmask_b32_e32 v116, v114, v115, vcc
	v_pk_fma_f32 v[126:127], v[244:245], v[116:117], v[46:47] op_sel_hi:[1,0,1]
	v_pk_fma_f32 v[128:129], v[242:243], v[116:117], v[44:45] op_sel_hi:[1,0,1]
	v_pk_fma_f32 v[122:123], v[248:249], v[116:117], v[42:43] op_sel_hi:[1,0,1]
	v_pk_fma_f32 v[124:125], v[246:247], v[116:117], v[40:41] op_sel_hi:[1,0,1]
	v_pk_fma_f32 v[118:119], v[146:147], v[116:117], v[38:39] op_sel_hi:[1,0,1]
	v_pk_fma_f32 v[120:121], v[144:145], v[116:117], v[36:37] op_sel_hi:[1,0,1]
	v_pk_fma_f32 v[114:115], v[50:51], v[116:117], v[34:35] op_sel_hi:[1,0,1]
	v_pk_fma_f32 v[116:117], v[48:49], v[116:117], v[32:33] op_sel_hi:[1,0,1]
	s_waitcnt vmcnt(4)
; DI unsigned pk2(float a, float b) { f32x2 v = {a, b}; bf2_t r = __builtin_convertvector(v, bf2_t); return __builtin_bit_cast(unsigned, r); }
;     static DI void run(const f32x4 (&acc)[8][4], const TileCtx& tc, const Params& p, ldsp_t wb) {
;     ...
;                 for (int n = 0; n < 4; ++n) {
;                     f32x4 a = acc[m][n];
; #pragma unroll
;                     for (int j = 0; j < 4; ++j) { const float r = fmaxf(a[j], 0.f); a[j] = r * r; }
;                     u32x2 w; w[0] = pk2(a[0], a[1]); w[1] = pk2(a[2], a[3]);
; template <int EK>
; DI void gemm_stream(const Params& p, int l, const bf16_t* __restrict__ A, const bf16_t* __restrict__ Bt, int M, int N, int K, ldsp_t shm) {
;     ...
; #pragma unroll
;                 for (int m = 0; m < 8; ++m) {
;                     const f32x4 pp = *(const f32x4*)(ssp + m * 256);
;                     float sq = pp[0] + pp[1] + pp[2] + pp[3];
;                     sq += __shfl_xor(sq, 16);
;                     sq += __shfl_xor(sq, 32);
;                     const float rstd = rsqrtf(sq * (1.f / DM) + EPS);
; #pragma unroll
;                     for (int n = 0; n < 4; ++n) acc[m][n] = acc[m][n] * rstd + shv[n];
	v_mov_b64_e32 v[48:49], v[176:177]
	v_mov_b64_e32 v[50:51], v[178:179]
	v_mov_b64_e32 v[144:145], v[180:181]
	v_mov_b64_e32 v[146:147], v[182:183]
	v_mov_b32_e32 v149, v48
	v_mov_b32_e32 v148, v144
	v_mov_b32_e32 v48, v145
	v_pk_add_f32 v[48:49], v[148:149], v[48:49]
	v_mov_b32_e32 v144, v146
	v_mov_b32_e32 v145, v50
	v_pk_add_f32 v[48:49], v[144:145], v[48:49]
	v_mov_b32_e32 v50, v147
	v_pk_add_f32 v[48:49], v[50:51], v[48:49]
	ds_bpermute_b32 v51, v162, v49
	ds_bpermute_b32 v50, v162, v48
	s_waitcnt lgkmcnt(0)
	v_pk_add_f32 v[48:49], v[48:49], v[50:51]
	ds_bpermute_b32 v51, v161, v49
	ds_bpermute_b32 v50, v161, v48
	s_waitcnt lgkmcnt(0)
	v_pk_add_f32 v[48:49], v[48:49], v[50:51]
	s_nop 0
	v_pk_fma_f32 v[48:49], v[48:49], s[16:17], v[166:167] op_sel_hi:[1,0,0]
	s_nop 0
	v_mul_f32_e32 v50, 0x4b800000, v49
	v_cmp_gt_f32_e64 s[4:5], s92, v49
	v_cmp_gt_f32_e32 vcc, s92, v48
	s_nop 0
	v_cndmask_b32_e64 v49, v49, v50, s[4:5]
	v_rsq_f32_e32 v49, v49
	s_nop 0
	v_mul_f32_e32 v50, 0x45800000, v49
	v_cndmask_b32_e64 v50, v49, v50, s[4:5]
	v_mul_f32_e32 v49, 0x4b800000, v48
	v_cndmask_b32_e32 v48, v48, v49, vcc
	v_rsq_f32_e32 v48, v48
	v_pk_fma_f32 v[110:111], v[110:111], v[50:51], v[46:47] op_sel_hi:[1,0,1]
	v_pk_fma_f32 v[148:149], v[108:109], v[50:51], v[44:45] op_sel_hi:[1,0,1]
	v_pk_fma_f32 v[106:107], v[106:107], v[50:51], v[42:43] op_sel_hi:[1,0,1]
	v_mul_f32_e32 v49, 0x45800000, v48
	v_cndmask_b32_e32 v48, v48, v49, vcc
	v_add_co_u32_e32 v156, vcc, s29, v150
	v_pk_fma_f32 v[104:105], v[104:105], v[50:51], v[40:41] op_sel_hi:[1,0,1]
	s_nop 0
	v_addc_co_u32_e32 v157, vcc, 0, v151, vcc
	v_pk_fma_f32 v[102:103], v[102:103], v[50:51], v[38:39] op_sel_hi:[1,0,1]
	v_pk_fma_f32 v[100:101], v[100:101], v[50:51], v[36:37] op_sel_hi:[1,0,1]
	v_pk_fma_f32 v[98:99], v[98:99], v[50:51], v[34:35] op_sel_hi:[1,0,1]
	v_pk_fma_f32 v[96:97], v[96:97], v[50:51], v[32:33] op_sel_hi:[1,0,1]
	v_pk_fma_f32 v[94:95], v[94:95], v[48:49], v[46:47] op_sel_hi:[1,0,1]
	v_pk_fma_f32 v[92:93], v[92:93], v[48:49], v[44:45] op_sel_hi:[1,0,1]
	v_pk_fma_f32 v[90:91], v[90:91], v[48:49], v[42:43] op_sel_hi:[1,0,1]
	v_pk_fma_f32 v[88:89], v[88:89], v[48:49], v[40:41] op_sel_hi:[1,0,1]
	v_pk_fma_f32 v[86:87], v[86:87], v[48:49], v[38:39] op_sel_hi:[1,0,1]
	v_pk_fma_f32 v[84:85], v[84:85], v[48:49], v[36:37] op_sel_hi:[1,0,1]
	v_pk_fma_f32 v[82:83], v[82:83], v[48:49], v[34:35] op_sel_hi:[1,0,1]
	v_pk_fma_f32 v[80:81], v[80:81], v[48:49], v[32:33] op_sel_hi:[1,0,1]
	s_waitcnt vmcnt(2)
	v_mov_b64_e32 v[48:49], v[184:185]
	v_mov_b64_e32 v[50:51], v[186:187]
	v_mov_b64_e32 v[144:145], v[188:189]
	v_mov_b64_e32 v[146:147], v[190:191]
	v_mov_b32_e32 v109, v48
	v_mov_b32_e32 v108, v144
	v_mov_b32_e32 v48, v145
	v_pk_add_f32 v[48:49], v[108:109], v[48:49]
	v_mov_b32_e32 v108, v146
	v_mov_b32_e32 v109, v50
	v_pk_add_f32 v[48:49], v[108:109], v[48:49]
	v_mov_b32_e32 v50, v147
	v_pk_add_f32 v[48:49], v[50:51], v[48:49]
	ds_bpermute_b32 v51, v162, v49
	ds_bpermute_b32 v50, v162, v48
	s_waitcnt lgkmcnt(0)
	v_pk_add_f32 v[48:49], v[48:49], v[50:51]
	ds_bpermute_b32 v51, v161, v49
	ds_bpermute_b32 v50, v161, v48
	s_waitcnt lgkmcnt(0)
	v_pk_add_f32 v[48:49], v[48:49], v[50:51]
	s_nop 0
	v_pk_fma_f32 v[48:49], v[48:49], s[16:17], v[166:167] op_sel_hi:[1,0,0]
	s_nop 0
	v_mul_f32_e32 v50, 0x4b800000, v49
	v_cmp_gt_f32_e64 s[4:5], s92, v49
	v_cmp_gt_f32_e32 vcc, s92, v48
	s_nop 0
	v_cndmask_b32_e64 v49, v49, v50, s[4:5]
	v_rsq_f32_e32 v49, v49
	s_nop 0
	v_mul_f32_e32 v50, 0x45800000, v49
	v_cndmask_b32_e64 v50, v49, v50, s[4:5]
	v_mul_f32_e32 v49, 0x4b800000, v48
	v_cndmask_b32_e32 v48, v48, v49, vcc
	v_rsq_f32_e32 v48, v48
	v_pk_fma_f32 v[152:153], v[78:79], v[50:51], v[46:47] op_sel_hi:[1,0,1]
	v_pk_fma_f32 v[154:155], v[76:77], v[50:51], v[44:45] op_sel_hi:[1,0,1]
	v_pk_fma_f32 v[108:109], v[74:75], v[50:51], v[42:43] op_sel_hi:[1,0,1]
	v_mul_f32_e32 v49, 0x45800000, v48
	v_cndmask_b32_e32 v48, v48, v49, vcc
	v_pk_fma_f32 v[150:151], v[72:73], v[50:51], v[40:41] op_sel_hi:[1,0,1]
	v_pk_fma_f32 v[76:77], v[70:71], v[50:51], v[38:39] op_sel_hi:[1,0,1]
	v_pk_fma_f32 v[78:79], v[68:69], v[50:51], v[36:37] op_sel_hi:[1,0,1]
	v_pk_fma_f32 v[72:73], v[66:67], v[50:51], v[34:35] op_sel_hi:[1,0,1]
	v_pk_fma_f32 v[74:75], v[64:65], v[50:51], v[32:33] op_sel_hi:[1,0,1]
	v_pk_fma_f32 v[68:69], v[62:63], v[48:49], v[46:47] op_sel_hi:[1,0,1]
	v_pk_fma_f32 v[70:71], v[60:61], v[48:49], v[44:45] op_sel_hi:[1,0,1]
	v_pk_fma_f32 v[64:65], v[58:59], v[48:49], v[42:43] op_sel_hi:[1,0,1]
	v_pk_fma_f32 v[66:67], v[56:57], v[48:49], v[40:41] op_sel_hi:[1,0,1]
	v_pk_fma_f32 v[60:61], v[54:55], v[48:49], v[38:39] op_sel_hi:[1,0,1]
	v_pk_fma_f32 v[62:63], v[52:53], v[48:49], v[36:37] op_sel_hi:[1,0,1]
	v_pk_fma_f32 v[56:57], v[174:175], v[48:49], v[34:35] op_sel_hi:[1,0,1]
	v_pk_fma_f32 v[58:59], v[172:173], v[48:49], v[32:33] op_sel_hi:[1,0,1]
	v_max_f32_e32 v78, 0, v78
	v_max_f32_e32 v79, 0, v79
	v_max_f32_e32 v76, 0, v76
	v_max_f32_e32 v77, 0, v77
	v_max_f32_e32 v74, 0, v74
	v_max_f32_e32 v75, 0, v75
	v_max_f32_e32 v72, 0, v72
	v_max_f32_e32 v73, 0, v73
	v_pk_mul_f32 v[78:79], v[78:79], v[78:79]
	v_pk_mul_f32 v[76:77], v[76:77], v[76:77]
	v_pk_mul_f32 v[74:75], v[74:75], v[74:75]
	v_pk_mul_f32 v[72:73], v[72:73], v[72:73]
	v_cvt_pk_bf16_f32 v78, v78, v79
	v_cvt_pk_bf16_f32 v79, v76, v77
	v_cvt_pk_bf16_f32 v74, v74, v75
	v_cvt_pk_bf16_f32 v75, v72, v73
	v_max_f32_e32 v70, 0, v70
	v_max_f32_e32 v71, 0, v71
	v_max_f32_e32 v68, 0, v68
	v_max_f32_e32 v69, 0, v69
	v_max_f32_e32 v66, 0, v66
	v_max_f32_e32 v67, 0, v67
	v_max_f32_e32 v64, 0, v64
	v_max_f32_e32 v65, 0, v65
	v_max_f32_e32 v62, 0, v62
	v_max_f32_e32 v63, 0, v63
	v_max_f32_e32 v60, 0, v60
	v_max_f32_e32 v61, 0, v61
	v_max_f32_e32 v58, 0, v58
	v_max_f32_e32 v59, 0, v59
	v_max_f32_e32 v56, 0, v56
	v_max_f32_e32 v57, 0, v57
	v_pk_mul_f32 v[70:71], v[70:71], v[70:71]
	v_pk_mul_f32 v[68:69], v[68:69], v[68:69]
	v_pk_mul_f32 v[66:67], v[66:67], v[66:67]
	v_pk_mul_f32 v[64:65], v[64:65], v[64:65]
	v_pk_mul_f32 v[62:63], v[62:63], v[62:63]
	v_pk_mul_f32 v[60:61], v[60:61], v[60:61]
	v_pk_mul_f32 v[58:59], v[58:59], v[58:59]
	v_pk_mul_f32 v[56:57], v[56:57], v[56:57]
	v_cvt_pk_bf16_f32 v70, v70, v71
	v_cvt_pk_bf16_f32 v71, v68, v69
	v_cvt_pk_bf16_f32 v66, v66, v67
	v_cvt_pk_bf16_f32 v67, v64, v65
	v_cvt_pk_bf16_f32 v62, v62, v63
	v_cvt_pk_bf16_f32 v63, v60, v61
	v_cvt_pk_bf16_f32 v58, v58, v59
	v_cvt_pk_bf16_f32 v59, v56, v57
	s_waitcnt vmcnt(0)
; DI unsigned pk2(float a, float b) { f32x2 v = {a, b}; bf2_t r = __builtin_convertvector(v, bf2_t); return __builtin_bit_cast(unsigned, r); }
;     static DI void run(const f32x4 (&acc)[8][4], const TileCtx& tc, const Params& p, ldsp_t wb) {
; #pragma unroll
;         for (int h = 0; h < 2; ++h) {
; #pragma unroll
;             for (int mm = 0; mm < 4; ++mm) {
;                 const int m = h * 4 + mm;
; #pragma unroll
;                 for (int n = 0; n < 4; ++n) {
;                     f32x4 a = acc[m][n];
; #pragma unroll
;                     for (int j = 0; j < 4; ++j) { const float r = fmaxf(a[j], 0.f); a[j] = r * r; }
;                     u32x2 w; w[0] = pk2(a[0], a[1]); w[1] = pk2(a[2], a[3]);
;                     wave_put(wb, mm * 16 + tc.fr, n, tc.fq, w);
;                 }
; template <int EK>
; DI void gemm_stream(const Params& p, int l, const bf16_t* __restrict__ A, const bf16_t* __restrict__ Bt, int M, int N, int K, ldsp_t shm) {
;     ...
; #pragma unroll
;                 for (int m = 0; m < 8; ++m) {
;                     const f32x4 pp = *(const f32x4*)(ssp + m * 256);
;                     float sq = pp[0] + pp[1] + pp[2] + pp[3];
;                     sq += __shfl_xor(sq, 16);
;                     sq += __shfl_xor(sq, 32);
;                     const float rstd = rsqrtf(sq * (1.f / DM) + EPS);
; #pragma unroll
;                     for (int n = 0; n < 4; ++n) acc[m][n] = acc[m][n] * rstd + shv[n];
	v_mov_b64_e32 v[48:49], v[218:219]
	v_mov_b64_e32 v[50:51], v[220:221]
	v_mov_b64_e32 v[52:53], v[222:223]
	v_mov_b64_e32 v[54:55], v[224:225]
	v_mov_b32_e32 v145, v48
	v_mov_b32_e32 v144, v52
	v_mov_b32_e32 v48, v53
	v_pk_add_f32 v[48:49], v[144:145], v[48:49]
	v_mov_b32_e32 v52, v54
	v_mov_b32_e32 v53, v50
	v_pk_add_f32 v[48:49], v[52:53], v[48:49]
	v_mov_b32_e32 v50, v55
	v_pk_add_f32 v[48:49], v[50:51], v[48:49]
	ds_bpermute_b32 v51, v162, v49
	ds_bpermute_b32 v50, v162, v48
	s_waitcnt lgkmcnt(0)
	v_pk_add_f32 v[48:49], v[48:49], v[50:51]
	ds_bpermute_b32 v51, v161, v49
	ds_bpermute_b32 v50, v161, v48
	s_waitcnt lgkmcnt(0)
	v_pk_add_f32 v[48:49], v[48:49], v[50:51]
	s_nop 0
	v_pk_fma_f32 v[48:49], v[48:49], s[16:17], v[166:167] op_sel_hi:[1,0,0]
	s_nop 0
	v_mul_f32_e32 v50, 0x4b800000, v49
	v_cmp_gt_f32_e64 s[4:5], s92, v49
	v_cmp_gt_f32_e32 vcc, s92, v48
	s_nop 0
	v_cndmask_b32_e64 v49, v49, v50, s[4:5]
	v_rsq_f32_e32 v49, v49
	s_nop 0
	v_mul_f32_e32 v50, 0x45800000, v49
	v_cndmask_b32_e64 v50, v49, v50, s[4:5]
	v_mul_f32_e32 v49, 0x4b800000, v48
	v_cndmask_b32_e32 v48, v48, v49, vcc
	v_rsq_f32_e32 v48, v48
	v_pk_fma_f32 v[18:19], v[18:19], v[50:51], v[34:35] op_sel_hi:[1,0,1]
	v_pk_fma_f32 v[16:17], v[16:17], v[50:51], v[32:33] op_sel_hi:[1,0,1]
	v_pk_fma_f32 v[20:21], v[20:21], v[50:51], v[36:37] op_sel_hi:[1,0,1]
	v_mul_f32_e32 v49, 0x45800000, v48
	v_cndmask_b32_e32 v48, v48, v49, vcc
	v_pk_fma_f32 v[2:3], v[2:3], v[48:49], v[34:35] op_sel_hi:[1,0,1]
	v_pk_fma_f32 v[0:1], v[0:1], v[48:49], v[32:33] op_sel_hi:[1,0,1]
	v_max_f32_e32 v32, 0, v164
	v_max_f32_e32 v33, 0, v165
	v_max_f32_e32 v34, 0, v142
	v_max_f32_e32 v35, 0, v143
	v_pk_fma_f32 v[4:5], v[4:5], v[48:49], v[36:37] op_sel_hi:[1,0,1]
	v_pk_mul_f32 v[32:33], v[32:33], v[32:33]
	v_pk_mul_f32 v[34:35], v[34:35], v[34:35]
	v_bfe_u32 v37, v158, 5, 1
	v_add_u32_e32 v36, 0x10000, v160
	v_cvt_pk_bf16_f32 v32, v32, v33
	v_cvt_pk_bf16_f32 v33, v34, v35
	v_bitop3_b32 v34, v37, v158, 7 bitop3:0x78
	v_lshrrev_b32_e32 v35, 1, v158
	v_pk_fma_f32 v[24:25], v[24:25], v[50:51], v[40:41] op_sel_hi:[1,0,1]
	v_pk_fma_f32 v[22:23], v[22:23], v[50:51], v[38:39] op_sel_hi:[1,0,1]
	v_pk_fma_f32 v[8:9], v[8:9], v[48:49], v[40:41] op_sel_hi:[1,0,1]
	v_pk_fma_f32 v[6:7], v[6:7], v[48:49], v[38:39] op_sel_hi:[1,0,1]
	v_lshl_or_b32 v38, v159, 7, v36
	v_lshlrev_b32_e32 v34, 4, v34
	v_and_b32_e32 v40, 8, v35
	v_or3_b32 v52, v38, v34, v40
	ds_write_b64 v52, v[32:33]
	v_max_f32_e32 v32, 0, v140
	v_max_f32_e32 v33, 0, v141
	v_max_f32_e32 v34, 0, v138
	v_max_f32_e32 v35, 0, v139
	v_and_b32_e32 v39, 7, v158
	v_pk_mul_f32 v[32:33], v[32:33], v[32:33]
	v_pk_mul_f32 v[34:35], v[34:35], v[34:35]
	v_cvt_pk_bf16_f32 v32, v32, v33
	v_cvt_pk_bf16_f32 v33, v34, v35
	v_bitop3_b32 v34, v37, v39, 2 bitop3:0x36
	v_lshlrev_b32_e32 v34, 4, v34
	v_or3_b32 v53, v38, v34, v40
	ds_write_b64 v53, v[32:33]
	v_max_f32_e32 v32, 0, v136
	v_max_f32_e32 v33, 0, v137
	v_max_f32_e32 v34, 0, v134
	v_max_f32_e32 v35, 0, v135
	v_pk_mul_f32 v[32:33], v[32:33], v[32:33]
	v_pk_mul_f32 v[34:35], v[34:35], v[34:35]
	v_cvt_pk_bf16_f32 v32, v32, v33
	v_cvt_pk_bf16_f32 v33, v34, v35
	v_bitop3_b32 v34, v37, v39, 4 bitop3:0x36
	v_lshlrev_b32_e32 v34, 4, v34
	v_or3_b32 v54, v38, v34, v40
	ds_write_b64 v54, v[32:33]
	v_max_f32_e32 v32, 0, v132
	v_max_f32_e32 v33, 0, v133
	v_max_f32_e32 v34, 0, v130
	v_max_f32_e32 v35, 0, v131
	v_pk_mul_f32 v[32:33], v[32:33], v[32:33]
	v_pk_mul_f32 v[34:35], v[34:35], v[34:35]
	v_cvt_pk_bf16_f32 v32, v32, v33
	v_cvt_pk_bf16_f32 v33, v34, v35
	v_bitop3_b32 v34, v37, v39, 6 bitop3:0x36
	v_lshlrev_b32_e32 v34, 4, v34
	v_or3_b32 v55, v38, v34, v40
	ds_write_b64 v55, v[32:33]
	v_max_f32_e32 v32, 0, v128
	v_max_f32_e32 v33, 0, v129
	v_max_f32_e32 v34, 0, v126
	v_max_f32_e32 v35, 0, v127
	v_pk_mul_f32 v[32:33], v[32:33], v[32:33]
	v_pk_mul_f32 v[34:35], v[34:35], v[34:35]
	v_cvt_pk_bf16_f32 v32, v32, v33
	v_cvt_pk_bf16_f32 v33, v34, v35
	ds_write_b64 v52, v[32:33] offset:2048
	v_max_f32_e32 v32, 0, v124
	v_max_f32_e32 v33, 0, v125
	v_max_f32_e32 v34, 0, v122
	v_max_f32_e32 v35, 0, v123
	v_pk_mul_f32 v[32:33], v[32:33], v[32:33]
	v_pk_mul_f32 v[34:35], v[34:35], v[34:35]
	v_cvt_pk_bf16_f32 v32, v32, v33
	v_cvt_pk_bf16_f32 v33, v34, v35
	ds_write_b64 v53, v[32:33] offset:2048
	v_max_f32_e32 v32, 0, v120
	v_max_f32_e32 v33, 0, v121
	v_max_f32_e32 v34, 0, v118
	v_max_f32_e32 v35, 0, v119
	v_pk_mul_f32 v[32:33], v[32:33], v[32:33]
	v_pk_mul_f32 v[34:35], v[34:35], v[34:35]
	v_cvt_pk_bf16_f32 v32, v32, v33
	v_cvt_pk_bf16_f32 v33, v34, v35
	ds_write_b64 v54, v[32:33] offset:2048
	v_max_f32_e32 v32, 0, v116
	v_max_f32_e32 v33, 0, v117
	v_max_f32_e32 v34, 0, v114
	v_max_f32_e32 v35, 0, v115
	v_pk_mul_f32 v[32:33], v[32:33], v[32:33]
	v_pk_mul_f32 v[34:35], v[34:35], v[34:35]
	v_cvt_pk_bf16_f32 v32, v32, v33
	v_cvt_pk_bf16_f32 v33, v34, v35
	ds_write_b64 v55, v[32:33] offset:2048
	v_max_f32_e32 v32, 0, v148
	v_max_f32_e32 v33, 0, v149
	v_max_f32_e32 v34, 0, v110
	v_max_f32_e32 v35, 0, v111
	v_pk_mul_f32 v[32:33], v[32:33], v[32:33]
	v_pk_mul_f32 v[34:35], v[34:35], v[34:35]
	v_cvt_pk_bf16_f32 v32, v32, v33
	v_cvt_pk_bf16_f32 v33, v34, v35
	ds_write_b64 v52, v[32:33] offset:4096
	v_max_f32_e32 v32, 0, v104
	v_max_f32_e32 v33, 0, v105
	v_max_f32_e32 v34, 0, v106
	v_max_f32_e32 v35, 0, v107
	v_pk_mul_f32 v[32:33], v[32:33], v[32:33]
	v_pk_mul_f32 v[34:35], v[34:35], v[34:35]
	v_cvt_pk_bf16_f32 v32, v32, v33
	v_cvt_pk_bf16_f32 v33, v34, v35
	ds_write_b64 v53, v[32:33] offset:4096
	v_max_f32_e32 v32, 0, v100
	v_max_f32_e32 v33, 0, v101
	v_max_f32_e32 v34, 0, v102
	v_max_f32_e32 v35, 0, v103
	v_pk_mul_f32 v[32:33], v[32:33], v[32:33]
; #define LDSP __attribute__((address_space(3)))
; DI unsigned pk2(float a, float b) { f32x2 v = {a, b}; bf2_t r = __builtin_convertvector(v, bf2_t); return __builtin_bit_cast(unsigned, r); }
; DI void wave_rows_store(ldsp_t wb, int lane, bf16_t* dst0, size_t ld) {
; #pragma unroll
;     for (int i = 0; i < 8; ++i) {
;         const int row = i * 8 + (lane >> 3), ch = lane & 7;
;         const u32x4 v = *(const LDSP u32x4*)(wb + row * 128 + ((ch ^ (row & 7)) << 4));
;         *(u32x4*)(dst0 + (size_t)row * ld + ch * 8) = v;
;     }
;     static DI void run(const f32x4 (&acc)[8][4], const TileCtx& tc, const Params& p, ldsp_t wb) {
;     ...
;                 for (int n = 0; n < 4; ++n) {
;                     f32x4 a = acc[m][n];
; #pragma unroll
;                     for (int j = 0; j < 4; ++j) { const float r = fmaxf(a[j], 0.f); a[j] = r * r; }
;                     u32x2 w; w[0] = pk2(a[0], a[1]); w[1] = pk2(a[2], a[3]);
;                     wave_put(wb, mm * 16 + tc.fr, n, tc.fq, w);
;                 }
;             }
;             wave_rows_store(wb, tc.lane, p.ACT + (size_t)(tc.brow + tc.wr * 128 + h * 64) * FF + tc.bcol + tc.wc * 64, FF);
	v_pk_mul_f32 v[34:35], v[34:35], v[34:35]
	v_cvt_pk_bf16_f32 v32, v32, v33
	v_cvt_pk_bf16_f32 v33, v34, v35
	ds_write_b64 v54, v[32:33] offset:4096
	v_max_f32_e32 v32, 0, v96
	v_max_f32_e32 v33, 0, v97
	v_max_f32_e32 v34, 0, v98
	v_max_f32_e32 v35, 0, v99
	v_pk_mul_f32 v[32:33], v[32:33], v[32:33]
	v_pk_mul_f32 v[34:35], v[34:35], v[34:35]
	v_cvt_pk_bf16_f32 v32, v32, v33
	v_cvt_pk_bf16_f32 v33, v34, v35
	ds_write_b64 v55, v[32:33] offset:4096
	v_max_f32_e32 v32, 0, v92
	v_max_f32_e32 v33, 0, v93
	v_max_f32_e32 v34, 0, v94
	v_max_f32_e32 v35, 0, v95
	v_pk_mul_f32 v[32:33], v[32:33], v[32:33]
	v_pk_mul_f32 v[34:35], v[34:35], v[34:35]
	v_cvt_pk_bf16_f32 v32, v32, v33
	v_cvt_pk_bf16_f32 v33, v34, v35
	ds_write_b64 v52, v[32:33] offset:6144
	v_max_f32_e32 v32, 0, v88
	v_max_f32_e32 v33, 0, v89
	v_max_f32_e32 v34, 0, v90
	v_max_f32_e32 v35, 0, v91
	v_pk_mul_f32 v[32:33], v[32:33], v[32:33]
	v_pk_mul_f32 v[34:35], v[34:35], v[34:35]
	v_cvt_pk_bf16_f32 v32, v32, v33
	v_cvt_pk_bf16_f32 v33, v34, v35
	ds_write_b64 v53, v[32:33] offset:6144
	v_max_f32_e32 v32, 0, v84
	v_max_f32_e32 v33, 0, v85
	v_max_f32_e32 v34, 0, v86
	v_max_f32_e32 v35, 0, v87
	v_pk_mul_f32 v[32:33], v[32:33], v[32:33]
	v_pk_mul_f32 v[34:35], v[34:35], v[34:35]
	v_cvt_pk_bf16_f32 v32, v32, v33
	v_cvt_pk_bf16_f32 v33, v34, v35
	ds_write_b64 v54, v[32:33] offset:6144
	v_max_f32_e32 v32, 0, v80
	v_max_f32_e32 v33, 0, v81
	v_max_f32_e32 v34, 0, v82
	v_max_f32_e32 v35, 0, v83
	v_pk_fma_f32 v[28:29], v[28:29], v[50:51], v[44:45] op_sel_hi:[1,0,1]
	v_pk_fma_f32 v[12:13], v[12:13], v[48:49], v[44:45] op_sel_hi:[1,0,1]
	v_pk_mul_f32 v[32:33], v[32:33], v[32:33]
	v_pk_mul_f32 v[34:35], v[34:35], v[34:35]
	v_add_u32_e32 v44, s35, v112
	v_cvt_pk_bf16_f32 v32, v32, v33
	v_cvt_pk_bf16_f32 v33, v34, v35
	v_ashrrev_i32_e32 v45, 31, v44
	ds_write_b64 v55, v[32:33] offset:6144
	v_lshlrev_b64 v[32:33], 13, v[44:45]
	v_bfe_u32 v45, v158, 3, 3
	v_xor_b32_e32 v34, v45, v158
	v_lshl_add_u64 v[32:33], s[12:13], 0, v[32:33]
	s_lshl_b64 s[4:5], s[42:43], 1
	v_lshlrev_b32_e32 v34, 4, v34
	v_lshl_add_u64 v[32:33], v[32:33], 0, s[4:5]
	v_and_or_b32 v86, v34, s15, v36
	v_lshlrev_b32_e32 v34, 4, v158
	v_pk_fma_f32 v[30:31], v[30:31], v[50:51], v[46:47] op_sel_hi:[1,0,1]
	v_pk_fma_f32 v[26:27], v[26:27], v[50:51], v[42:43] op_sel_hi:[1,0,1]
	v_lshl_add_u64 v[32:33], v[32:33], 0, v[192:193]
	v_and_b32_e32 v50, 0x70, v34
	v_mov_b32_e32 v51, v193
	v_lshl_or_b32 v87, v45, 7, v86
	v_lshl_add_u64 v[84:85], v[32:33], 0, v[50:51]
	ds_read_b128 v[32:35], v87
	v_pk_fma_f32 v[14:15], v[14:15], v[48:49], v[46:47] op_sel_hi:[1,0,1]
	v_pk_fma_f32 v[10:11], v[10:11], v[48:49], v[42:43] op_sel_hi:[1,0,1]
	v_lshlrev_b32_e32 v48, 13, v45
	v_mov_b32_e32 v49, v193
	v_lshl_add_u64 v[36:37], v[84:85], 0, v[48:49]
	s_waitcnt lgkmcnt(0)
	global_store_dwordx4 v[36:37], v[32:35], off sc1
	v_or_b32_e32 v36, 8, v45
	v_lshl_or_b32 v88, v36, 7, v86
	ds_read_b128 v[32:35], v88
	v_lshlrev_b32_e32 v46, 13, v36
	v_mov_b32_e32 v47, v193
	v_lshl_add_u64 v[36:37], v[84:85], 0, v[46:47]
	v_mov_b32_e32 v43, v193
	s_waitcnt lgkmcnt(0)
	global_store_dwordx4 v[36:37], v[32:35], off sc1
	v_or_b32_e32 v36, 16, v45
	v_lshl_or_b32 v89, v36, 7, v86
	ds_read_b128 v[32:35], v89
	v_lshlrev_b32_e32 v42, 13, v36
	v_lshl_add_u64 v[36:37], v[84:85], 0, v[42:43]
	v_mov_b32_e32 v41, v193
	v_max_f32_e32 v0, 0, v0
	s_waitcnt lgkmcnt(0)
	global_store_dwordx4 v[36:37], v[32:35], off sc1
	v_or_b32_e32 v36, 24, v45
	v_lshl_or_b32 v90, v36, 7, v86
	ds_read_b128 v[32:35], v90
	v_lshlrev_b32_e32 v40, 13, v36
	v_lshl_add_u64 v[36:37], v[84:85], 0, v[40:41]
	v_max_f32_e32 v1, 0, v1
	v_max_f32_e32 v2, 0, v2
	s_waitcnt lgkmcnt(0)
	global_store_dwordx4 v[36:37], v[32:35], off sc1
	v_max_f32_e32 v3, 0, v3
	v_pk_mul_f32 v[0:1], v[0:1], v[0:1]
	v_or_b32_e32 v32, 32, v45
	v_lshl_or_b32 v91, v32, 7, v86
	ds_read_b128 v[36:39], v91
	v_lshlrev_b32_e32 v34, 13, v32
	v_mov_b32_e32 v35, v193
	v_lshl_add_u64 v[32:33], v[84:85], 0, v[34:35]
	v_pk_mul_f32 v[2:3], v[2:3], v[2:3]
	s_waitcnt lgkmcnt(0)
	global_store_dwordx4 v[32:33], v[36:39], off sc1
	v_or_b32_e32 v32, 40, v45
	v_lshl_or_b32 v92, v32, 7, v86
	ds_read_b128 v[80:83], v92
	v_lshlrev_b32_e32 v38, 13, v32
	v_mov_b32_e32 v39, v193
	v_lshl_add_u64 v[32:33], v[84:85], 0, v[38:39]
	v_mov_b32_e32 v37, v193
	s_waitcnt lgkmcnt(0)
	global_store_dwordx4 v[32:33], v[80:83], off sc1
	v_or_b32_e32 v32, 48, v45
	v_lshl_or_b32 v93, v32, 7, v86
	ds_read_b128 v[80:83], v93
	v_lshlrev_b32_e32 v36, 13, v32
	v_lshl_add_u64 v[32:33], v[84:85], 0, v[36:37]
	v_cvt_pk_bf16_f32 v0, v0, v1
	v_cvt_pk_bf16_f32 v1, v2, v3
	s_waitcnt lgkmcnt(0)
; DI unsigned pk2(float a, float b) { f32x2 v = {a, b}; bf2_t r = __builtin_convertvector(v, bf2_t); return __builtin_bit_cast(unsigned, r); }
;     static DI void run(const f32x4 (&acc)[8][4], const TileCtx& tc, const Params& p, ldsp_t wb) {
; #pragma unroll
;         for (int h = 0; h < 2; ++h) {
; #pragma unroll
;             for (int mm = 0; mm < 4; ++mm) {
;                 const int m = h * 4 + mm;
; #pragma unroll
;                 for (int n = 0; n < 4; ++n) {
;                     f32x4 a = acc[m][n];
; #pragma unroll
;                     for (int j = 0; j < 4; ++j) { const float r = fmaxf(a[j], 0.f); a[j] = r * r; }
;                     u32x2 w; w[0] = pk2(a[0], a[1]); w[1] = pk2(a[2], a[3]);
;                     wave_put(wb, mm * 16 + tc.fr, n, tc.fq, w);
;                 }
;             }
;             wave_rows_store(wb, tc.lane, p.ACT + (size_t)(tc.brow + tc.wr * 128 + h * 64) * FF + tc.bcol + tc.wc * 64, FF);
;         }
	global_store_dwordx4 v[32:33], v[80:83], off sc1
	v_or_b32_e32 v32, 56, v45
	v_lshl_or_b32 v45, v32, 7, v86
	ds_read_b128 v[80:83], v45
	v_lshlrev_b32_e32 v32, 13, v32
	v_mov_b32_e32 v33, v193
	v_lshl_add_u64 v[84:85], v[84:85], 0, v[32:33]
	ds_write_b64 v55, v[0:1] offset:6144
	s_waitcnt lgkmcnt(1)
	global_store_dwordx4 v[84:85], v[80:83], off sc1
	v_or_b32_e32 v0, 64, v44
	v_ashrrev_i32_e32 v1, 31, v0
	v_max_f32_e32 v80, 0, v154
	v_max_f32_e32 v81, 0, v155
	v_max_f32_e32 v82, 0, v152
	v_max_f32_e32 v83, 0, v153
	v_pk_mul_f32 v[80:81], v[80:81], v[80:81]
	v_pk_mul_f32 v[82:83], v[82:83], v[82:83]
	v_cvt_pk_bf16_f32 v80, v80, v81
	v_cvt_pk_bf16_f32 v81, v82, v83
	ds_write_b64 v52, v[80:81]
	v_max_f32_e32 v80, 0, v150
	v_max_f32_e32 v81, 0, v151
	v_max_f32_e32 v82, 0, v108
	v_max_f32_e32 v83, 0, v109
	v_lshlrev_b64 v[0:1], 13, v[0:1]
	v_pk_mul_f32 v[80:81], v[80:81], v[80:81]
	v_pk_mul_f32 v[82:83], v[82:83], v[82:83]
	v_max_f32_e32 v4, 0, v4
	v_max_f32_e32 v5, 0, v5
	v_max_f32_e32 v6, 0, v6
	v_max_f32_e32 v7, 0, v7
	v_lshl_add_u64 v[0:1], s[12:13], 0, v[0:1]
	v_cvt_pk_bf16_f32 v80, v80, v81
	v_cvt_pk_bf16_f32 v81, v82, v83
	v_pk_mul_f32 v[4:5], v[4:5], v[4:5]
	v_pk_mul_f32 v[6:7], v[6:7], v[6:7]
	v_lshl_add_u64 v[0:1], v[0:1], 0, s[4:5]
	ds_write_b64 v53, v[80:81]
	ds_write_b64 v54, v[78:79]
	ds_write_b64 v55, v[74:75]
	v_cvt_pk_bf16_f32 v4, v4, v5
	v_cvt_pk_bf16_f32 v5, v6, v7
	v_lshl_add_u64 v[0:1], v[0:1], 0, v[192:193]
	ds_write_b64 v54, v[4:5] offset:6144
	v_lshl_add_u64 v[4:5], v[0:1], 0, v[50:51]
	ds_read_b128 v[0:3], v87
	v_lshl_add_u64 v[6:7], v[4:5], 0, v[48:49]
	ds_write_b64 v52, v[70:71] offset:2048
	ds_write_b64 v53, v[66:67] offset:2048
	ds_write_b64 v54, v[62:63] offset:2048
	s_waitcnt lgkmcnt(3)
	global_store_dwordx4 v[6:7], v[0:3], off sc1
	ds_read_b128 v[0:3], v88
	ds_write_b64 v55, v[58:59] offset:2048
	v_lshl_add_u64 v[6:7], v[4:5], 0, v[46:47]
	v_max_f32_e32 v28, 0, v28
	v_max_f32_e32 v29, 0, v29
	s_waitcnt lgkmcnt(1)
	global_store_dwordx4 v[6:7], v[0:3], off sc1
	ds_read_b128 v[0:3], v89
	v_lshl_add_u64 v[6:7], v[4:5], 0, v[42:43]
	v_max_f32_e32 v30, 0, v30
	v_max_f32_e32 v31, 0, v31
	v_max_f32_e32 v24, 0, v24
	s_waitcnt lgkmcnt(0)
	global_store_dwordx4 v[6:7], v[0:3], off sc1
	ds_read_b128 v[0:3], v90
	v_max_f32_e32 v25, 0, v25
	v_max_f32_e32 v26, 0, v26
	v_max_f32_e32 v27, 0, v27
	v_max_f32_e32 v20, 0, v20
	v_max_f32_e32 v21, 0, v21
	v_max_f32_e32 v22, 0, v22
	v_max_f32_e32 v23, 0, v23
	v_max_f32_e32 v16, 0, v16
	v_max_f32_e32 v17, 0, v17
	v_max_f32_e32 v18, 0, v18
	v_max_f32_e32 v19, 0, v19
	v_pk_mul_f32 v[28:29], v[28:29], v[28:29]
	v_pk_mul_f32 v[30:31], v[30:31], v[30:31]
	v_pk_mul_f32 v[24:25], v[24:25], v[24:25]
	v_pk_mul_f32 v[26:27], v[26:27], v[26:27]
	v_pk_mul_f32 v[20:21], v[20:21], v[20:21]
	v_pk_mul_f32 v[22:23], v[22:23], v[22:23]
	v_pk_mul_f32 v[16:17], v[16:17], v[16:17]
	v_pk_mul_f32 v[18:19], v[18:19], v[18:19]
	v_cvt_pk_bf16_f32 v28, v28, v29
	v_cvt_pk_bf16_f32 v29, v30, v31
	v_cvt_pk_bf16_f32 v24, v24, v25
	v_cvt_pk_bf16_f32 v25, v26, v27
	v_cvt_pk_bf16_f32 v20, v20, v21
	v_cvt_pk_bf16_f32 v21, v22, v23
	v_cvt_pk_bf16_f32 v16, v16, v17
	v_cvt_pk_bf16_f32 v17, v18, v19
	ds_write_b64 v52, v[28:29] offset:4096
	ds_write_b64 v53, v[24:25] offset:4096
	ds_write_b64 v54, v[20:21] offset:4096
	ds_write_b64 v55, v[16:17] offset:4096
	v_lshl_add_u64 v[6:7], v[4:5], 0, v[40:41]
	s_waitcnt lgkmcnt(4)
	global_store_dwordx4 v[6:7], v[0:3], off sc1
	ds_read_b128 v[0:3], v91
	v_lshl_add_u64 v[6:7], v[4:5], 0, v[34:35]
	v_max_f32_e32 v12, 0, v12
	v_max_f32_e32 v13, 0, v13
	v_max_f32_e32 v14, 0, v14
	s_waitcnt lgkmcnt(0)
	global_store_dwordx4 v[6:7], v[0:3], off sc1
	ds_read_b128 v[0:3], v92
	v_max_f32_e32 v15, 0, v15
	v_max_f32_e32 v8, 0, v8
	v_max_f32_e32 v9, 0, v9
	v_max_f32_e32 v10, 0, v10
	v_max_f32_e32 v11, 0, v11
	v_pk_mul_f32 v[12:13], v[12:13], v[12:13]
	v_pk_mul_f32 v[14:15], v[14:15], v[14:15]
	v_pk_mul_f32 v[8:9], v[8:9], v[8:9]
	v_pk_mul_f32 v[10:11], v[10:11], v[10:11]
	v_cvt_pk_bf16_f32 v12, v12, v13
	v_cvt_pk_bf16_f32 v13, v14, v15
	v_cvt_pk_bf16_f32 v8, v8, v9
	v_cvt_pk_bf16_f32 v9, v10, v11
	ds_write_b64 v52, v[12:13] offset:6144
	ds_write_b64 v53, v[8:9] offset:6144
	v_lshl_add_u64 v[6:7], v[4:5], 0, v[38:39]
	s_waitcnt lgkmcnt(2)
	global_store_dwordx4 v[6:7], v[0:3], off sc1
	ds_read_b128 v[0:3], v93
	v_lshl_add_u64 v[6:7], v[4:5], 0, v[36:37]
	v_lshl_add_u64 v[4:5], v[4:5], 0, v[32:33]
	s_and_b64 vcc, exec, s[6:7]
	s_waitcnt lgkmcnt(0)
	global_store_dwordx4 v[6:7], v[0:3], off sc1
	ds_read_b128 v[0:3], v45
	s_waitcnt lgkmcnt(0)
	global_store_dwordx4 v[4:5], v[0:3], off sc1
	s_barrier
	s_cbranch_vccnz .LBB0_117

; #define WAIT_V0() asm volatile("s_waitcnt vmcnt(0)" ::: "memory")
; #define G_STAGE_A(Ap, buf, kt) do { const char* ab_ = (const char*)(Ap) + (size_t)(kt) * 128; \
;       _Pragma("unroll") for (int i = 0; i < 4; ++i) \
;         __builtin_amdgcn_global_load_lds((const unsigned*)(ab_ + soff[i]), (LDSP unsigned*)(G_SA(buf) + wid * 1024 + i * 8192), 16, 0, 0); } while (0)
; #define G_STAGE_B(Bp, buf, kt) do { const char* bb_ = (const char*)(Bp) + (size_t)(kt) * 128; \
;       _Pragma("unroll") for (int i = 0; i < 4; ++i) \
;         __builtin_amdgcn_global_load_lds((const unsigned*)(bb_ + soff[i]), (LDSP unsigned*)(G_SB(buf) + wid * 1024 + i * 8192), 16, 0, 0); } while (0)
; #define G_RDA(AF, buf, ks, mh) do { _Pragma("unroll") for (int m = 0; m < 4; ++m) AF[m] = *(const LDSP bf16x8*)(G_SA(buf) + aoff + ((mh) * 4 + m) * 2048 + (ks) * 1024); } while (0)
; #define G_RDB(BF, buf, ks) do { _Pragma("unroll") for (int n = 0; n < 4; ++n) BF[n] = *(const LDSP bf16x8*)(G_SB(buf) + boff + n * 2048 + (ks) * 1024); } while (0)
; #define G_SB0() __builtin_amdgcn_sched_barrier(0)
; template <int EK>
; DI void gemm_stream(const Params& p, int l, const bf16_t* __restrict__ A, const bf16_t* __restrict__ Bt, int M, int N, int K, ldsp_t shm) {
;     ...
;         for (int t = 0; t < nt; ++t) {
;             const int cur = t & 1;
;             G_RDA(Aa, cur, 0, 0); G_RDB(Bk0, cur, 0);
;             if (t + 1 < nt) G_STAGE_B(Bb, cur ^ 1, t + 1);
;             else if (has_next) G_STAGE_B(Bb2, cur ^ 1, 0);
;             G_SB0();
;             if (t > 0) G_MMA(Ab_, Bk1, 1);
;             G_SB0();
;             if (t + 1 < nt) G_STAGE_A(Ab, cur ^ 1, t + 1);
;             else if (has_next) G_STAGE_A(Ab2, cur ^ 1, 0);
;             G_RDA(Ab_, cur, 0, 1);
;             G_MMA(Aa, Bk0, 0); G_SB0();
;             G_RDA(Aa, cur, 1, 0); G_RDB(Bk1, cur, 1);
;             G_MMA(Ab_, Bk0, 1); G_SB0();
;             G_RDA(Ab_, cur, 1, 1);
;             G_MMA(Aa, Bk1, 0); G_SB0();
;             asm volatile("s_waitcnt lgkmcnt(0)" ::: "memory");
;             WAIT_V0(); __syncthreads();
;         }
;         G_MMA(Ab_, Bk1, 1);
.LBB0_269:
	v_add_u32_e32 v80, 0x12000, v218
	v_add_u32_e32 v132, 0x12800, v218
	v_add_u32_e32 v136, 0x13000, v218
	v_add_u32_e32 v140, 0x13800, v218
	ds_read_b128 v[80:83], v80
	ds_read_b128 v[132:135], v132
	ds_read_b128 v[136:139], v136
	ds_read_b128 v[140:143], v140
	s_setprio 1
	s_waitcnt lgkmcnt(0)
	v_mfma_f32_16x16x32_bf16 v[20:23], v[164:167], v[180:183], v[20:23]
	v_mfma_f32_16x16x32_bf16 v[24:27], v[168:171], v[180:183], v[24:27]
	v_mfma_f32_16x16x32_bf16 v[28:31], v[172:175], v[180:183], v[28:31]
	v_mfma_f32_16x16x32_bf16 v[44:47], v[172:175], v[184:187], v[44:47]
	v_mfma_f32_16x16x32_bf16 v[48:51], v[160:163], v[176:179], v[48:51]
	v_mfma_f32_16x16x32_bf16 v[52:55], v[164:167], v[176:179], v[52:55]
	v_mfma_f32_16x16x32_bf16 v[56:59], v[168:171], v[176:179], v[56:59]
	v_mfma_f32_16x16x32_bf16 v[60:63], v[172:175], v[176:179], v[60:63]
	v_mfma_f32_16x16x32_bf16 v[0:3], v[160:163], v[188:191], v[0:3]
	v_mfma_f32_16x16x32_bf16 v[4:7], v[164:167], v[188:191], v[4:7]
	v_mfma_f32_16x16x32_bf16 v[8:11], v[168:171], v[188:191], v[8:11]
	v_mfma_f32_16x16x32_bf16 v[12:15], v[172:175], v[188:191], v[12:15]
	v_mfma_f32_16x16x32_bf16 v[16:19], v[160:163], v[180:183], v[16:19]
	v_mfma_f32_16x16x32_bf16 v[32:35], v[160:163], v[184:187], v[32:35]
	v_mfma_f32_16x16x32_bf16 v[36:39], v[164:167], v[184:187], v[36:39]
	v_mfma_f32_16x16x32_bf16 v[40:43], v[168:171], v[184:187], v[40:43]
	s_setprio 0
	v_add_u32_e32 v144, 0x10400, v218
	v_add_u32_e32 v148, 0x10c00, v218
	v_add_u32_e32 v152, 0x11400, v218
	v_add_u32_e32 v156, 0x11c00, v218
	v_add_u32_e32 v176, 0x18400, v219
	v_add_u32_e32 v180, 0x18c00, v219
	v_add_u32_e32 v184, 0x19400, v219
	v_add_u32_e32 v188, 0x19c00, v219
	ds_read_b128 v[144:147], v144
	ds_read_b128 v[148:151], v148
	ds_read_b128 v[152:155], v152
	ds_read_b128 v[156:159], v156
	ds_read_b128 v[176:179], v176
	ds_read_b128 v[180:183], v180
	ds_read_b128 v[184:187], v184
	ds_read_b128 v[188:191], v188
	s_setprio 1
	v_mfma_f32_16x16x32_bf16 v[128:131], v[160:163], v[80:83], v[128:131]
	v_mfma_f32_16x16x32_bf16 v[124:127], v[164:167], v[80:83], v[124:127]
	v_mfma_f32_16x16x32_bf16 v[120:123], v[168:171], v[80:83], v[120:123]
	v_mfma_f32_16x16x32_bf16 v[116:119], v[172:175], v[80:83], v[116:119]
	v_mfma_f32_16x16x32_bf16 v[112:115], v[160:163], v[132:135], v[112:115]
	v_mfma_f32_16x16x32_bf16 v[194:197], v[164:167], v[132:135], v[108:111]
	v_mfma_f32_16x16x32_bf16 v[214:217], v[168:171], v[132:135], v[104:107]
	v_mfma_f32_16x16x32_bf16 v[132:135], v[172:175], v[132:135], v[100:103]
	v_mfma_f32_16x16x32_bf16 v[220:223], v[160:163], v[136:139], v[96:99]
	v_mfma_f32_16x16x32_bf16 v[224:227], v[164:167], v[136:139], v[92:95]
	v_mfma_f32_16x16x32_bf16 v[228:231], v[168:171], v[136:139], v[88:91]
	v_mfma_f32_16x16x32_bf16 v[136:139], v[172:175], v[136:139], v[84:87]
	v_mfma_f32_16x16x32_bf16 v[160:163], v[160:163], v[140:143], v[64:67]
	v_mfma_f32_16x16x32_bf16 v[164:167], v[164:167], v[140:143], v[68:71]
	v_mfma_f32_16x16x32_bf16 v[168:171], v[168:171], v[140:143], v[76:79]
	v_mfma_f32_16x16x32_bf16 v[140:143], v[172:175], v[140:143], v[72:75]
	s_setprio 0
	v_add_u32_e32 v64, 0x12400, v218
	v_add_u32_e32 v68, 0x12c00, v218
	ds_read_b128 v[64:67], v64
	ds_read_b128 v[172:175], v68
	v_add_u32_e32 v68, 0x13400, v218
	v_add_u32_e32 v69, 0x13c00, v218
	ds_read_b128 v[232:235], v68
	ds_read_b128 v[236:239], v69
	s_setprio 1
	s_waitcnt lgkmcnt(0)
	v_mfma_f32_16x16x32_bf16 v[240:243], v[176:179], v[144:147], v[0:3]
	v_mfma_f32_16x16x32_bf16 v[244:247], v[180:183], v[144:147], v[4:7]
	v_mfma_f32_16x16x32_bf16 v[248:251], v[184:187], v[144:147], v[8:11]
	v_mfma_f32_16x16x32_bf16 v[144:147], v[188:191], v[144:147], v[12:15]
	v_mfma_f32_16x16x32_bf16 v[108:111], v[176:179], v[152:155], v[32:35]
	v_mfma_f32_16x16x32_bf16 v[104:107], v[180:183], v[152:155], v[36:39]
	v_mfma_f32_16x16x32_bf16 v[100:103], v[184:187], v[152:155], v[40:43]
	v_mfma_f32_16x16x32_bf16 v[96:99], v[188:191], v[152:155], v[44:47]
	v_mfma_f32_16x16x32_bf16 v[92:95], v[176:179], v[156:159], v[48:51]
	v_mfma_f32_16x16x32_bf16 v[88:91], v[180:183], v[156:159], v[52:55]
	v_mfma_f32_16x16x32_bf16 v[84:87], v[184:187], v[156:159], v[56:59]
	v_mfma_f32_16x16x32_bf16 v[80:83], v[188:191], v[156:159], v[60:63]
	v_mfma_f32_16x16x32_bf16 v[210:213], v[176:179], v[148:151], v[16:19]
	v_mfma_f32_16x16x32_bf16 v[204:207], v[180:183], v[148:151], v[20:23]
	v_mfma_f32_16x16x32_bf16 v[198:201], v[184:187], v[148:151], v[24:27]
	v_mfma_f32_16x16x32_bf16 v[148:151], v[188:191], v[148:151], v[28:31]
	s_setprio 0
	s_waitcnt lgkmcnt(0)
	s_waitcnt vmcnt(0)
	s_waitcnt vmcnt(0)
	s_barrier
; #define G_STAGE_B(Bp, buf, kt) do { const char* bb_ = (const char*)(Bp) + (size_t)(kt) * 128; \
;       _Pragma("unroll") for (int i = 0; i < 4; ++i) \
;         __builtin_amdgcn_global_load_lds((const unsigned*)(bb_ + soff[i]), (LDSP unsigned*)(G_SB(buf) + wid * 1024 + i * 8192), 16, 0, 0); } while (0)
; #define G_MMA(AF, BF, mh) do { __builtin_amdgcn_s_setprio(1); \
;             _Pragma("unroll") for (int m = 0; m < 4; ++m) _Pragma("unroll") for (int n = 0; n < 4; ++n) \
;                 acc[(mh) * 4 + m][n] = __builtin_amdgcn_mfma_f32_16x16x32_bf16(BF[n], AF[m], acc[(mh) * 4 + m][n], 0, 0, 0); \
;             __builtin_amdgcn_s_setprio(0); } while (0)
; template <int EK>
; DI void gemm_stream(const Params& p, int l, const bf16_t* __restrict__ A, const bf16_t* __restrict__ Bt, int M, int N, int K, ldsp_t shm) {
;     ...
;         G_MMA(Ab_, Bk1, 1);
;         G_SB0();
;         {
;             int tid2 = threadIdx.x, pme = pm, pne = pn;
;             asm volatile("" : "+v"(tid2), "+s"(pme), "+s"(pne));
;             TileCtx tc;
;             tc.wid = tid2 >> 6; tc.lane = tid2 & 63; tc.wr = tc.wid >> 2; tc.wc = tc.wid & 3; tc.fr = tc.lane & 15; tc.fq = tc.lane >> 4; tc.l = l;
;             tc.brow = pme * 256; tc.bcol = pne * 256; tc.pn = pne;
;             ldsp_t ex = shm + G_STAGE_B + tc.wid * 8192;
;             if (EK == 0 || EK == 2) {
;                 const int cond = tc.brow < NLAT ? (tc.brow >> 12) : 4;
;                 const float* ssp = p.ss + ((size_t)(l * 2 + (EK == 0 ? 0 : 1)) * NTOK + tc.brow + tc.wr * 128 + tc.fr) * 16 + tc.fq * 4;
;                 const float* shw = (EK == 0 ? p.shw_in + ((size_t)l * 5 + cond) * IN_DIM : p.shw_ff1 + ((size_t)l * 5 + cond) * FF) + tc.bcol + tc.wc * 64 + tc.fq * 4;
;                 f32x4 shv[4];
; #pragma unroll
;                 for (int n = 0; n < 4; ++n) shv[n] = *(const f32x4*)(shw + n * 16);
; #pragma unroll
;                 for (int m = 0; m < 8; ++m) {
;                     const f32x4 pp = *(const f32x4*)(ssp + m * 256);
;                     float sq = pp[0] + pp[1] + pp[2] + pp[3];
;                     sq += __shfl_xor(sq, 16);
;                     sq += __shfl_xor(sq, 32);
;                     const float rstd = rsqrtf(sq * (1.f / DM) + EPS);
; #pragma unroll
;                     for (int n = 0; n < 4; ++n) acc[m][n] = acc[m][n] * rstd + shv[n];
	s_setprio 1
	v_mfma_f32_16x16x32_bf16 v[76:79], v[176:179], v[64:67], v[128:131]
	v_mfma_f32_16x16x32_bf16 v[72:75], v[180:183], v[64:67], v[124:127]
	v_mfma_f32_16x16x32_bf16 v[68:71], v[184:187], v[64:67], v[120:123]
	v_mfma_f32_16x16x32_bf16 v[64:67], v[188:191], v[64:67], v[116:119]
	v_mfma_f32_16x16x32_bf16 v[60:63], v[176:179], v[172:175], v[112:115]
	v_mfma_f32_16x16x32_bf16 v[56:59], v[180:183], v[172:175], v[194:197]
	v_mfma_f32_16x16x32_bf16 v[52:55], v[184:187], v[172:175], v[214:217]
	v_mfma_f32_16x16x32_bf16 v[48:51], v[188:191], v[172:175], v[132:135]
	v_mfma_f32_16x16x32_bf16 v[28:31], v[176:179], v[232:235], v[220:223]
	v_mfma_f32_16x16x32_bf16 v[24:27], v[180:183], v[232:235], v[224:227]
	v_mfma_f32_16x16x32_bf16 v[20:23], v[184:187], v[232:235], v[228:231]
	v_mfma_f32_16x16x32_bf16 v[16:19], v[188:191], v[232:235], v[136:139]
	v_mfma_f32_16x16x32_bf16 v[12:15], v[176:179], v[236:239], v[160:163]
	v_mfma_f32_16x16x32_bf16 v[8:11], v[180:183], v[236:239], v[164:167]
	v_mfma_f32_16x16x32_bf16 v[4:7], v[184:187], v[236:239], v[168:171]
	v_mfma_f32_16x16x32_bf16 v[0:3], v[188:191], v[236:239], v[140:143]
	s_setprio 0
	v_mov_b32_e32 v172, v252
	s_lshl_b32 s41, s31, 8
	s_min_i32 s4, s41, 0x4000
	s_lshl_b32 s6, s98, 8
	s_ashr_i32 s4, s4, 12
	s_ashr_i32 s5, s41, 31
	s_add_u32 s7, s45, s41
	v_ashrrev_i32_e32 v174, 1, v172
	v_and_b32_e32 v169, 15, v172
	s_addc_u32 s5, s48, s5
	v_and_b32_e32 v112, 0xffffff80, v174
	v_ashrrev_i32_e32 v113, 31, v112
	v_or_b32_e32 v32, s7, v169
	v_mov_b32_e32 v33, s5
	s_ashr_i32 s5, s4, 31
	v_lshl_add_u64 v[32:33], v[32:33], 0, v[112:113]
	s_add_u32 s4, s44, s4
	v_lshlrev_b64 v[114:115], 6, v[32:33]
	s_addc_u32 s5, s49, s5
	v_mov_b64_e32 v[32:33], s[76:77]
	v_mov_b32_e32 v34, 0x1c00
	s_mul_i32 s7, s5, 0x1c00
	v_mad_u64_u32 v[32:33], s[4:5], s4, v34, v[32:33]
	v_ashrrev_i32_e32 v166, 6, v172
	v_add_u32_e32 v33, s7, v33
	s_ashr_i32 s7, s6, 31
	v_and_b32_e32 v171, 3, v166
	s_lshl_b64 s[4:5], s[6:7], 2
	v_xor_b32_e32 v230, 16, v202
	v_lshl_add_u64 v[32:33], v[32:33], 0, s[4:5]
	v_lshlrev_b32_e32 v192, 8, v171
	v_cmp_lt_i32_e32 vcc, v230, v203
	v_lshl_add_u64 v[32:33], v[32:33], 0, v[192:193]
	v_and_b32_e32 v192, 48, v172
	v_lshl_add_u64 v[114:115], s[74:75], 0, v[114:115]
	v_cndmask_b32_e32 v113, v202, v230, vcc
	v_cmp_lt_i32_e32 vcc, v209, v203
	v_lshl_add_u64 v[32:33], v[32:33], 0, v[192:193]
	v_lshl_add_u64 v[164:165], v[114:115], 0, v[192:193]
	v_cndmask_b32_e32 v114, v202, v209, vcc
	global_load_dwordx4 v[44:47], v[32:33], off
	global_load_dwordx4 v[40:43], v[32:33], off offset:64
	global_load_dwordx4 v[36:39], v[32:33], off offset:128
	s_nop 0
	global_load_dwordx4 v[32:35], v[32:33], off offset:192
	v_lshlrev_b32_e32 v168, 2, v114
	global_load_dwordx4 v[114:117], v[164:165], off
	global_load_dwordx4 v[118:121], v[164:165], off offset:1024
	global_load_dwordx4 v[178:181], v[164:165], off offset:2048
	global_load_dwordx4 v[130:133], v[164:165], off offset:3072
	v_mov_b32_e32 v190, s29
	v_mov_b32_e32 v191, 0
	v_lshl_add_u64 v[190:191], v[164:165], 0, v[190:191]
	global_load_dwordx4 v[182:185], v[190:191], off
	global_load_dwordx4 v[186:189], v[190:191], off offset:1024
	global_load_dwordx4 v[232:235], v[190:191], off offset:2048
	global_load_dwordx4 v[236:239], v[190:191], off offset:3072
	v_lshlrev_b32_e32 v113, 2, v113
	s_mov_b32 s4, 0x358637bd
	v_mov_b64_e32 v[162:163], s[4:5]
	s_mov_b32 s8, 0x3a800000
	v_bfe_u32 v173, v172, 4, 2
	v_and_b32_e32 v170, 63, v172
	v_lshlrev_b32_e32 v175, 2, v173
	s_cmp_gt_i32 s98, 1
	s_waitcnt vmcnt(7)
	v_mov_b32_e32 v123, v114
	s_waitcnt vmcnt(6)
	v_mov_b32_e32 v122, v118
	v_mov_b32_e32 v114, v119
	v_pk_add_f32 v[114:115], v[122:123], v[114:115]
	v_mov_b32_e32 v118, v120
	v_mov_b32_e32 v119, v116
	v_pk_add_f32 v[114:115], v[118:119], v[114:115]
	v_mov_b32_e32 v116, v121
	v_pk_add_f32 v[114:115], v[116:117], v[114:115]
	ds_bpermute_b32 v117, v113, v115
	ds_bpermute_b32 v116, v113, v114
	s_waitcnt lgkmcnt(0)
	v_pk_add_f32 v[114:115], v[114:115], v[116:117]
	ds_bpermute_b32 v117, v168, v115
	ds_bpermute_b32 v116, v168, v114
	s_waitcnt lgkmcnt(0)
	v_pk_add_f32 v[114:115], v[114:115], v[116:117]
	s_nop 0
	v_pk_fma_f32 v[114:115], v[114:115], s[8:9], v[162:163] op_sel_hi:[1,0,0]
	s_nop 0
	v_mul_f32_e32 v116, 0x4b800000, v115
	v_cmp_gt_f32_e64 s[4:5], s92, v115
	v_cmp_gt_f32_e32 vcc, s92, v114
	s_nop 0
	v_cndmask_b32_e64 v115, v115, v116, s[4:5]
	v_rsq_f32_e32 v115, v115
	s_nop 0
	v_mul_f32_e32 v116, 0x45800000, v115
	v_cndmask_b32_e64 v116, v115, v116, s[4:5]
	v_mul_f32_e32 v115, 0x4b800000, v114
	v_cndmask_b32_e32 v114, v114, v115, vcc
	v_rsq_f32_e32 v114, v114
	v_pk_fma_f32 v[158:159], v[242:243], v[116:117], v[46:47] op_sel_hi:[1,0,1]
	v_pk_fma_f32 v[160:161], v[240:241], v[116:117], v[44:45] op_sel_hi:[1,0,1]
	v_pk_fma_f32 v[154:155], v[246:247], v[116:117], v[42:43] op_sel_hi:[1,0,1]
	v_mul_f32_e32 v115, 0x45800000, v114
	v_cndmask_b32_e32 v114, v114, v115, vcc
	v_pk_fma_f32 v[156:157], v[244:245], v[116:117], v[40:41] op_sel_hi:[1,0,1]
	v_pk_fma_f32 v[216:217], v[250:251], v[116:117], v[38:39] op_sel_hi:[1,0,1]
	v_pk_fma_f32 v[152:153], v[248:249], v[116:117], v[36:37] op_sel_hi:[1,0,1]
	v_pk_fma_f32 v[146:147], v[146:147], v[116:117], v[34:35] op_sel_hi:[1,0,1]
	v_pk_fma_f32 v[214:215], v[144:145], v[116:117], v[32:33] op_sel_hi:[1,0,1]
	v_pk_fma_f32 v[140:141], v[212:213], v[114:115], v[46:47] op_sel_hi:[1,0,1]
	v_pk_fma_f32 v[144:145], v[210:211], v[114:115], v[44:45] op_sel_hi:[1,0,1]
	v_pk_fma_f32 v[138:139], v[206:207], v[114:115], v[42:43] op_sel_hi:[1,0,1]
	v_pk_fma_f32 v[142:143], v[204:205], v[114:115], v[40:41] op_sel_hi:[1,0,1]
	v_pk_fma_f32 v[126:127], v[200:201], v[114:115], v[38:39] op_sel_hi:[1,0,1]
	v_pk_fma_f32 v[128:129], v[198:199], v[114:115], v[36:37] op_sel_hi:[1,0,1]
	v_pk_fma_f32 v[120:121], v[150:151], v[114:115], v[34:35] op_sel_hi:[1,0,1]
	v_pk_fma_f32 v[124:125], v[148:149], v[114:115], v[32:33] op_sel_hi:[1,0,1]
	s_waitcnt vmcnt(4)
; template <int EK>
; DI void gemm_stream(const Params& p, int l, const bf16_t* __restrict__ A, const bf16_t* __restrict__ Bt, int M, int N, int K, ldsp_t shm) {
;     ...
; #pragma unroll
;                 for (int m = 0; m < 8; ++m) {
;                     const f32x4 pp = *(const f32x4*)(ssp + m * 256);
;                     float sq = pp[0] + pp[1] + pp[2] + pp[3];
;                     sq += __shfl_xor(sq, 16);
;                     sq += __shfl_xor(sq, 32);
;                     const float rstd = rsqrtf(sq * (1.f / DM) + EPS);
; #pragma unroll
;                     for (int n = 0; n < 4; ++n) acc[m][n] = acc[m][n] * rstd + shv[n];
	v_mov_b64_e32 v[114:115], v[178:179]
	v_mov_b64_e32 v[116:117], v[180:181]
	v_mov_b32_e32 v119, v114
	v_mov_b32_e32 v118, v130
	v_mov_b32_e32 v114, v131
	v_pk_add_f32 v[114:115], v[118:119], v[114:115]
	v_mov_b32_e32 v118, v132
	v_mov_b32_e32 v119, v116
	v_pk_add_f32 v[114:115], v[118:119], v[114:115]
	v_mov_b32_e32 v116, v133
	v_pk_add_f32 v[114:115], v[116:117], v[114:115]
	ds_bpermute_b32 v117, v113, v115
	ds_bpermute_b32 v116, v113, v114
	s_waitcnt lgkmcnt(0)
	v_pk_add_f32 v[114:115], v[114:115], v[116:117]
	ds_bpermute_b32 v117, v168, v115
	ds_bpermute_b32 v116, v168, v114
	s_waitcnt lgkmcnt(0)
	v_pk_add_f32 v[114:115], v[114:115], v[116:117]
	s_nop 0
	v_pk_fma_f32 v[148:149], v[114:115], s[8:9], v[162:163] op_sel_hi:[1,0,0]
	s_nop 0
	v_mul_f32_e32 v114, 0x4b800000, v149
	v_cmp_gt_f32_e64 s[4:5], s92, v149
	v_cmp_gt_f32_e32 vcc, s92, v148
	s_nop 0
	v_cndmask_b32_e64 v114, v149, v114, s[4:5]
	v_rsq_f32_e32 v114, v114
	s_nop 0
	v_mul_f32_e32 v115, 0x45800000, v114
	v_cndmask_b32_e64 v116, v114, v115, s[4:5]
	v_pk_fma_f32 v[132:133], v[110:111], v[116:117], v[46:47] op_sel_hi:[1,0,1]
	v_pk_fma_f32 v[136:137], v[108:109], v[116:117], v[44:45] op_sel_hi:[1,0,1]
	v_pk_fma_f32 v[130:131], v[106:107], v[116:117], v[42:43] op_sel_hi:[1,0,1]
	v_pk_fma_f32 v[134:135], v[104:105], v[116:117], v[40:41] op_sel_hi:[1,0,1]
	v_pk_fma_f32 v[118:119], v[102:103], v[116:117], v[38:39] op_sel_hi:[1,0,1]
	v_pk_fma_f32 v[122:123], v[100:101], v[116:117], v[36:37] op_sel_hi:[1,0,1]
	v_pk_fma_f32 v[114:115], v[98:99], v[116:117], v[34:35] op_sel_hi:[1,0,1]
	v_pk_fma_f32 v[116:117], v[96:97], v[116:117], v[32:33] op_sel_hi:[1,0,1]
	v_mul_f32_e32 v96, 0x4b800000, v148
	v_cndmask_b32_e32 v96, v148, v96, vcc
	v_rsq_f32_e32 v96, v96
	s_nop 0
	v_mul_f32_e32 v97, 0x45800000, v96
	v_cndmask_b32_e32 v104, v96, v97, vcc
	v_pk_fma_f32 v[98:99], v[94:95], v[104:105], v[46:47] op_sel_hi:[1,0,1]
	v_pk_fma_f32 v[102:103], v[92:93], v[104:105], v[44:45] op_sel_hi:[1,0,1]
	v_pk_fma_f32 v[96:97], v[90:91], v[104:105], v[42:43] op_sel_hi:[1,0,1]
	v_pk_fma_f32 v[100:101], v[88:89], v[104:105], v[40:41] op_sel_hi:[1,0,1]
	v_pk_fma_f32 v[92:93], v[86:87], v[104:105], v[38:39] op_sel_hi:[1,0,1]
	v_pk_fma_f32 v[94:95], v[84:85], v[104:105], v[36:37] op_sel_hi:[1,0,1]
	v_pk_fma_f32 v[88:89], v[82:83], v[104:105], v[34:35] op_sel_hi:[1,0,1]
	v_pk_fma_f32 v[90:91], v[80:81], v[104:105], v[32:33] op_sel_hi:[1,0,1]
	v_add_co_u32_e32 v104, vcc, s29, v164
	s_nop 1
	v_addc_co_u32_e32 v105, vcc, 0, v165, vcc
	s_waitcnt vmcnt(2)
	v_mov_b64_e32 v[80:81], v[182:183]
	v_mov_b64_e32 v[82:83], v[184:185]
	v_mov_b64_e32 v[84:85], v[186:187]
	v_mov_b64_e32 v[86:87], v[188:189]
	v_mov_b32_e32 v107, v80
	v_mov_b32_e32 v106, v84
	v_mov_b32_e32 v80, v85
	v_pk_add_f32 v[80:81], v[106:107], v[80:81]
	v_mov_b32_e32 v84, v86
	v_mov_b32_e32 v85, v82
	v_pk_add_f32 v[80:81], v[84:85], v[80:81]
	v_mov_b32_e32 v82, v87
	v_pk_add_f32 v[80:81], v[82:83], v[80:81]
	ds_bpermute_b32 v83, v113, v81
	ds_bpermute_b32 v82, v113, v80
	s_waitcnt lgkmcnt(0)
	v_pk_add_f32 v[80:81], v[80:81], v[82:83]
	ds_bpermute_b32 v83, v168, v81
	ds_bpermute_b32 v82, v168, v80
	s_waitcnt lgkmcnt(0)
	v_pk_add_f32 v[80:81], v[80:81], v[82:83]
	s_nop 0
	v_pk_fma_f32 v[106:107], v[80:81], s[8:9], v[162:163] op_sel_hi:[1,0,0]
	s_nop 0
	v_mul_f32_e32 v80, 0x4b800000, v107
	v_cmp_gt_f32_e64 s[4:5], s92, v107
	v_cmp_gt_f32_e32 vcc, s92, v106
	s_nop 0
	v_cndmask_b32_e64 v80, v107, v80, s[4:5]
	v_rsq_f32_e32 v80, v80
	s_nop 0
	v_mul_f32_e32 v81, 0x45800000, v80
	v_cndmask_b32_e64 v108, v80, v81, s[4:5]
	v_pk_fma_f32 v[80:81], v[74:75], v[108:109], v[42:43] op_sel_hi:[1,0,1]
	v_pk_fma_f32 v[74:75], v[64:65], v[108:109], v[32:33] op_sel_hi:[1,0,1]
	v_mul_f32_e32 v64, 0x4b800000, v106
	v_cndmask_b32_e32 v64, v106, v64, vcc
	v_rsq_f32_e32 v64, v64
	v_pk_fma_f32 v[82:83], v[78:79], v[108:109], v[46:47] op_sel_hi:[1,0,1]
	v_pk_fma_f32 v[86:87], v[76:77], v[108:109], v[44:45] op_sel_hi:[1,0,1]
	v_pk_fma_f32 v[84:85], v[72:73], v[108:109], v[40:41] op_sel_hi:[1,0,1]
	v_mul_f32_e32 v65, 0x45800000, v64
	v_cndmask_b32_e32 v106, v64, v65, vcc
	v_pk_fma_f32 v[76:77], v[70:71], v[108:109], v[38:39] op_sel_hi:[1,0,1]
	v_pk_fma_f32 v[78:79], v[68:69], v[108:109], v[36:37] op_sel_hi:[1,0,1]
	v_pk_fma_f32 v[72:73], v[66:67], v[108:109], v[34:35] op_sel_hi:[1,0,1]
	v_pk_fma_f32 v[68:69], v[62:63], v[106:107], v[46:47] op_sel_hi:[1,0,1]
	v_pk_fma_f32 v[70:71], v[60:61], v[106:107], v[44:45] op_sel_hi:[1,0,1]
	v_pk_fma_f32 v[64:65], v[58:59], v[106:107], v[42:43] op_sel_hi:[1,0,1]
	v_pk_fma_f32 v[66:67], v[56:57], v[106:107], v[40:41] op_sel_hi:[1,0,1]
	v_pk_fma_f32 v[60:61], v[54:55], v[106:107], v[38:39] op_sel_hi:[1,0,1]
	v_pk_fma_f32 v[62:63], v[52:53], v[106:107], v[36:37] op_sel_hi:[1,0,1]
	v_pk_fma_f32 v[56:57], v[50:51], v[106:107], v[34:35] op_sel_hi:[1,0,1]
	v_pk_fma_f32 v[58:59], v[48:49], v[106:107], v[32:33] op_sel_hi:[1,0,1]
	s_waitcnt vmcnt(0)
	v_mov_b64_e32 v[48:49], v[232:233]
	v_mov_b64_e32 v[50:51], v[234:235]
	v_mov_b64_e32 v[52:53], v[236:237]
	v_mov_b64_e32 v[54:55], v[238:239]
	v_mov_b32_e32 v105, v48
	v_mov_b32_e32 v104, v52
	v_mov_b32_e32 v48, v53
	v_pk_add_f32 v[48:49], v[104:105], v[48:49]
	v_mov_b32_e32 v52, v54
	v_mov_b32_e32 v53, v50
	v_pk_add_f32 v[48:49], v[52:53], v[48:49]
	v_mov_b32_e32 v50, v55
	v_pk_add_f32 v[48:49], v[50:51], v[48:49]
	ds_bpermute_b32 v51, v113, v49
	ds_bpermute_b32 v50, v113, v48
	s_waitcnt lgkmcnt(0)
	v_pk_add_f32 v[48:49], v[48:49], v[50:51]
	ds_bpermute_b32 v51, v168, v49
	ds_bpermute_b32 v50, v168, v48
	s_waitcnt lgkmcnt(0)
; DI unsigned pk2(float a, float b) { f32x2 v = {a, b}; bf2_t r = __builtin_convertvector(v, bf2_t); return __builtin_bit_cast(unsigned, r); }
;     static DI void run(const f32x4 (&acc)[8][4], const TileCtx& tc, const Params& p, ldsp_t wb) {
;     ...
;         } else if (BRK == 2) {
; #pragma unroll
;             for (int h = 0; h < 2; ++h) {
; #pragma unroll
;                 for (int mm = 0; mm < 4; ++mm) {
;                     const int m = h * 4 + mm;
; #pragma unroll
;                     for (int n = 0; n < 4; ++n) {
;                         u32x2 w; w[0] = pk2(gelu_tanh(acc[m][n][0]), gelu_tanh(acc[m][n][1])); w[1] = pk2(gelu_tanh(acc[m][n][2]), gelu_tanh(acc[m][n][3]));
;                         wave_put(wb, mm * 16 + fr, n, fq, w);
;                     }
;                 }
;                 wave_rows_store(wb, tc.lane, p.U + (size_t)(tc.brow + tc.wr * 128 + h * 64) * 1024 + (pn - 3) * 256 + wc * 64, 1024);
; template <int EK>
; DI void gemm_stream(const Params& p, int l, const bf16_t* __restrict__ A, const bf16_t* __restrict__ Bt, int M, int N, int K, ldsp_t shm) {
;     ...
; #pragma unroll
;                 for (int m = 0; m < 8; ++m) {
;                     const f32x4 pp = *(const f32x4*)(ssp + m * 256);
;                     float sq = pp[0] + pp[1] + pp[2] + pp[3];
;                     sq += __shfl_xor(sq, 16);
;                     sq += __shfl_xor(sq, 32);
;                     const float rstd = rsqrtf(sq * (1.f / DM) + EPS);
; #pragma unroll
;                     for (int n = 0; n < 4; ++n) acc[m][n] = acc[m][n] * rstd + shv[n];
;                 }
;             }
;             if (EK == 0) {
;                 if (pne < 2) EpiIn<0>::run(acc, tc, p, ex);
;                 else if (pne == 2) EpiIn<1>::run(acc, tc, p, ex);
;                 else EpiIn<2>::run(acc, tc, p, ex);
	v_pk_add_f32 v[48:49], v[48:49], v[50:51]
	s_nop 0
	v_pk_fma_f32 v[148:149], v[48:49], s[8:9], v[162:163] op_sel_hi:[1,0,0]
	s_nop 0
	v_mul_f32_e32 v48, 0x4b800000, v149
	v_cmp_gt_f32_e64 s[4:5], s92, v149
	v_cmp_gt_f32_e32 vcc, s92, v148
	s_nop 0
	v_cndmask_b32_e64 v48, v149, v48, s[4:5]
	v_rsq_f32_e32 v48, v48
	s_nop 0
	v_mul_f32_e32 v49, 0x45800000, v48
	v_cndmask_b32_e64 v50, v48, v49, s[4:5]
	v_pk_fma_f32 v[108:109], v[30:31], v[50:51], v[46:47] op_sel_hi:[1,0,1]
	v_pk_fma_f32 v[110:111], v[28:29], v[50:51], v[44:45] op_sel_hi:[1,0,1]
	v_pk_fma_f32 v[104:105], v[26:27], v[50:51], v[42:43] op_sel_hi:[1,0,1]
	v_pk_fma_f32 v[106:107], v[24:25], v[50:51], v[40:41] op_sel_hi:[1,0,1]
	v_pk_fma_f32 v[52:53], v[22:23], v[50:51], v[38:39] op_sel_hi:[1,0,1]
	v_pk_fma_f32 v[54:55], v[20:21], v[50:51], v[36:37] op_sel_hi:[1,0,1]
	v_pk_fma_f32 v[48:49], v[18:19], v[50:51], v[34:35] op_sel_hi:[1,0,1]
	v_pk_fma_f32 v[50:51], v[16:17], v[50:51], v[32:33] op_sel_hi:[1,0,1]
	v_mul_f32_e32 v16, 0x4b800000, v148
	v_cndmask_b32_e32 v16, v148, v16, vcc
	v_rsq_f32_e32 v16, v16
	s_mov_b64 s[4:5], -1
	v_mul_f32_e32 v17, 0x45800000, v16
	v_cndmask_b32_e32 v16, v16, v17, vcc
	v_pk_fma_f32 v[22:23], v[0:1], v[16:17], v[32:33] op_sel_hi:[1,0,1]
	v_mov_b32_e32 v0, 0x10000
	v_pk_fma_f32 v[46:47], v[14:15], v[16:17], v[46:47] op_sel_hi:[1,0,1]
	v_pk_fma_f32 v[44:45], v[12:13], v[16:17], v[44:45] op_sel_hi:[1,0,1]
	v_pk_fma_f32 v[28:29], v[10:11], v[16:17], v[42:43] op_sel_hi:[1,0,1]
	v_pk_fma_f32 v[30:31], v[8:9], v[16:17], v[40:41] op_sel_hi:[1,0,1]
	v_pk_fma_f32 v[24:25], v[6:7], v[16:17], v[38:39] op_sel_hi:[1,0,1]
	v_pk_fma_f32 v[26:27], v[4:5], v[16:17], v[36:37] op_sel_hi:[1,0,1]
	v_pk_fma_f32 v[20:21], v[2:3], v[16:17], v[34:35] op_sel_hi:[1,0,1]
	v_lshl_add_u32 v176, v166, 13, v0
	s_cbranch_scc0 .LBB0_327
	s_cmp_lg_u32 s98, 2
	s_cbranch_scc0 .LBB0_272
	v_lshlrev_b32_e32 v3, 3, v173
	v_lshlrev_b32_e32 v2, 7, v169
	v_and_b32_e32 v3, 8, v3
	v_add3_u32 v7, v176, v2, v3
	v_mul_f32_e32 v2, 0x3d372713, v160
	v_mul_f32_e32 v3, 0x3d372713, v161
	v_mul_f32_e32 v2, v160, v2
	v_mul_f32_e32 v3, v161, v3
	v_fma_f32 v2, v160, v2, v160
	v_fma_f32 v3, v161, v3, v161
	v_mul_f32_e32 v2, 0x3f4c422a, v2
	v_mul_f32_e32 v3, 0x3f4c422a, v3
	v_mul_f32_e32 v2, 0xc038aa3b, v2
	v_mul_f32_e32 v3, 0xc038aa3b, v3
	v_exp_f32_e32 v2, v2
	v_exp_f32_e32 v3, v3
	v_lshrrev_b32_e32 v1, 5, v170
	v_and_b32_e32 v6, 7, v172
	v_add_f32_e32 v2, 1.0, v2
	v_add_f32_e32 v3, 1.0, v3
	v_rcp_f32_e32 v2, v2
	v_rcp_f32_e32 v3, v3
	v_add_u32_e32 v10, s41, v112
	s_add_i32 s4, s6, 0xfffffd00
	v_ashrrev_i32_e32 v11, 31, v10
	v_pk_mul_f32 v[2:3], v[160:161], v[2:3]
	s_ashr_i32 s5, s4, 31
	v_cvt_pk_bf16_f32 v2, v2, v3
	v_mul_f32_e32 v3, 0x3d372713, v158
	v_mul_f32_e32 v3, v158, v3
	v_fma_f32 v3, v158, v3, v158
	v_mul_f32_e32 v3, 0x3f4c422a, v3
	v_mul_f32_e32 v3, 0xc038aa3b, v3
	v_exp_f32_e32 v3, v3
	v_lshlrev_b32_e32 v0, 6, v171
	s_lshl_b64 s[4:5], s[4:5], 1
	v_lshlrev_b32_e32 v192, 1, v0
	v_add_f32_e32 v3, 1.0, v3
	v_rcp_f32_e32 v4, v3
	v_mul_f32_e32 v3, 0x3d372713, v159
	v_mul_f32_e32 v3, v159, v3
	v_fma_f32 v3, v159, v3, v159
	v_mul_f32_e32 v3, 0x3f4c422a, v3
	v_mul_f32_e32 v3, 0xc038aa3b, v3
	v_exp_f32_e32 v3, v3
	v_mov_b32_e32 v19, v193
	v_mov_b32_e32 v17, v193
	v_mov_b32_e32 v15, v193
	v_add_f32_e32 v3, 1.0, v3
	v_rcp_f32_e32 v5, v3
	v_mov_b32_e32 v13, v193
	v_mov_b32_e32 v9, v193
	v_pk_mul_f32 v[4:5], v[158:159], v[4:5]
	s_nop 0
	v_cvt_pk_bf16_f32 v3, v4, v5
	v_bitop3_b32 v4, v1, v172, 7 bitop3:0x78
	v_lshl_add_u32 v32, v4, 4, v7
	ds_write_b64 v32, v[2:3]
	v_mul_f32_e32 v2, 0x3d372713, v156
	v_mul_f32_e32 v3, 0x3d372713, v157
	v_mul_f32_e32 v2, v156, v2
	v_mul_f32_e32 v3, v157, v3
	v_fma_f32 v2, v156, v2, v156
	v_fma_f32 v3, v157, v3, v157
	v_mul_f32_e32 v2, 0x3f4c422a, v2
	v_mul_f32_e32 v3, 0x3f4c422a, v3
	v_mul_f32_e32 v2, 0xc038aa3b, v2
	v_mul_f32_e32 v3, 0xc038aa3b, v3
	v_exp_f32_e32 v2, v2
	v_exp_f32_e32 v3, v3
	v_add_f32_e32 v2, 1.0, v2
	v_add_f32_e32 v3, 1.0, v3
	v_rcp_f32_e32 v2, v2
	v_rcp_f32_e32 v3, v3
	s_nop 0
	v_pk_mul_f32 v[2:3], v[156:157], v[2:3]
	s_nop 0
	v_cvt_pk_bf16_f32 v2, v2, v3
	v_mul_f32_e32 v3, 0x3d372713, v154
	v_mul_f32_e32 v3, v154, v3
	v_fma_f32 v3, v154, v3, v154
	v_mul_f32_e32 v3, 0x3f4c422a, v3
	v_mul_f32_e32 v3, 0xc038aa3b, v3
	v_exp_f32_e32 v3, v3
	s_nop 0
	v_add_f32_e32 v3, 1.0, v3
	v_rcp_f32_e32 v4, v3
	v_mul_f32_e32 v3, 0x3d372713, v155
	v_mul_f32_e32 v3, v155, v3
	v_fma_f32 v3, v155, v3, v155
	v_mul_f32_e32 v3, 0x3f4c422a, v3
	v_mul_f32_e32 v3, 0xc038aa3b, v3
	v_exp_f32_e32 v3, v3
	s_nop 0
	v_add_f32_e32 v3, 1.0, v3
	v_rcp_f32_e32 v5, v3
	s_nop 0
	v_pk_mul_f32 v[4:5], v[154:155], v[4:5]
	s_nop 0
	v_cvt_pk_bf16_f32 v3, v4, v5
	v_bitop3_b32 v4, v1, v6, 2 bitop3:0x36
	v_lshl_add_u32 v33, v4, 4, v7
	ds_write_b64 v33, v[2:3]
	v_mul_f32_e32 v2, 0x3d372713, v152
	v_mul_f32_e32 v3, 0x3d372713, v153
	v_mul_f32_e32 v2, v152, v2
	v_mul_f32_e32 v3, v153, v3
	v_fma_f32 v2, v152, v2, v152
	v_fma_f32 v3, v153, v3, v153
	v_mul_f32_e32 v2, 0x3f4c422a, v2
	v_mul_f32_e32 v3, 0x3f4c422a, v3
	v_mul_f32_e32 v2, 0xc038aa3b, v2
	v_mul_f32_e32 v3, 0xc038aa3b, v3
	v_exp_f32_e32 v2, v2
	v_exp_f32_e32 v3, v3
	v_add_f32_e32 v2, 1.0, v2
	v_add_f32_e32 v3, 1.0, v3
	v_rcp_f32_e32 v2, v2
	v_rcp_f32_e32 v3, v3
	s_nop 0
	v_pk_mul_f32 v[2:3], v[152:153], v[2:3]
	s_nop 0
	v_cvt_pk_bf16_f32 v2, v2, v3
	v_mul_f32_e32 v3, 0x3d372713, v216
	v_mul_f32_e32 v3, v216, v3
	v_fma_f32 v3, v216, v3, v216
	v_mul_f32_e32 v3, 0x3f4c422a, v3
	v_mul_f32_e32 v3, 0xc038aa3b, v3
	v_exp_f32_e32 v3, v3
	s_nop 0
	v_add_f32_e32 v3, 1.0, v3
	v_rcp_f32_e32 v4, v3
	v_mul_f32_e32 v3, 0x3d372713, v217
	v_mul_f32_e32 v3, v217, v3
; DI unsigned pk2(float a, float b) { f32x2 v = {a, b}; bf2_t r = __builtin_convertvector(v, bf2_t); return __builtin_bit_cast(unsigned, r); }
; DI float fexp2(float x) { return __builtin_amdgcn_exp2f(x); }
; DI float gelu_tanh(float x) {
;     const float y = 0.7978845608028654f * (x + 0.044715f * x * x * x);
;     return x * __builtin_amdgcn_rcpf(1.f + fexp2(-2.f * LOG2E * y));
; }
;     static DI void run(const f32x4 (&acc)[8][4], const TileCtx& tc, const Params& p, ldsp_t wb) {
;     ...
;         } else if (BRK == 2) {
; #pragma unroll
;             for (int h = 0; h < 2; ++h) {
; #pragma unroll
;                 for (int mm = 0; mm < 4; ++mm) {
;                     const int m = h * 4 + mm;
; #pragma unroll
;                     for (int n = 0; n < 4; ++n) {
;                         u32x2 w; w[0] = pk2(gelu_tanh(acc[m][n][0]), gelu_tanh(acc[m][n][1])); w[1] = pk2(gelu_tanh(acc[m][n][2]), gelu_tanh(acc[m][n][3]));
;                         wave_put(wb, mm * 16 + fr, n, fq, w);
;                     }
;                 }
;                 wave_rows_store(wb, tc.lane, p.U + (size_t)(tc.brow + tc.wr * 128 + h * 64) * 1024 + (pn - 3) * 256 + wc * 64, 1024);
	v_fma_f32 v3, v217, v3, v217
	v_mul_f32_e32 v3, 0x3f4c422a, v3
	v_mul_f32_e32 v3, 0xc038aa3b, v3
	v_exp_f32_e32 v3, v3
	s_nop 0
	v_add_f32_e32 v3, 1.0, v3
	v_rcp_f32_e32 v5, v3
	s_nop 0
	v_pk_mul_f32 v[4:5], v[216:217], v[4:5]
	s_nop 0
	v_cvt_pk_bf16_f32 v3, v4, v5
	v_bitop3_b32 v4, v1, v6, 4 bitop3:0x36
	v_lshl_add_u32 v34, v4, 4, v7
	ds_write_b64 v34, v[2:3]
	v_mul_f32_e32 v2, 0x3d372713, v214
	v_mul_f32_e32 v3, 0x3d372713, v215
	v_mul_f32_e32 v2, v214, v2
	v_mul_f32_e32 v3, v215, v3
	v_fma_f32 v2, v214, v2, v214
	v_fma_f32 v3, v215, v3, v215
	v_mul_f32_e32 v2, 0x3f4c422a, v2
	v_mul_f32_e32 v3, 0x3f4c422a, v3
	v_mul_f32_e32 v2, 0xc038aa3b, v2
	v_mul_f32_e32 v3, 0xc038aa3b, v3
	v_exp_f32_e32 v2, v2
	v_exp_f32_e32 v3, v3
	v_bitop3_b32 v1, v1, v6, 6 bitop3:0x36
	v_lshl_add_u32 v35, v1, 4, v7
	v_add_f32_e32 v2, 1.0, v2
	v_add_f32_e32 v3, 1.0, v3
	v_rcp_f32_e32 v2, v2
	v_rcp_f32_e32 v3, v3
	v_mul_f32_e32 v1, 0x3d372713, v144
	v_mul_f32_e32 v1, v144, v1
	v_fma_f32 v1, v144, v1, v144
	v_pk_mul_f32 v[2:3], v[214:215], v[2:3]
	v_mul_f32_e32 v1, 0x3f4c422a, v1
	v_cvt_pk_bf16_f32 v2, v2, v3
	v_mul_f32_e32 v3, 0x3d372713, v146
	v_mul_f32_e32 v3, v146, v3
	v_fma_f32 v3, v146, v3, v146
	v_mul_f32_e32 v3, 0x3f4c422a, v3
	v_mul_f32_e32 v3, 0xc038aa3b, v3
	v_exp_f32_e32 v3, v3
	v_mul_f32_e32 v1, 0xc038aa3b, v1
	v_exp_f32_e32 v1, v1
	v_add_f32_e32 v3, 1.0, v3
	v_rcp_f32_e32 v4, v3
	v_mul_f32_e32 v3, 0x3d372713, v147
	v_mul_f32_e32 v3, v147, v3
	v_fma_f32 v3, v147, v3, v147
	v_mul_f32_e32 v3, 0x3f4c422a, v3
	v_mul_f32_e32 v3, 0xc038aa3b, v3
	v_exp_f32_e32 v3, v3
	v_add_f32_e32 v1, 1.0, v1
	v_add_f32_e32 v3, 1.0, v3
	v_rcp_f32_e32 v5, v3
	s_nop 0
	v_pk_mul_f32 v[4:5], v[146:147], v[4:5]
	s_nop 0
	v_cvt_pk_bf16_f32 v3, v4, v5
	ds_write_b64 v35, v[2:3]
	v_rcp_f32_e32 v2, v1
	v_mul_f32_e32 v1, 0x3d372713, v145
	v_mul_f32_e32 v1, v145, v1
	v_fma_f32 v1, v145, v1, v145
	v_mul_f32_e32 v1, 0x3f4c422a, v1
	v_mul_f32_e32 v1, 0xc038aa3b, v1
	v_exp_f32_e32 v1, v1
	s_nop 0
	v_add_f32_e32 v1, 1.0, v1
	v_rcp_f32_e32 v3, v1
	v_mul_f32_e32 v1, 0x3d372713, v140
	v_mul_f32_e32 v1, v140, v1
	v_fma_f32 v1, v140, v1, v140
	v_mul_f32_e32 v1, 0x3f4c422a, v1
	v_mul_f32_e32 v1, 0xc038aa3b, v1
	v_exp_f32_e32 v1, v1
	v_pk_mul_f32 v[2:3], v[144:145], v[2:3]
	v_add_f32_e32 v1, 1.0, v1
	v_rcp_f32_e32 v4, v1
	v_mul_f32_e32 v1, 0x3d372713, v141
	v_mul_f32_e32 v1, v141, v1
	v_fma_f32 v1, v141, v1, v141
	v_mul_f32_e32 v1, 0x3f4c422a, v1
	v_mul_f32_e32 v1, 0xc038aa3b, v1
	v_exp_f32_e32 v1, v1
	v_cvt_pk_bf16_f32 v2, v2, v3
	v_add_f32_e32 v1, 1.0, v1
	v_rcp_f32_e32 v5, v1
	v_mul_f32_e32 v1, 0x3d372713, v142
	v_mul_f32_e32 v1, v142, v1
	v_fma_f32 v1, v142, v1, v142
	v_mul_f32_e32 v1, 0x3f4c422a, v1
	v_mul_f32_e32 v1, 0xc038aa3b, v1
	v_exp_f32_e32 v1, v1
	v_pk_mul_f32 v[4:5], v[140:141], v[4:5]
	v_add_f32_e32 v1, 1.0, v1
	v_cvt_pk_bf16_f32 v3, v4, v5
	ds_write_b64 v32, v[2:3] offset:2048
	v_rcp_f32_e32 v2, v1
	v_mul_f32_e32 v1, 0x3d372713, v143
	v_mul_f32_e32 v1, v143, v1
	v_fma_f32 v1, v143, v1, v143
	v_mul_f32_e32 v1, 0x3f4c422a, v1
	v_mul_f32_e32 v1, 0xc038aa3b, v1
	v_exp_f32_e32 v1, v1
	s_nop 0
	v_add_f32_e32 v1, 1.0, v1
	v_rcp_f32_e32 v3, v1
	v_mul_f32_e32 v1, 0x3d372713, v138
	v_mul_f32_e32 v1, v138, v1
	v_fma_f32 v1, v138, v1, v138
	v_mul_f32_e32 v1, 0x3f4c422a, v1
	v_mul_f32_e32 v1, 0xc038aa3b, v1
	v_exp_f32_e32 v1, v1
	v_pk_mul_f32 v[2:3], v[142:143], v[2:3]
	v_add_f32_e32 v1, 1.0, v1
	v_rcp_f32_e32 v4, v1
	v_mul_f32_e32 v1, 0x3d372713, v139
	v_mul_f32_e32 v1, v139, v1
	v_fma_f32 v1, v139, v1, v139
	v_mul_f32_e32 v1, 0x3f4c422a, v1
	v_mul_f32_e32 v1, 0xc038aa3b, v1
	v_exp_f32_e32 v1, v1
	v_cvt_pk_bf16_f32 v2, v2, v3
	v_add_f32_e32 v1, 1.0, v1
	v_rcp_f32_e32 v5, v1
	v_mul_f32_e32 v1, 0x3d372713, v128
	v_mul_f32_e32 v1, v128, v1
	v_fma_f32 v1, v128, v1, v128
	v_mul_f32_e32 v1, 0x3f4c422a, v1
	v_mul_f32_e32 v1, 0xc038aa3b, v1
	v_exp_f32_e32 v1, v1
	v_pk_mul_f32 v[4:5], v[138:139], v[4:5]
	v_add_f32_e32 v1, 1.0, v1
	v_cvt_pk_bf16_f32 v3, v4, v5
	ds_write_b64 v33, v[2:3] offset:2048
	v_rcp_f32_e32 v2, v1
	v_mul_f32_e32 v1, 0x3d372713, v129
	v_mul_f32_e32 v1, v129, v1
	v_fma_f32 v1, v129, v1, v129
	v_mul_f32_e32 v1, 0x3f4c422a, v1
	v_mul_f32_e32 v1, 0xc038aa3b, v1
	v_exp_f32_e32 v1, v1
	s_nop 0
	v_add_f32_e32 v1, 1.0, v1
	v_rcp_f32_e32 v3, v1
	v_mul_f32_e32 v1, 0x3d372713, v126
	v_mul_f32_e32 v1, v126, v1
	v_fma_f32 v1, v126, v1, v126
	v_mul_f32_e32 v1, 0x3f4c422a, v1
	v_mul_f32_e32 v1, 0xc038aa3b, v1
	v_exp_f32_e32 v1, v1
	v_pk_mul_f32 v[2:3], v[128:129], v[2:3]
	v_add_f32_e32 v1, 1.0, v1
	v_rcp_f32_e32 v4, v1
	v_mul_f32_e32 v1, 0x3d372713, v127
	v_mul_f32_e32 v1, v127, v1
	v_fma_f32 v1, v127, v1, v127
	v_mul_f32_e32 v1, 0x3f4c422a, v1
	v_mul_f32_e32 v1, 0xc038aa3b, v1
	v_exp_f32_e32 v1, v1
	v_cvt_pk_bf16_f32 v2, v2, v3
	v_add_f32_e32 v1, 1.0, v1
	v_rcp_f32_e32 v5, v1
	v_mul_f32_e32 v1, 0x3d372713, v124
	v_mul_f32_e32 v1, v124, v1
	v_fma_f32 v1, v124, v1, v124
	v_mul_f32_e32 v1, 0x3f4c422a, v1
	v_mul_f32_e32 v1, 0xc038aa3b, v1
	v_exp_f32_e32 v1, v1
	v_pk_mul_f32 v[4:5], v[126:127], v[4:5]
	v_add_f32_e32 v1, 1.0, v1
	v_cvt_pk_bf16_f32 v3, v4, v5
	ds_write_b64 v34, v[2:3] offset:2048
	v_rcp_f32_e32 v2, v1
	v_mul_f32_e32 v1, 0x3d372713, v125
	v_mul_f32_e32 v1, v125, v1
	v_fma_f32 v1, v125, v1, v125
	v_mul_f32_e32 v1, 0x3f4c422a, v1
	v_mul_f32_e32 v1, 0xc038aa3b, v1
	v_exp_f32_e32 v1, v1
	s_nop 0
	v_add_f32_e32 v1, 1.0, v1
	v_rcp_f32_e32 v3, v1
	v_mul_f32_e32 v1, 0x3d372713, v120
	v_mul_f32_e32 v1, v120, v1
	v_fma_f32 v1, v120, v1, v120
	v_mul_f32_e32 v1, 0x3f4c422a, v1
	v_mul_f32_e32 v1, 0xc038aa3b, v1
	v_exp_f32_e32 v1, v1
	v_pk_mul_f32 v[2:3], v[124:125], v[2:3]
	v_add_f32_e32 v1, 1.0, v1
; DI unsigned pk2(float a, float b) { f32x2 v = {a, b}; bf2_t r = __builtin_convertvector(v, bf2_t); return __builtin_bit_cast(unsigned, r); }
; DI float fexp2(float x) { return __builtin_amdgcn_exp2f(x); }
; DI float gelu_tanh(float x) {
;     const float y = 0.7978845608028654f * (x + 0.044715f * x * x * x);
;     return x * __builtin_amdgcn_rcpf(1.f + fexp2(-2.f * LOG2E * y));
; }
;     static DI void run(const f32x4 (&acc)[8][4], const TileCtx& tc, const Params& p, ldsp_t wb) {
;     ...
;         } else if (BRK == 2) {
; #pragma unroll
;             for (int h = 0; h < 2; ++h) {
; #pragma unroll
;                 for (int mm = 0; mm < 4; ++mm) {
;                     const int m = h * 4 + mm;
; #pragma unroll
;                     for (int n = 0; n < 4; ++n) {
;                         u32x2 w; w[0] = pk2(gelu_tanh(acc[m][n][0]), gelu_tanh(acc[m][n][1])); w[1] = pk2(gelu_tanh(acc[m][n][2]), gelu_tanh(acc[m][n][3]));
;                         wave_put(wb, mm * 16 + fr, n, fq, w);
;                     }
;                 }
;                 wave_rows_store(wb, tc.lane, p.U + (size_t)(tc.brow + tc.wr * 128 + h * 64) * 1024 + (pn - 3) * 256 + wc * 64, 1024);
	v_rcp_f32_e32 v4, v1
	v_mul_f32_e32 v1, 0x3d372713, v121
	v_mul_f32_e32 v1, v121, v1
	v_fma_f32 v1, v121, v1, v121
	v_mul_f32_e32 v1, 0x3f4c422a, v1
	v_mul_f32_e32 v1, 0xc038aa3b, v1
	v_exp_f32_e32 v1, v1
	v_cvt_pk_bf16_f32 v2, v2, v3
	v_add_f32_e32 v1, 1.0, v1
	v_rcp_f32_e32 v5, v1
	v_mul_f32_e32 v1, 0x3d372713, v136
	v_mul_f32_e32 v1, v136, v1
	v_fma_f32 v1, v136, v1, v136
	v_mul_f32_e32 v1, 0x3f4c422a, v1
	v_mul_f32_e32 v1, 0xc038aa3b, v1
	v_exp_f32_e32 v1, v1
	v_pk_mul_f32 v[4:5], v[120:121], v[4:5]
	v_add_f32_e32 v1, 1.0, v1
	v_cvt_pk_bf16_f32 v3, v4, v5
	ds_write_b64 v35, v[2:3] offset:2048
	v_rcp_f32_e32 v2, v1
	v_mul_f32_e32 v1, 0x3d372713, v137
	v_mul_f32_e32 v1, v137, v1
	v_fma_f32 v1, v137, v1, v137
	v_mul_f32_e32 v1, 0x3f4c422a, v1
	v_mul_f32_e32 v1, 0xc038aa3b, v1
	v_exp_f32_e32 v1, v1
	s_nop 0
	v_add_f32_e32 v1, 1.0, v1
	v_rcp_f32_e32 v3, v1
	v_mul_f32_e32 v1, 0x3d372713, v132
	v_mul_f32_e32 v1, v132, v1
	v_fma_f32 v1, v132, v1, v132
	v_mul_f32_e32 v1, 0x3f4c422a, v1
	v_mul_f32_e32 v1, 0xc038aa3b, v1
	v_exp_f32_e32 v1, v1
	v_pk_mul_f32 v[2:3], v[136:137], v[2:3]
	v_add_f32_e32 v1, 1.0, v1
	v_rcp_f32_e32 v4, v1
	v_mul_f32_e32 v1, 0x3d372713, v133
	v_mul_f32_e32 v1, v133, v1
	v_fma_f32 v1, v133, v1, v133
	v_mul_f32_e32 v1, 0x3f4c422a, v1
	v_mul_f32_e32 v1, 0xc038aa3b, v1
	v_exp_f32_e32 v1, v1
	v_cvt_pk_bf16_f32 v2, v2, v3
	v_add_f32_e32 v1, 1.0, v1
	v_rcp_f32_e32 v5, v1
	v_mul_f32_e32 v1, 0x3d372713, v134
	v_mul_f32_e32 v1, v134, v1
	v_fma_f32 v1, v134, v1, v134
	v_mul_f32_e32 v1, 0x3f4c422a, v1
	v_mul_f32_e32 v1, 0xc038aa3b, v1
	v_exp_f32_e32 v1, v1
	v_pk_mul_f32 v[4:5], v[132:133], v[4:5]
	v_add_f32_e32 v1, 1.0, v1
	v_cvt_pk_bf16_f32 v3, v4, v5
	ds_write_b64 v32, v[2:3] offset:4096
	v_rcp_f32_e32 v2, v1
	v_mul_f32_e32 v1, 0x3d372713, v135
	v_mul_f32_e32 v1, v135, v1
	v_fma_f32 v1, v135, v1, v135
	v_mul_f32_e32 v1, 0x3f4c422a, v1
	v_mul_f32_e32 v1, 0xc038aa3b, v1
	v_exp_f32_e32 v1, v1
	s_nop 0
	v_add_f32_e32 v1, 1.0, v1
	v_rcp_f32_e32 v3, v1
	v_mul_f32_e32 v1, 0x3d372713, v130
	v_mul_f32_e32 v1, v130, v1
	v_fma_f32 v1, v130, v1, v130
	v_mul_f32_e32 v1, 0x3f4c422a, v1
	v_mul_f32_e32 v1, 0xc038aa3b, v1
	v_exp_f32_e32 v1, v1
	v_pk_mul_f32 v[2:3], v[134:135], v[2:3]
	v_add_f32_e32 v1, 1.0, v1
	v_rcp_f32_e32 v4, v1
	v_mul_f32_e32 v1, 0x3d372713, v131
	v_mul_f32_e32 v1, v131, v1
	v_fma_f32 v1, v131, v1, v131
	v_mul_f32_e32 v1, 0x3f4c422a, v1
	v_mul_f32_e32 v1, 0xc038aa3b, v1
	v_exp_f32_e32 v1, v1
	v_cvt_pk_bf16_f32 v2, v2, v3
	v_add_f32_e32 v1, 1.0, v1
	v_rcp_f32_e32 v5, v1
	v_mul_f32_e32 v1, 0x3d372713, v122
	v_mul_f32_e32 v1, v122, v1
	v_fma_f32 v1, v122, v1, v122
	v_mul_f32_e32 v1, 0x3f4c422a, v1
	v_mul_f32_e32 v1, 0xc038aa3b, v1
	v_exp_f32_e32 v1, v1
	v_pk_mul_f32 v[4:5], v[130:131], v[4:5]
	v_add_f32_e32 v1, 1.0, v1
	v_cvt_pk_bf16_f32 v3, v4, v5
	ds_write_b64 v33, v[2:3] offset:4096
	v_rcp_f32_e32 v2, v1
	v_mul_f32_e32 v1, 0x3d372713, v123
	v_mul_f32_e32 v1, v123, v1
	v_fma_f32 v1, v123, v1, v123
	v_mul_f32_e32 v1, 0x3f4c422a, v1
	v_mul_f32_e32 v1, 0xc038aa3b, v1
	v_exp_f32_e32 v1, v1
	s_nop 0
	v_add_f32_e32 v1, 1.0, v1
	v_rcp_f32_e32 v3, v1
	v_mul_f32_e32 v1, 0x3d372713, v118
	v_mul_f32_e32 v1, v118, v1
	v_fma_f32 v1, v118, v1, v118
	v_mul_f32_e32 v1, 0x3f4c422a, v1
	v_mul_f32_e32 v1, 0xc038aa3b, v1
	v_exp_f32_e32 v1, v1
	v_pk_mul_f32 v[2:3], v[122:123], v[2:3]
	v_add_f32_e32 v1, 1.0, v1
	v_rcp_f32_e32 v4, v1
	v_mul_f32_e32 v1, 0x3d372713, v119
	v_mul_f32_e32 v1, v119, v1
	v_fma_f32 v1, v119, v1, v119
	v_mul_f32_e32 v1, 0x3f4c422a, v1
	v_mul_f32_e32 v1, 0xc038aa3b, v1
	v_exp_f32_e32 v1, v1
	v_cvt_pk_bf16_f32 v2, v2, v3
	v_add_f32_e32 v1, 1.0, v1
	v_rcp_f32_e32 v5, v1
	v_mul_f32_e32 v1, 0x3d372713, v116
	v_mul_f32_e32 v1, v116, v1
	v_fma_f32 v1, v116, v1, v116
	v_mul_f32_e32 v1, 0x3f4c422a, v1
	v_mul_f32_e32 v1, 0xc038aa3b, v1
	v_exp_f32_e32 v1, v1
	v_pk_mul_f32 v[4:5], v[118:119], v[4:5]
	v_add_f32_e32 v1, 1.0, v1
	v_cvt_pk_bf16_f32 v3, v4, v5
	ds_write_b64 v34, v[2:3] offset:4096
	v_rcp_f32_e32 v2, v1
	v_mul_f32_e32 v1, 0x3d372713, v117
	v_mul_f32_e32 v1, v117, v1
	v_fma_f32 v1, v117, v1, v117
	v_mul_f32_e32 v1, 0x3f4c422a, v1
	v_mul_f32_e32 v1, 0xc038aa3b, v1
	v_exp_f32_e32 v1, v1
	s_nop 0
	v_add_f32_e32 v1, 1.0, v1
	v_rcp_f32_e32 v3, v1
	v_mul_f32_e32 v1, 0x3d372713, v114
	v_mul_f32_e32 v1, v114, v1
	v_fma_f32 v1, v114, v1, v114
	v_mul_f32_e32 v1, 0x3f4c422a, v1
	v_mul_f32_e32 v1, 0xc038aa3b, v1
	v_exp_f32_e32 v1, v1
	v_pk_mul_f32 v[2:3], v[116:117], v[2:3]
	v_add_f32_e32 v1, 1.0, v1
	v_rcp_f32_e32 v4, v1
	v_mul_f32_e32 v1, 0x3d372713, v115
	v_mul_f32_e32 v1, v115, v1
	v_fma_f32 v1, v115, v1, v115
	v_mul_f32_e32 v1, 0x3f4c422a, v1
	v_mul_f32_e32 v1, 0xc038aa3b, v1
	v_exp_f32_e32 v1, v1
	v_cvt_pk_bf16_f32 v2, v2, v3
	v_add_f32_e32 v1, 1.0, v1
	v_rcp_f32_e32 v5, v1
	v_mul_f32_e32 v1, 0x3d372713, v102
	v_mul_f32_e32 v1, v102, v1
	v_fma_f32 v1, v102, v1, v102
	v_mul_f32_e32 v1, 0x3f4c422a, v1
	v_mul_f32_e32 v1, 0xc038aa3b, v1
	v_exp_f32_e32 v1, v1
	v_pk_mul_f32 v[4:5], v[114:115], v[4:5]
	v_add_f32_e32 v1, 1.0, v1
	v_cvt_pk_bf16_f32 v3, v4, v5
	ds_write_b64 v35, v[2:3] offset:4096
	v_rcp_f32_e32 v2, v1
	v_mul_f32_e32 v1, 0x3d372713, v103
	v_mul_f32_e32 v1, v103, v1
	v_fma_f32 v1, v103, v1, v103
	v_mul_f32_e32 v1, 0x3f4c422a, v1
	v_mul_f32_e32 v1, 0xc038aa3b, v1
	v_exp_f32_e32 v1, v1
	s_nop 0
	v_add_f32_e32 v1, 1.0, v1
	v_rcp_f32_e32 v3, v1
	v_mul_f32_e32 v1, 0x3d372713, v98
	v_mul_f32_e32 v1, v98, v1
	v_fma_f32 v1, v98, v1, v98
	v_mul_f32_e32 v1, 0x3f4c422a, v1
	v_mul_f32_e32 v1, 0xc038aa3b, v1
	v_exp_f32_e32 v1, v1
	v_pk_mul_f32 v[2:3], v[102:103], v[2:3]
	v_add_f32_e32 v1, 1.0, v1
	v_rcp_f32_e32 v4, v1
; #define LDSP __attribute__((address_space(3)))
; DI unsigned pk2(float a, float b) { f32x2 v = {a, b}; bf2_t r = __builtin_convertvector(v, bf2_t); return __builtin_bit_cast(unsigned, r); }
; DI void wave_rows_store(ldsp_t wb, int lane, bf16_t* dst0, size_t ld) {
; #pragma unroll
;     for (int i = 0; i < 8; ++i) {
;         const int row = i * 8 + (lane >> 3), ch = lane & 7;
;         const u32x4 v = *(const LDSP u32x4*)(wb + row * 128 + ((ch ^ (row & 7)) << 4));
;         *(u32x4*)(dst0 + (size_t)row * ld + ch * 8) = v;
;     }
;     static DI void run(const f32x4 (&acc)[8][4], const TileCtx& tc, const Params& p, ldsp_t wb) {
;     ...
;         } else if (BRK == 2) {
; #pragma unroll
;             for (int h = 0; h < 2; ++h) {
; #pragma unroll
;                 for (int mm = 0; mm < 4; ++mm) {
;                     const int m = h * 4 + mm;
; #pragma unroll
;                     for (int n = 0; n < 4; ++n) {
;                         u32x2 w; w[0] = pk2(gelu_tanh(acc[m][n][0]), gelu_tanh(acc[m][n][1])); w[1] = pk2(gelu_tanh(acc[m][n][2]), gelu_tanh(acc[m][n][3]));
;                         wave_put(wb, mm * 16 + fr, n, fq, w);
;                     }
;                 }
;                 wave_rows_store(wb, tc.lane, p.U + (size_t)(tc.brow + tc.wr * 128 + h * 64) * 1024 + (pn - 3) * 256 + wc * 64, 1024);
	v_mul_f32_e32 v1, 0x3d372713, v99
	v_mul_f32_e32 v1, v99, v1
	v_fma_f32 v1, v99, v1, v99
	v_mul_f32_e32 v1, 0x3f4c422a, v1
	v_mul_f32_e32 v1, 0xc038aa3b, v1
	v_exp_f32_e32 v1, v1
	v_cvt_pk_bf16_f32 v2, v2, v3
	v_add_f32_e32 v1, 1.0, v1
	v_rcp_f32_e32 v5, v1
	v_mul_f32_e32 v1, 0x3d372713, v100
	v_mul_f32_e32 v1, v100, v1
	v_fma_f32 v1, v100, v1, v100
	v_mul_f32_e32 v1, 0x3f4c422a, v1
	v_mul_f32_e32 v1, 0xc038aa3b, v1
	v_exp_f32_e32 v1, v1
	v_pk_mul_f32 v[4:5], v[98:99], v[4:5]
	v_add_f32_e32 v1, 1.0, v1
	v_cvt_pk_bf16_f32 v3, v4, v5
	ds_write_b64 v32, v[2:3] offset:6144
	v_rcp_f32_e32 v2, v1
	v_mul_f32_e32 v1, 0x3d372713, v101
	v_mul_f32_e32 v1, v101, v1
	v_fma_f32 v1, v101, v1, v101
	v_mul_f32_e32 v1, 0x3f4c422a, v1
	v_mul_f32_e32 v1, 0xc038aa3b, v1
	v_exp_f32_e32 v1, v1
	s_nop 0
	v_add_f32_e32 v1, 1.0, v1
	v_rcp_f32_e32 v3, v1
	v_mul_f32_e32 v1, 0x3d372713, v96
	v_mul_f32_e32 v1, v96, v1
	v_fma_f32 v1, v96, v1, v96
	v_mul_f32_e32 v1, 0x3f4c422a, v1
	v_mul_f32_e32 v1, 0xc038aa3b, v1
	v_exp_f32_e32 v1, v1
	v_pk_mul_f32 v[2:3], v[100:101], v[2:3]
	v_add_f32_e32 v1, 1.0, v1
	v_rcp_f32_e32 v4, v1
	v_mul_f32_e32 v1, 0x3d372713, v97
	v_mul_f32_e32 v1, v97, v1
	v_fma_f32 v1, v97, v1, v97
	v_mul_f32_e32 v1, 0x3f4c422a, v1
	v_mul_f32_e32 v1, 0xc038aa3b, v1
	v_exp_f32_e32 v1, v1
	v_cvt_pk_bf16_f32 v2, v2, v3
	v_add_f32_e32 v1, 1.0, v1
	v_rcp_f32_e32 v5, v1
	v_mul_f32_e32 v1, 0x3d372713, v94
	v_mul_f32_e32 v1, v94, v1
	v_fma_f32 v1, v94, v1, v94
	v_mul_f32_e32 v1, 0x3f4c422a, v1
	v_mul_f32_e32 v1, 0xc038aa3b, v1
	v_exp_f32_e32 v1, v1
	v_pk_mul_f32 v[4:5], v[96:97], v[4:5]
	v_add_f32_e32 v1, 1.0, v1
	v_cvt_pk_bf16_f32 v3, v4, v5
	ds_write_b64 v33, v[2:3] offset:6144
	v_rcp_f32_e32 v2, v1
	v_mul_f32_e32 v1, 0x3d372713, v95
	v_mul_f32_e32 v1, v95, v1
	v_fma_f32 v1, v95, v1, v95
	v_mul_f32_e32 v1, 0x3f4c422a, v1
	v_mul_f32_e32 v1, 0xc038aa3b, v1
	v_exp_f32_e32 v1, v1
	s_nop 0
	v_add_f32_e32 v1, 1.0, v1
	v_rcp_f32_e32 v3, v1
	v_mul_f32_e32 v1, 0x3d372713, v92
	v_mul_f32_e32 v1, v92, v1
	v_fma_f32 v1, v92, v1, v92
	v_mul_f32_e32 v1, 0x3f4c422a, v1
	v_mul_f32_e32 v1, 0xc038aa3b, v1
	v_exp_f32_e32 v1, v1
	v_pk_mul_f32 v[2:3], v[94:95], v[2:3]
	v_add_f32_e32 v1, 1.0, v1
	v_rcp_f32_e32 v4, v1
	v_mul_f32_e32 v1, 0x3d372713, v93
	v_mul_f32_e32 v1, v93, v1
	v_fma_f32 v1, v93, v1, v93
	v_mul_f32_e32 v1, 0x3f4c422a, v1
	v_mul_f32_e32 v1, 0xc038aa3b, v1
	v_exp_f32_e32 v1, v1
	v_cvt_pk_bf16_f32 v2, v2, v3
	v_add_f32_e32 v1, 1.0, v1
	v_rcp_f32_e32 v5, v1
	v_mul_f32_e32 v1, 0x3d372713, v90
	v_mul_f32_e32 v1, v90, v1
	v_fma_f32 v1, v90, v1, v90
	v_mul_f32_e32 v1, 0x3f4c422a, v1
	v_mul_f32_e32 v1, 0xc038aa3b, v1
	v_exp_f32_e32 v1, v1
	v_pk_mul_f32 v[4:5], v[92:93], v[4:5]
	v_add_f32_e32 v1, 1.0, v1
	v_cvt_pk_bf16_f32 v3, v4, v5
	ds_write_b64 v34, v[2:3] offset:6144
	v_rcp_f32_e32 v2, v1
	v_mul_f32_e32 v1, 0x3d372713, v91
	v_mul_f32_e32 v1, v91, v1
	v_fma_f32 v1, v91, v1, v91
	v_mul_f32_e32 v1, 0x3f4c422a, v1
	v_mul_f32_e32 v1, 0xc038aa3b, v1
	v_exp_f32_e32 v1, v1
	s_nop 0
	v_add_f32_e32 v1, 1.0, v1
	v_rcp_f32_e32 v3, v1
	v_mul_f32_e32 v1, 0x3d372713, v88
	v_mul_f32_e32 v1, v88, v1
	v_fma_f32 v1, v88, v1, v88
	v_mul_f32_e32 v1, 0x3f4c422a, v1
	v_mul_f32_e32 v1, 0xc038aa3b, v1
	v_exp_f32_e32 v1, v1
	v_pk_mul_f32 v[2:3], v[90:91], v[2:3]
	v_add_f32_e32 v1, 1.0, v1
	v_rcp_f32_e32 v4, v1
	v_mul_f32_e32 v1, 0x3d372713, v89
	v_mul_f32_e32 v1, v89, v1
	v_fma_f32 v1, v89, v1, v89
	v_mul_f32_e32 v1, 0x3f4c422a, v1
	v_mul_f32_e32 v1, 0xc038aa3b, v1
	v_exp_f32_e32 v1, v1
	v_cvt_pk_bf16_f32 v2, v2, v3
	v_add_f32_e32 v1, 1.0, v1
	v_rcp_f32_e32 v5, v1
	s_nop 0
	v_pk_mul_f32 v[4:5], v[88:89], v[4:5]
	s_nop 0
	v_cvt_pk_bf16_f32 v3, v4, v5
	ds_write_b64 v35, v[2:3] offset:6144
	v_lshlrev_b64 v[2:3], 11, v[10:11]
	v_lshl_add_u64 v[2:3], s[16:17], 0, v[2:3]
	v_lshl_add_u64 v[2:3], v[2:3], 0, s[4:5]
	v_lshrrev_b32_e32 v11, 3, v170
	v_lshl_add_u64 v[0:1], v[2:3], 0, v[192:193]
	v_xor_b32_e32 v2, v11, v170
	v_lshlrev_b32_e32 v2, 4, v2
	v_and_b32_e32 v2, 0x70, v2
	v_add_u32_e32 v43, v176, v2
	v_lshlrev_b32_e32 v2, 4, v170
	v_and_b32_e32 v18, 0x70, v2
	v_lshl_add_u32 v42, v11, 7, v43
	v_lshl_add_u64 v[162:163], v[0:1], 0, v[18:19]
	ds_read_b128 v[0:3], v42
	v_lshlrev_b32_e32 v16, 11, v11
	v_lshl_add_u64 v[4:5], v[162:163], 0, v[16:17]
	s_waitcnt lgkmcnt(0)
	global_store_dwordx4 v[4:5], v[0:3], off
	v_or_b32_e32 v4, 8, v11
	v_lshl_add_u32 v41, v4, 7, v43
	ds_read_b128 v[0:3], v41
	v_lshlrev_b32_e32 v14, 11, v4
	v_lshl_add_u64 v[4:5], v[162:163], 0, v[14:15]
	s_waitcnt lgkmcnt(0)
	global_store_dwordx4 v[4:5], v[0:3], off
	v_or_b32_e32 v4, 16, v11
	v_lshl_add_u32 v40, v4, 7, v43
	ds_read_b128 v[0:3], v40
	v_lshlrev_b32_e32 v12, 11, v4
	v_lshl_add_u64 v[4:5], v[162:163], 0, v[12:13]
	s_waitcnt lgkmcnt(0)
	global_store_dwordx4 v[4:5], v[0:3], off
	v_or_b32_e32 v4, 24, v11
	v_lshl_add_u32 v39, v4, 7, v43
	ds_read_b128 v[0:3], v39
	v_lshlrev_b32_e32 v8, 11, v4
	v_lshl_add_u64 v[4:5], v[162:163], 0, v[8:9]
	s_waitcnt lgkmcnt(0)
	global_store_dwordx4 v[4:5], v[0:3], off
	s_nop 1
	v_or_b32_e32 v0, 32, v11
	v_lshl_add_u32 v38, v0, 7, v43
	ds_read_b128 v[4:7], v38
	v_lshlrev_b32_e32 v2, 11, v0
	v_mov_b32_e32 v3, v193
	v_lshl_add_u64 v[0:1], v[162:163], 0, v[2:3]
	s_waitcnt lgkmcnt(0)
	global_store_dwordx4 v[0:1], v[4:7], off
	v_or_b32_e32 v0, 40, v11
	v_lshl_add_u32 v37, v0, 7, v43
	ds_read_b128 v[148:151], v37
	v_lshlrev_b32_e32 v6, 11, v0
	v_mov_b32_e32 v7, v193
	v_lshl_add_u64 v[0:1], v[162:163], 0, v[6:7]
	v_mov_b32_e32 v5, v193
	s_waitcnt lgkmcnt(0)
	global_store_dwordx4 v[0:1], v[148:151], off
	v_or_b32_e32 v0, 48, v11
	v_lshl_add_u32 v36, v0, 7, v43
	ds_read_b128 v[148:151], v36
	v_lshlrev_b32_e32 v4, 11, v0
	v_lshl_add_u64 v[0:1], v[162:163], 0, v[4:5]
	s_waitcnt lgkmcnt(0)
; DI unsigned pk2(float a, float b) { f32x2 v = {a, b}; bf2_t r = __builtin_convertvector(v, bf2_t); return __builtin_bit_cast(unsigned, r); }
; DI float fexp2(float x) { return __builtin_amdgcn_exp2f(x); }
; DI float gelu_tanh(float x) {
;     const float y = 0.7978845608028654f * (x + 0.044715f * x * x * x);
;     return x * __builtin_amdgcn_rcpf(1.f + fexp2(-2.f * LOG2E * y));
; }
;     static DI void run(const f32x4 (&acc)[8][4], const TileCtx& tc, const Params& p, ldsp_t wb) {
;     ...
;         } else if (BRK == 2) {
; #pragma unroll
;             for (int h = 0; h < 2; ++h) {
; #pragma unroll
;                 for (int mm = 0; mm < 4; ++mm) {
;                     const int m = h * 4 + mm;
; #pragma unroll
;                     for (int n = 0; n < 4; ++n) {
;                         u32x2 w; w[0] = pk2(gelu_tanh(acc[m][n][0]), gelu_tanh(acc[m][n][1])); w[1] = pk2(gelu_tanh(acc[m][n][2]), gelu_tanh(acc[m][n][3]));
;                         wave_put(wb, mm * 16 + fr, n, fq, w);
;                     }
;                 }
;                 wave_rows_store(wb, tc.lane, p.U + (size_t)(tc.brow + tc.wr * 128 + h * 64) * 1024 + (pn - 3) * 256 + wc * 64, 1024);
	global_store_dwordx4 v[0:1], v[148:151], off
	v_or_b32_e32 v0, 56, v11
	v_lshl_add_u32 v11, v0, 7, v43
	v_mul_f32_e32 v43, 0x3d372713, v86
	v_mul_f32_e32 v43, v86, v43
	v_fma_f32 v43, v86, v43, v86
	v_mul_f32_e32 v43, 0x3f4c422a, v43
	v_mul_f32_e32 v43, 0xc038aa3b, v43
	ds_read_b128 v[148:151], v11
	v_exp_f32_e32 v43, v43
	v_lshlrev_b32_e32 v0, 11, v0
	v_mov_b32_e32 v1, v193
	v_lshl_add_u64 v[162:163], v[162:163], 0, v[0:1]
	v_add_f32_e32 v43, 1.0, v43
	s_waitcnt lgkmcnt(0)
	global_store_dwordx4 v[162:163], v[148:151], off
	s_nop 1
	v_rcp_f32_e32 v148, v43
	v_mul_f32_e32 v43, 0x3d372713, v87
	v_mul_f32_e32 v43, v87, v43
	v_fma_f32 v43, v87, v43, v87
	v_mul_f32_e32 v43, 0x3f4c422a, v43
	v_mul_f32_e32 v43, 0xc038aa3b, v43
	v_exp_f32_e32 v43, v43
	s_nop 0
	v_add_f32_e32 v43, 1.0, v43
	v_rcp_f32_e32 v149, v43
	v_mul_f32_e32 v43, 0x3d372713, v82
	v_mul_f32_e32 v43, v82, v43
	v_fma_f32 v43, v82, v43, v82
	v_mul_f32_e32 v43, 0x3f4c422a, v43
	v_mul_f32_e32 v43, 0xc038aa3b, v43
	v_exp_f32_e32 v43, v43
	v_pk_mul_f32 v[148:149], v[86:87], v[148:149]
	v_add_f32_e32 v43, 1.0, v43
	v_rcp_f32_e32 v150, v43
	v_mul_f32_e32 v43, 0x3d372713, v83
	v_mul_f32_e32 v43, v83, v43
	v_fma_f32 v43, v83, v43, v83
	v_mul_f32_e32 v43, 0x3f4c422a, v43
	v_mul_f32_e32 v43, 0xc038aa3b, v43
	v_exp_f32_e32 v43, v43
	v_cvt_pk_bf16_f32 v148, v148, v149
	v_add_f32_e32 v43, 1.0, v43
	v_rcp_f32_e32 v151, v43
	v_mul_f32_e32 v43, 0x3d372713, v84
	v_mul_f32_e32 v43, v84, v43
	v_fma_f32 v43, v84, v43, v84
	v_mul_f32_e32 v43, 0x3f4c422a, v43
	v_mul_f32_e32 v43, 0xc038aa3b, v43
	v_exp_f32_e32 v43, v43
	v_pk_mul_f32 v[150:151], v[82:83], v[150:151]
	v_add_f32_e32 v43, 1.0, v43
	v_cvt_pk_bf16_f32 v149, v150, v151
	ds_write_b64 v32, v[148:149]
	v_rcp_f32_e32 v148, v43
	v_mul_f32_e32 v43, 0x3d372713, v85
	v_mul_f32_e32 v43, v85, v43
	v_fma_f32 v43, v85, v43, v85
	v_mul_f32_e32 v43, 0x3f4c422a, v43
	v_mul_f32_e32 v43, 0xc038aa3b, v43
	v_exp_f32_e32 v43, v43
	s_nop 0
	v_add_f32_e32 v43, 1.0, v43
	v_rcp_f32_e32 v149, v43
	v_mul_f32_e32 v43, 0x3d372713, v80
	v_mul_f32_e32 v43, v80, v43
	v_fma_f32 v43, v80, v43, v80
	v_mul_f32_e32 v43, 0x3f4c422a, v43
	v_mul_f32_e32 v43, 0xc038aa3b, v43
	v_exp_f32_e32 v43, v43
	v_pk_mul_f32 v[148:149], v[84:85], v[148:149]
	v_add_f32_e32 v43, 1.0, v43
	v_rcp_f32_e32 v150, v43
	v_mul_f32_e32 v43, 0x3d372713, v81
	v_mul_f32_e32 v43, v81, v43
	v_fma_f32 v43, v81, v43, v81
	v_mul_f32_e32 v43, 0x3f4c422a, v43
	v_mul_f32_e32 v43, 0xc038aa3b, v43
	v_exp_f32_e32 v43, v43
	v_cvt_pk_bf16_f32 v148, v148, v149
	v_add_f32_e32 v43, 1.0, v43
	v_rcp_f32_e32 v151, v43
	v_mul_f32_e32 v43, 0x3d372713, v78
	v_mul_f32_e32 v43, v78, v43
	v_fma_f32 v43, v78, v43, v78
	v_mul_f32_e32 v43, 0x3f4c422a, v43
	v_mul_f32_e32 v43, 0xc038aa3b, v43
	v_exp_f32_e32 v43, v43
	v_pk_mul_f32 v[150:151], v[80:81], v[150:151]
	v_add_f32_e32 v43, 1.0, v43
	v_cvt_pk_bf16_f32 v149, v150, v151
	ds_write_b64 v33, v[148:149]
	v_rcp_f32_e32 v148, v43
	v_mul_f32_e32 v43, 0x3d372713, v79
	v_mul_f32_e32 v43, v79, v43
	v_fma_f32 v43, v79, v43, v79
	v_mul_f32_e32 v43, 0x3f4c422a, v43
	v_mul_f32_e32 v43, 0xc038aa3b, v43
	v_exp_f32_e32 v43, v43
	s_nop 0
	v_add_f32_e32 v43, 1.0, v43
	v_rcp_f32_e32 v149, v43
	v_mul_f32_e32 v43, 0x3d372713, v76
	v_mul_f32_e32 v43, v76, v43
	v_fma_f32 v43, v76, v43, v76
	v_mul_f32_e32 v43, 0x3f4c422a, v43
	v_mul_f32_e32 v43, 0xc038aa3b, v43
	v_exp_f32_e32 v43, v43
	v_pk_mul_f32 v[148:149], v[78:79], v[148:149]
	v_add_f32_e32 v43, 1.0, v43
	v_rcp_f32_e32 v150, v43
	v_mul_f32_e32 v43, 0x3d372713, v77
	v_mul_f32_e32 v43, v77, v43
	v_fma_f32 v43, v77, v43, v77
	v_mul_f32_e32 v43, 0x3f4c422a, v43
	v_mul_f32_e32 v43, 0xc038aa3b, v43
	v_exp_f32_e32 v43, v43
	v_cvt_pk_bf16_f32 v148, v148, v149
	v_add_f32_e32 v43, 1.0, v43
	v_rcp_f32_e32 v151, v43
	v_mul_f32_e32 v43, 0x3d372713, v74
	v_mul_f32_e32 v43, v74, v43
	v_fma_f32 v43, v74, v43, v74
	v_mul_f32_e32 v43, 0x3f4c422a, v43
	v_mul_f32_e32 v43, 0xc038aa3b, v43
	v_exp_f32_e32 v43, v43
	v_pk_mul_f32 v[150:151], v[76:77], v[150:151]
	v_add_f32_e32 v43, 1.0, v43
	v_cvt_pk_bf16_f32 v149, v150, v151
	ds_write_b64 v34, v[148:149]
	v_rcp_f32_e32 v148, v43
	v_mul_f32_e32 v43, 0x3d372713, v75
	v_mul_f32_e32 v43, v75, v43
	v_fma_f32 v43, v75, v43, v75
	v_mul_f32_e32 v43, 0x3f4c422a, v43
	v_mul_f32_e32 v43, 0xc038aa3b, v43
	v_exp_f32_e32 v43, v43
	s_nop 0
	v_add_f32_e32 v43, 1.0, v43
	v_rcp_f32_e32 v149, v43
	v_mul_f32_e32 v43, 0x3d372713, v72
	v_mul_f32_e32 v43, v72, v43
	v_fma_f32 v43, v72, v43, v72
	v_mul_f32_e32 v43, 0x3f4c422a, v43
	v_mul_f32_e32 v43, 0xc038aa3b, v43
	v_exp_f32_e32 v43, v43
	v_pk_mul_f32 v[148:149], v[74:75], v[148:149]
	v_add_f32_e32 v43, 1.0, v43
	v_rcp_f32_e32 v150, v43
	v_mul_f32_e32 v43, 0x3d372713, v73
	v_mul_f32_e32 v43, v73, v43
	v_fma_f32 v43, v73, v43, v73
	v_mul_f32_e32 v43, 0x3f4c422a, v43
	v_mul_f32_e32 v43, 0xc038aa3b, v43
	v_exp_f32_e32 v43, v43
	v_cvt_pk_bf16_f32 v148, v148, v149
	v_add_f32_e32 v43, 1.0, v43
	v_rcp_f32_e32 v151, v43
	v_mul_f32_e32 v43, 0x3d372713, v70
	v_mul_f32_e32 v43, v70, v43
	v_fma_f32 v43, v70, v43, v70
	v_mul_f32_e32 v43, 0x3f4c422a, v43
	v_mul_f32_e32 v43, 0xc038aa3b, v43
	v_exp_f32_e32 v43, v43
	v_pk_mul_f32 v[150:151], v[72:73], v[150:151]
	v_add_f32_e32 v43, 1.0, v43
	v_cvt_pk_bf16_f32 v149, v150, v151
	ds_write_b64 v35, v[148:149]
	v_rcp_f32_e32 v148, v43
	v_mul_f32_e32 v43, 0x3d372713, v71
	v_mul_f32_e32 v43, v71, v43
	v_fma_f32 v43, v71, v43, v71
	v_mul_f32_e32 v43, 0x3f4c422a, v43
	v_mul_f32_e32 v43, 0xc038aa3b, v43
	v_exp_f32_e32 v43, v43
	s_nop 0
	v_add_f32_e32 v43, 1.0, v43
	v_rcp_f32_e32 v149, v43
	v_mul_f32_e32 v43, 0x3d372713, v68
	v_mul_f32_e32 v43, v68, v43
	v_fma_f32 v43, v68, v43, v68
; DI unsigned pk2(float a, float b) { f32x2 v = {a, b}; bf2_t r = __builtin_convertvector(v, bf2_t); return __builtin_bit_cast(unsigned, r); }
; DI float fexp2(float x) { return __builtin_amdgcn_exp2f(x); }
; DI float gelu_tanh(float x) {
;     const float y = 0.7978845608028654f * (x + 0.044715f * x * x * x);
;     return x * __builtin_amdgcn_rcpf(1.f + fexp2(-2.f * LOG2E * y));
; }
;     static DI void run(const f32x4 (&acc)[8][4], const TileCtx& tc, const Params& p, ldsp_t wb) {
;     ...
;         } else if (BRK == 2) {
; #pragma unroll
;             for (int h = 0; h < 2; ++h) {
; #pragma unroll
;                 for (int mm = 0; mm < 4; ++mm) {
;                     const int m = h * 4 + mm;
; #pragma unroll
;                     for (int n = 0; n < 4; ++n) {
;                         u32x2 w; w[0] = pk2(gelu_tanh(acc[m][n][0]), gelu_tanh(acc[m][n][1])); w[1] = pk2(gelu_tanh(acc[m][n][2]), gelu_tanh(acc[m][n][3]));
;                         wave_put(wb, mm * 16 + fr, n, fq, w);
;                     }
;                 }
;                 wave_rows_store(wb, tc.lane, p.U + (size_t)(tc.brow + tc.wr * 128 + h * 64) * 1024 + (pn - 3) * 256 + wc * 64, 1024);
	v_mul_f32_e32 v43, 0x3f4c422a, v43
	v_mul_f32_e32 v43, 0xc038aa3b, v43
	v_exp_f32_e32 v43, v43
	v_pk_mul_f32 v[148:149], v[70:71], v[148:149]
	v_add_f32_e32 v43, 1.0, v43
	v_rcp_f32_e32 v150, v43
	v_mul_f32_e32 v43, 0x3d372713, v69
	v_mul_f32_e32 v43, v69, v43
	v_fma_f32 v43, v69, v43, v69
	v_mul_f32_e32 v43, 0x3f4c422a, v43
	v_mul_f32_e32 v43, 0xc038aa3b, v43
	v_exp_f32_e32 v43, v43
	v_cvt_pk_bf16_f32 v148, v148, v149
	v_add_f32_e32 v43, 1.0, v43
	v_rcp_f32_e32 v151, v43
	v_mul_f32_e32 v43, 0x3d372713, v66
	v_mul_f32_e32 v43, v66, v43
	v_fma_f32 v43, v66, v43, v66
	v_mul_f32_e32 v43, 0x3f4c422a, v43
	v_mul_f32_e32 v43, 0xc038aa3b, v43
	v_exp_f32_e32 v43, v43
	v_pk_mul_f32 v[150:151], v[68:69], v[150:151]
	v_add_f32_e32 v43, 1.0, v43
	v_cvt_pk_bf16_f32 v149, v150, v151
	ds_write_b64 v32, v[148:149] offset:2048
	v_rcp_f32_e32 v148, v43
	v_mul_f32_e32 v43, 0x3d372713, v67
	v_mul_f32_e32 v43, v67, v43
	v_fma_f32 v43, v67, v43, v67
	v_mul_f32_e32 v43, 0x3f4c422a, v43
	v_mul_f32_e32 v43, 0xc038aa3b, v43
	v_exp_f32_e32 v43, v43
	s_nop 0
	v_add_f32_e32 v43, 1.0, v43
	v_rcp_f32_e32 v149, v43
	v_mul_f32_e32 v43, 0x3d372713, v64
	v_mul_f32_e32 v43, v64, v43
	v_fma_f32 v43, v64, v43, v64
	v_mul_f32_e32 v43, 0x3f4c422a, v43
	v_mul_f32_e32 v43, 0xc038aa3b, v43
	v_exp_f32_e32 v43, v43
	v_pk_mul_f32 v[148:149], v[66:67], v[148:149]
	v_add_f32_e32 v43, 1.0, v43
	v_rcp_f32_e32 v150, v43
	v_mul_f32_e32 v43, 0x3d372713, v65
	v_mul_f32_e32 v43, v65, v43
	v_fma_f32 v43, v65, v43, v65
	v_mul_f32_e32 v43, 0x3f4c422a, v43
	v_mul_f32_e32 v43, 0xc038aa3b, v43
	v_exp_f32_e32 v43, v43
	v_cvt_pk_bf16_f32 v148, v148, v149
	v_add_f32_e32 v43, 1.0, v43
	v_rcp_f32_e32 v151, v43
	v_mul_f32_e32 v43, 0x3d372713, v62
	v_mul_f32_e32 v43, v62, v43
	v_fma_f32 v43, v62, v43, v62
	v_mul_f32_e32 v43, 0x3f4c422a, v43
	v_mul_f32_e32 v43, 0xc038aa3b, v43
	v_exp_f32_e32 v43, v43
	v_pk_mul_f32 v[150:151], v[64:65], v[150:151]
	v_add_f32_e32 v43, 1.0, v43
	v_cvt_pk_bf16_f32 v149, v150, v151
	ds_write_b64 v33, v[148:149] offset:2048
	v_rcp_f32_e32 v148, v43
	v_mul_f32_e32 v43, 0x3d372713, v63
	v_mul_f32_e32 v43, v63, v43
	v_fma_f32 v43, v63, v43, v63
	v_mul_f32_e32 v43, 0x3f4c422a, v43
	v_mul_f32_e32 v43, 0xc038aa3b, v43
	v_exp_f32_e32 v43, v43
	s_nop 0
	v_add_f32_e32 v43, 1.0, v43
	v_rcp_f32_e32 v149, v43
	v_mul_f32_e32 v43, 0x3d372713, v60
	v_mul_f32_e32 v43, v60, v43
	v_fma_f32 v43, v60, v43, v60
	v_mul_f32_e32 v43, 0x3f4c422a, v43
	v_mul_f32_e32 v43, 0xc038aa3b, v43
	v_exp_f32_e32 v43, v43
	v_pk_mul_f32 v[148:149], v[62:63], v[148:149]
	v_add_f32_e32 v43, 1.0, v43
	v_rcp_f32_e32 v150, v43
	v_mul_f32_e32 v43, 0x3d372713, v61
	v_mul_f32_e32 v43, v61, v43
	v_fma_f32 v43, v61, v43, v61
	v_mul_f32_e32 v43, 0x3f4c422a, v43
	v_mul_f32_e32 v43, 0xc038aa3b, v43
	v_exp_f32_e32 v43, v43
	v_cvt_pk_bf16_f32 v148, v148, v149
	v_add_f32_e32 v43, 1.0, v43
	v_rcp_f32_e32 v151, v43
	v_mul_f32_e32 v43, 0x3d372713, v58
	v_mul_f32_e32 v43, v58, v43
	v_fma_f32 v43, v58, v43, v58
	v_mul_f32_e32 v43, 0x3f4c422a, v43
	v_mul_f32_e32 v43, 0xc038aa3b, v43
	v_exp_f32_e32 v43, v43
	v_pk_mul_f32 v[150:151], v[60:61], v[150:151]
	v_add_f32_e32 v43, 1.0, v43
	v_cvt_pk_bf16_f32 v149, v150, v151
	ds_write_b64 v34, v[148:149] offset:2048
	v_rcp_f32_e32 v148, v43
	v_mul_f32_e32 v43, 0x3d372713, v59
	v_mul_f32_e32 v43, v59, v43
	v_fma_f32 v43, v59, v43, v59
	v_mul_f32_e32 v43, 0x3f4c422a, v43
	v_mul_f32_e32 v43, 0xc038aa3b, v43
	v_exp_f32_e32 v43, v43
	s_nop 0
	v_add_f32_e32 v43, 1.0, v43
	v_rcp_f32_e32 v149, v43
	v_mul_f32_e32 v43, 0x3d372713, v56
	v_mul_f32_e32 v43, v56, v43
	v_fma_f32 v43, v56, v43, v56
	v_mul_f32_e32 v43, 0x3f4c422a, v43
	v_mul_f32_e32 v43, 0xc038aa3b, v43
	v_exp_f32_e32 v43, v43
	v_pk_mul_f32 v[148:149], v[58:59], v[148:149]
	v_add_f32_e32 v43, 1.0, v43
	v_rcp_f32_e32 v150, v43
	v_mul_f32_e32 v43, 0x3d372713, v57
	v_mul_f32_e32 v43, v57, v43
	v_fma_f32 v43, v57, v43, v57
	v_mul_f32_e32 v43, 0x3f4c422a, v43
	v_mul_f32_e32 v43, 0xc038aa3b, v43
	v_exp_f32_e32 v43, v43
	v_cvt_pk_bf16_f32 v148, v148, v149
	v_add_f32_e32 v43, 1.0, v43
	v_rcp_f32_e32 v151, v43
	v_mul_f32_e32 v43, 0x3d372713, v110
	v_mul_f32_e32 v43, v110, v43
	v_fma_f32 v43, v110, v43, v110
	v_mul_f32_e32 v43, 0x3f4c422a, v43
	v_mul_f32_e32 v43, 0xc038aa3b, v43
	v_exp_f32_e32 v43, v43
	v_pk_mul_f32 v[150:151], v[56:57], v[150:151]
	v_add_f32_e32 v43, 1.0, v43
	v_cvt_pk_bf16_f32 v149, v150, v151
	ds_write_b64 v35, v[148:149] offset:2048
	v_rcp_f32_e32 v148, v43
	v_mul_f32_e32 v43, 0x3d372713, v111
	v_mul_f32_e32 v43, v111, v43
	v_fma_f32 v43, v111, v43, v111
	v_mul_f32_e32 v43, 0x3f4c422a, v43
	v_mul_f32_e32 v43, 0xc038aa3b, v43
	v_exp_f32_e32 v43, v43
	s_nop 0
	v_add_f32_e32 v43, 1.0, v43
	v_rcp_f32_e32 v149, v43
	v_mul_f32_e32 v43, 0x3d372713, v108
	v_mul_f32_e32 v43, v108, v43
	v_fma_f32 v43, v108, v43, v108
	v_mul_f32_e32 v43, 0x3f4c422a, v43
	v_mul_f32_e32 v43, 0xc038aa3b, v43
	v_exp_f32_e32 v43, v43
	v_pk_mul_f32 v[148:149], v[110:111], v[148:149]
	v_add_f32_e32 v43, 1.0, v43
	v_rcp_f32_e32 v150, v43
	v_mul_f32_e32 v43, 0x3d372713, v109
	v_mul_f32_e32 v43, v109, v43
	v_fma_f32 v43, v109, v43, v109
	v_mul_f32_e32 v43, 0x3f4c422a, v43
	v_mul_f32_e32 v43, 0xc038aa3b, v43
	v_exp_f32_e32 v43, v43
	v_cvt_pk_bf16_f32 v148, v148, v149
	v_add_f32_e32 v43, 1.0, v43
	v_rcp_f32_e32 v151, v43
	v_mul_f32_e32 v43, 0x3d372713, v106
	v_mul_f32_e32 v43, v106, v43
	v_fma_f32 v43, v106, v43, v106
	v_mul_f32_e32 v43, 0x3f4c422a, v43
	v_mul_f32_e32 v43, 0xc038aa3b, v43
	v_exp_f32_e32 v43, v43
	v_pk_mul_f32 v[150:151], v[108:109], v[150:151]
	v_add_f32_e32 v43, 1.0, v43
	v_cvt_pk_bf16_f32 v149, v150, v151
	ds_write_b64 v32, v[148:149] offset:4096
; DI unsigned pk2(float a, float b) { f32x2 v = {a, b}; bf2_t r = __builtin_convertvector(v, bf2_t); return __builtin_bit_cast(unsigned, r); }
; DI float fexp2(float x) { return __builtin_amdgcn_exp2f(x); }
; DI float gelu_tanh(float x) {
;     const float y = 0.7978845608028654f * (x + 0.044715f * x * x * x);
;     return x * __builtin_amdgcn_rcpf(1.f + fexp2(-2.f * LOG2E * y));
; }
;     static DI void run(const f32x4 (&acc)[8][4], const TileCtx& tc, const Params& p, ldsp_t wb) {
;     ...
;         } else if (BRK == 2) {
; #pragma unroll
;             for (int h = 0; h < 2; ++h) {
; #pragma unroll
;                 for (int mm = 0; mm < 4; ++mm) {
;                     const int m = h * 4 + mm;
; #pragma unroll
;                     for (int n = 0; n < 4; ++n) {
;                         u32x2 w; w[0] = pk2(gelu_tanh(acc[m][n][0]), gelu_tanh(acc[m][n][1])); w[1] = pk2(gelu_tanh(acc[m][n][2]), gelu_tanh(acc[m][n][3]));
;                         wave_put(wb, mm * 16 + fr, n, fq, w);
;                     }
;                 }
;                 wave_rows_store(wb, tc.lane, p.U + (size_t)(tc.brow + tc.wr * 128 + h * 64) * 1024 + (pn - 3) * 256 + wc * 64, 1024);
	v_rcp_f32_e32 v148, v43
	v_mul_f32_e32 v43, 0x3d372713, v107
	v_mul_f32_e32 v43, v107, v43
	v_fma_f32 v43, v107, v43, v107
	v_mul_f32_e32 v43, 0x3f4c422a, v43
	v_mul_f32_e32 v43, 0xc038aa3b, v43
	v_exp_f32_e32 v43, v43
	s_nop 0
	v_add_f32_e32 v43, 1.0, v43
	v_rcp_f32_e32 v149, v43
	v_mul_f32_e32 v43, 0x3d372713, v104
	v_mul_f32_e32 v43, v104, v43
	v_fma_f32 v43, v104, v43, v104
	v_mul_f32_e32 v43, 0x3f4c422a, v43
	v_mul_f32_e32 v43, 0xc038aa3b, v43
	v_exp_f32_e32 v43, v43
	v_pk_mul_f32 v[148:149], v[106:107], v[148:149]
	v_add_f32_e32 v43, 1.0, v43
	v_rcp_f32_e32 v150, v43
	v_mul_f32_e32 v43, 0x3d372713, v105
	v_mul_f32_e32 v43, v105, v43
	v_fma_f32 v43, v105, v43, v105
	v_mul_f32_e32 v43, 0x3f4c422a, v43
	v_mul_f32_e32 v43, 0xc038aa3b, v43
	v_exp_f32_e32 v43, v43
	v_cvt_pk_bf16_f32 v148, v148, v149
	v_add_f32_e32 v43, 1.0, v43
	v_rcp_f32_e32 v151, v43
	v_mul_f32_e32 v43, 0x3d372713, v54
	v_mul_f32_e32 v43, v54, v43
	v_fma_f32 v43, v54, v43, v54
	v_mul_f32_e32 v43, 0x3f4c422a, v43
	v_mul_f32_e32 v43, 0xc038aa3b, v43
	v_exp_f32_e32 v43, v43
	v_pk_mul_f32 v[150:151], v[104:105], v[150:151]
	v_add_f32_e32 v43, 1.0, v43
	v_cvt_pk_bf16_f32 v149, v150, v151
	ds_write_b64 v33, v[148:149] offset:4096
	v_rcp_f32_e32 v148, v43
	v_mul_f32_e32 v43, 0x3d372713, v55
	v_mul_f32_e32 v43, v55, v43
	v_fma_f32 v43, v55, v43, v55
	v_mul_f32_e32 v43, 0x3f4c422a, v43
	v_mul_f32_e32 v43, 0xc038aa3b, v43
	v_exp_f32_e32 v43, v43
	s_nop 0
	v_add_f32_e32 v43, 1.0, v43
	v_rcp_f32_e32 v149, v43
	v_mul_f32_e32 v43, 0x3d372713, v52
	v_mul_f32_e32 v43, v52, v43
	v_fma_f32 v43, v52, v43, v52
	v_mul_f32_e32 v43, 0x3f4c422a, v43
	v_mul_f32_e32 v43, 0xc038aa3b, v43
	v_exp_f32_e32 v43, v43
	v_pk_mul_f32 v[148:149], v[54:55], v[148:149]
	v_add_f32_e32 v43, 1.0, v43
	v_rcp_f32_e32 v150, v43
	v_mul_f32_e32 v43, 0x3d372713, v53
	v_mul_f32_e32 v43, v53, v43
	v_fma_f32 v43, v53, v43, v53
	v_mul_f32_e32 v43, 0x3f4c422a, v43
	v_mul_f32_e32 v43, 0xc038aa3b, v43
	v_exp_f32_e32 v43, v43
	v_cvt_pk_bf16_f32 v148, v148, v149
	v_add_f32_e32 v43, 1.0, v43
	v_rcp_f32_e32 v151, v43
	v_mul_f32_e32 v43, 0x3d372713, v50
	v_mul_f32_e32 v43, v50, v43
	v_fma_f32 v43, v50, v43, v50
	v_mul_f32_e32 v43, 0x3f4c422a, v43
	v_mul_f32_e32 v43, 0xc038aa3b, v43
	v_exp_f32_e32 v43, v43
	v_pk_mul_f32 v[150:151], v[52:53], v[150:151]
	v_add_f32_e32 v43, 1.0, v43
	v_cvt_pk_bf16_f32 v149, v150, v151
	ds_write_b64 v34, v[148:149] offset:4096
	v_rcp_f32_e32 v148, v43
	v_mul_f32_e32 v43, 0x3d372713, v51
	v_mul_f32_e32 v43, v51, v43
	v_fma_f32 v43, v51, v43, v51
	v_mul_f32_e32 v43, 0x3f4c422a, v43
	v_mul_f32_e32 v43, 0xc038aa3b, v43
	v_exp_f32_e32 v43, v43
	s_nop 0
	v_add_f32_e32 v43, 1.0, v43
	v_rcp_f32_e32 v149, v43
	v_mul_f32_e32 v43, 0x3d372713, v48
	v_mul_f32_e32 v43, v48, v43
	v_fma_f32 v43, v48, v43, v48
	v_mul_f32_e32 v43, 0x3f4c422a, v43
	v_mul_f32_e32 v43, 0xc038aa3b, v43
	v_exp_f32_e32 v43, v43
	v_pk_mul_f32 v[148:149], v[50:51], v[148:149]
	v_add_f32_e32 v43, 1.0, v43
	v_rcp_f32_e32 v150, v43
	v_mul_f32_e32 v43, 0x3d372713, v49
	v_mul_f32_e32 v43, v49, v43
	v_fma_f32 v43, v49, v43, v49
	v_mul_f32_e32 v43, 0x3f4c422a, v43
	v_mul_f32_e32 v43, 0xc038aa3b, v43
	v_exp_f32_e32 v43, v43
	v_cvt_pk_bf16_f32 v148, v148, v149
	v_add_f32_e32 v43, 1.0, v43
	v_rcp_f32_e32 v151, v43
	v_mul_f32_e32 v43, 0x3d372713, v44
	v_mul_f32_e32 v43, v44, v43
	v_fma_f32 v43, v44, v43, v44
	v_mul_f32_e32 v43, 0x3f4c422a, v43
	v_mul_f32_e32 v43, 0xc038aa3b, v43
	v_exp_f32_e32 v43, v43
	v_pk_mul_f32 v[150:151], v[48:49], v[150:151]
	v_add_f32_e32 v43, 1.0, v43
	v_cvt_pk_bf16_f32 v149, v150, v151
	ds_write_b64 v35, v[148:149] offset:4096
	v_rcp_f32_e32 v148, v43
	v_mul_f32_e32 v43, 0x3d372713, v45
	v_mul_f32_e32 v43, v45, v43
	v_fma_f32 v43, v45, v43, v45
	v_mul_f32_e32 v43, 0x3f4c422a, v43
	v_mul_f32_e32 v43, 0xc038aa3b, v43
	v_exp_f32_e32 v43, v43
	s_nop 0
	v_add_f32_e32 v43, 1.0, v43
	v_rcp_f32_e32 v149, v43
	v_mul_f32_e32 v43, 0x3d372713, v46
	v_mul_f32_e32 v43, v46, v43
	v_fma_f32 v43, v46, v43, v46
	v_mul_f32_e32 v43, 0x3f4c422a, v43
	v_mul_f32_e32 v43, 0xc038aa3b, v43
	v_exp_f32_e32 v43, v43
	v_pk_mul_f32 v[148:149], v[44:45], v[148:149]
	v_add_f32_e32 v43, 1.0, v43
	v_rcp_f32_e32 v150, v43
	v_mul_f32_e32 v43, 0x3d372713, v47
	v_mul_f32_e32 v43, v47, v43
	v_fma_f32 v43, v47, v43, v47
	v_mul_f32_e32 v43, 0x3f4c422a, v43
	v_mul_f32_e32 v43, 0xc038aa3b, v43
	v_exp_f32_e32 v43, v43
	v_cvt_pk_bf16_f32 v148, v148, v149
	v_add_f32_e32 v43, 1.0, v43
	v_rcp_f32_e32 v151, v43
	s_nop 0
	v_pk_mul_f32 v[150:151], v[46:47], v[150:151]
	s_nop 0
	v_cvt_pk_bf16_f32 v149, v150, v151
	ds_write_b64 v32, v[148:149] offset:6144
	v_mul_f32_e32 v32, 0x3d372713, v30
	v_mul_f32_e32 v32, v30, v32
	v_fma_f32 v32, v30, v32, v30
	v_mul_f32_e32 v32, 0x3f4c422a, v32
	v_mul_f32_e32 v32, 0xc038aa3b, v32
	v_exp_f32_e32 v32, v32
	s_nop 0
	v_add_f32_e32 v32, 1.0, v32
	v_rcp_f32_e32 v148, v32
; #define LDSP __attribute__((address_space(3)))
; DI unsigned pk2(float a, float b) { f32x2 v = {a, b}; bf2_t r = __builtin_convertvector(v, bf2_t); return __builtin_bit_cast(unsigned, r); }
; DI void wave_rows_store(ldsp_t wb, int lane, bf16_t* dst0, size_t ld) {
; #pragma unroll
;     for (int i = 0; i < 8; ++i) {
;         const int row = i * 8 + (lane >> 3), ch = lane & 7;
;         const u32x4 v = *(const LDSP u32x4*)(wb + row * 128 + ((ch ^ (row & 7)) << 4));
;         *(u32x4*)(dst0 + (size_t)row * ld + ch * 8) = v;
;     }
;     static DI void run(const f32x4 (&acc)[8][4], const TileCtx& tc, const Params& p, ldsp_t wb) {
;     ...
;         } else if (BRK == 2) {
; #pragma unroll
;             for (int h = 0; h < 2; ++h) {
; #pragma unroll
;                 for (int mm = 0; mm < 4; ++mm) {
;                     const int m = h * 4 + mm;
; #pragma unroll
;                     for (int n = 0; n < 4; ++n) {
;                         u32x2 w; w[0] = pk2(gelu_tanh(acc[m][n][0]), gelu_tanh(acc[m][n][1])); w[1] = pk2(gelu_tanh(acc[m][n][2]), gelu_tanh(acc[m][n][3]));
;                         wave_put(wb, mm * 16 + fr, n, fq, w);
;                     }
;                 }
;                 wave_rows_store(wb, tc.lane, p.U + (size_t)(tc.brow + tc.wr * 128 + h * 64) * 1024 + (pn - 3) * 256 + wc * 64, 1024);
	v_mul_f32_e32 v32, 0x3d372713, v31
	v_mul_f32_e32 v32, v31, v32
	v_fma_f32 v32, v31, v32, v31
	v_mul_f32_e32 v32, 0x3f4c422a, v32
	v_mul_f32_e32 v32, 0xc038aa3b, v32
	v_exp_f32_e32 v32, v32
	s_nop 0
	v_add_f32_e32 v32, 1.0, v32
	v_rcp_f32_e32 v149, v32
	v_mul_f32_e32 v32, 0x3d372713, v28
	v_mul_f32_e32 v32, v28, v32
	v_fma_f32 v32, v28, v32, v28
	v_mul_f32_e32 v32, 0x3f4c422a, v32
	v_mul_f32_e32 v32, 0xc038aa3b, v32
	v_exp_f32_e32 v32, v32
	v_pk_mul_f32 v[148:149], v[30:31], v[148:149]
	v_add_f32_e32 v32, 1.0, v32
	v_rcp_f32_e32 v150, v32
	v_mul_f32_e32 v32, 0x3d372713, v29
	v_mul_f32_e32 v32, v29, v32
	v_fma_f32 v32, v29, v32, v29
	v_mul_f32_e32 v32, 0x3f4c422a, v32
	v_mul_f32_e32 v32, 0xc038aa3b, v32
	v_exp_f32_e32 v32, v32
	v_cvt_pk_bf16_f32 v148, v148, v149
	v_add_f32_e32 v32, 1.0, v32
	v_rcp_f32_e32 v151, v32
	v_mul_f32_e32 v32, 0x3d372713, v26
	v_mul_f32_e32 v32, v26, v32
	v_fma_f32 v32, v26, v32, v26
	v_pk_mul_f32 v[150:151], v[28:29], v[150:151]
	v_mul_f32_e32 v32, 0x3f4c422a, v32
	v_cvt_pk_bf16_f32 v149, v150, v151
	ds_write_b64 v33, v[148:149] offset:6144
	v_mul_f32_e32 v33, 0x3d372713, v27
	v_mul_f32_e32 v33, v27, v33
	v_fma_f32 v33, v27, v33, v27
	v_mul_f32_e32 v33, 0x3f4c422a, v33
	v_mul_f32_e32 v32, 0xc038aa3b, v32
	v_mul_f32_e32 v33, 0xc038aa3b, v33
	v_exp_f32_e32 v32, v32
	v_exp_f32_e32 v33, v33
	v_add_f32_e32 v32, 1.0, v32
	v_add_f32_e32 v33, 1.0, v33
	v_rcp_f32_e32 v32, v32
	v_rcp_f32_e32 v33, v33
	s_nop 0
	v_pk_mul_f32 v[32:33], v[26:27], v[32:33]
	s_nop 0
	v_cvt_pk_bf16_f32 v32, v32, v33
	v_mul_f32_e32 v33, 0x3d372713, v24
	v_mul_f32_e32 v33, v24, v33
	v_fma_f32 v33, v24, v33, v24
	v_mul_f32_e32 v33, 0x3f4c422a, v33
	v_mul_f32_e32 v33, 0xc038aa3b, v33
	v_exp_f32_e32 v33, v33
	s_nop 0
	v_add_f32_e32 v33, 1.0, v33
	v_rcp_f32_e32 v148, v33
	v_mul_f32_e32 v33, 0x3d372713, v25
	v_mul_f32_e32 v33, v25, v33
	v_fma_f32 v33, v25, v33, v25
	v_mul_f32_e32 v33, 0x3f4c422a, v33
	v_mul_f32_e32 v33, 0xc038aa3b, v33
	v_exp_f32_e32 v33, v33
	s_nop 0
	v_add_f32_e32 v33, 1.0, v33
	v_rcp_f32_e32 v149, v33
	s_nop 0
	v_pk_mul_f32 v[148:149], v[24:25], v[148:149]
	s_nop 0
	v_cvt_pk_bf16_f32 v33, v148, v149
	ds_write_b64 v34, v[32:33] offset:6144
	v_mul_f32_e32 v32, 0x3d372713, v22
	v_mul_f32_e32 v33, 0x3d372713, v23
	v_mul_f32_e32 v32, v22, v32
	v_mul_f32_e32 v33, v23, v33
	v_fma_f32 v32, v22, v32, v22
	v_fma_f32 v33, v23, v33, v23
	v_mul_f32_e32 v32, 0x3f4c422a, v32
	v_mul_f32_e32 v33, 0x3f4c422a, v33
	v_mul_f32_e32 v32, 0xc038aa3b, v32
	v_mul_f32_e32 v33, 0xc038aa3b, v33
	v_exp_f32_e32 v32, v32
	v_exp_f32_e32 v33, v33
	v_add_f32_e32 v32, 1.0, v32
	v_add_f32_e32 v33, 1.0, v33
	v_rcp_f32_e32 v32, v32
	v_rcp_f32_e32 v33, v33
	s_nop 0
	v_pk_mul_f32 v[32:33], v[22:23], v[32:33]
	s_nop 0
	v_cvt_pk_bf16_f32 v32, v32, v33
	v_mul_f32_e32 v33, 0x3d372713, v20
	v_mul_f32_e32 v33, v20, v33
	v_fma_f32 v33, v20, v33, v20
	v_mul_f32_e32 v33, 0x3f4c422a, v33
	v_mul_f32_e32 v33, 0xc038aa3b, v33
	v_exp_f32_e32 v33, v33
	s_nop 0
	v_add_f32_e32 v33, 1.0, v33
	v_rcp_f32_e32 v148, v33
	v_mul_f32_e32 v33, 0x3d372713, v21
	v_mul_f32_e32 v33, v21, v33
	v_fma_f32 v33, v21, v33, v21
	v_mul_f32_e32 v33, 0x3f4c422a, v33
	v_mul_f32_e32 v33, 0xc038aa3b, v33
	v_exp_f32_e32 v33, v33
	s_nop 0
	v_add_f32_e32 v33, 1.0, v33
	v_rcp_f32_e32 v149, v33
	s_nop 0
	v_pk_mul_f32 v[148:149], v[20:21], v[148:149]
	s_nop 0
	v_cvt_pk_bf16_f32 v33, v148, v149
	ds_write_b64 v35, v[32:33] offset:6144
	v_or_b32_e32 v32, 64, v10
	v_ashrrev_i32_e32 v33, 31, v32
	v_lshlrev_b64 v[32:33], 11, v[32:33]
	v_lshl_add_u64 v[32:33], s[16:17], 0, v[32:33]
	v_lshl_add_u64 v[32:33], v[32:33], 0, s[4:5]
	v_lshl_add_u64 v[32:33], v[32:33], 0, v[192:193]
	v_lshl_add_u64 v[148:149], v[32:33], 0, v[18:19]
	ds_read_b128 v[32:35], v42
	v_lshl_add_u64 v[16:17], v[148:149], 0, v[16:17]
	v_lshl_add_u64 v[14:15], v[148:149], 0, v[14:15]
	v_lshl_add_u64 v[12:13], v[148:149], 0, v[12:13]
	v_lshl_add_u64 v[8:9], v[148:149], 0, v[8:9]
	s_waitcnt lgkmcnt(0)
	global_store_dwordx4 v[16:17], v[32:35], off
	ds_read_b128 v[16:19], v41
	v_lshl_add_u64 v[2:3], v[148:149], 0, v[2:3]
	v_lshl_add_u64 v[0:1], v[148:149], 0, v[0:1]
	s_mov_b64 s[4:5], 0
	s_waitcnt lgkmcnt(0)
	global_store_dwordx4 v[14:15], v[16:19], off
	ds_read_b128 v[14:17], v40
	s_waitcnt lgkmcnt(0)
	global_store_dwordx4 v[12:13], v[14:17], off
	ds_read_b128 v[12:15], v39
	s_waitcnt lgkmcnt(0)
	global_store_dwordx4 v[8:9], v[12:15], off
	ds_read_b128 v[12:15], v38
	s_waitcnt lgkmcnt(0)
	global_store_dwordx4 v[2:3], v[12:15], off
	ds_read_b128 v[12:15], v37
	v_lshl_add_u64 v[2:3], v[148:149], 0, v[6:7]
	ds_read_b128 v[6:9], v36
	s_waitcnt lgkmcnt(1)
	global_store_dwordx4 v[2:3], v[12:15], off
	v_lshl_add_u64 v[2:3], v[148:149], 0, v[4:5]
	s_waitcnt lgkmcnt(0)
	global_store_dwordx4 v[2:3], v[6:9], off
	ds_read_b128 v[2:5], v11
	s_waitcnt lgkmcnt(0)
	global_store_dwordx4 v[0:1], v[2:5], off
